# in-proj GEMM phase also rewritten by hand with 256x128 tiles (f32 proj stores as dwordx2, bf16 tanh/sigmoid copies)
# speedup vs baseline: 1.1106x; 1.0331x over previous
.Lip_entry:
	v_and_b32_e32 v225, 63, v170
	v_lshrrev_b32_e32 v226, 6, v170
	v_lshrrev_b32_e32 v227, 1, v226
	v_and_b32_e32 v228, 1, v226
	v_and_b32_e32 v229, 15, v225
	v_lshrrev_b32_e32 v230, 4, v225
	v_lshlrev_b32_e32 v231, 10, v226
	v_lshrrev_b32_e32 v232, 3, v170
	v_readfirstlane_b32 s52, v231
	v_and_b32_e32 v233, 7, v170
	v_bfe_u32 v224, v232, 1, 3
	v_xor_b32_e32 v233, v233, v224
	v_lshlrev_b32_e32 v233, 4, v233
	s_movk_i32 s4, 0x880
	v_mad_u32_u24 v224, v232, s4, v233
	v_and_b32_e32 v233, 15, v232
	v_lshlrev_b32_e32 v233, 1, v233
	v_lshrrev_b32_e32 v168, 4, v232
	v_add_u32_e32 v233, v233, v168
	v_and_b32_e32 v168, 7, v170
	v_bfe_u32 v169, v232, 1, 3
	v_xor_b32_e32 v168, v168, v169
	v_lshlrev_b32_e32 v168, 4, v168
	v_mad_u32_u24 v168, v233, s4, v168
	v_bfe_u32 v233, v229, 1, 3
	v_xor_b32_e32 v231, v230, v233
	v_or_b32_e32 v232, 4, v230
	v_xor_b32_e32 v232, v232, v233
	v_lshlrev_b32_e32 v231, 4, v231
	v_lshlrev_b32_e32 v232, 4, v232
	v_lshl_add_u32 v233, v227, 7, v229
	v_lshlrev_b32_e32 v233, 7, v233
	v_add_u32_e32 v220, v233, v231
	v_add_u32_e32 v221, v233, v232
	v_lshl_add_u32 v233, v228, 6, v229
	v_lshlrev_b32_e32 v233, 7, v233
	v_add_u32_e32 v233, 0x8000, v233
	v_add_u32_e32 v222, v233, v231
	v_add_u32_e32 v223, v233, v232
	v_lshlrev_b32_e32 v231, 7, v227
	v_lshl_add_u32 v231, v230, 2, v231
	v_lshlrev_b32_e32 v232, 5, v228
	v_add_u32_e32 v232, v232, v229
	v_lshlrev_b32_e32 v232, 1, v232
	s_movk_i32 s4, 0x3600
	v_lshlrev_b32_e32 v233, 2, v232
	v_mad_u32_u24 v225, v231, s4, v233
	s_movk_i32 s4, 0x300
	v_lshlrev_b32_e32 v233, 1, v232
	v_mad_u32_u24 v169, v231, s4, v233
	v_readlane_b32 s54, v237, 0
	s_cmp_ge_u32 s54, 1296
	s_cbranch_scc1 .Lip_done
	s_lshr_b32 s55, s54, 4
	s_mul_hi_u32 s55, s55, 0x55555556
	s_mul_i32 s53, s55, 48
	s_sub_u32 s53, s54, s53
	v_readlane_b32 s4, v235, 34
	v_readlane_b32 s5, v235, 35
	s_mul_i32 s34, s53, 0x88000
	s_add_u32 s34, s34, 0xe166000
	s_add_u32 s34, s34, s4
	s_addc_u32 s35, s5, 0
	s_mul_i32 s36, s55, 0x44000
	s_add_u32 s36, s36, s40
	s_addc_u32 s37, s41, 0
	s_lshr_b32 s55, s54, 4
	s_mul_hi_u32 s55, s55, 0x55555556
	s_mul_i32 s53, s55, 48
	s_sub_u32 s53, s54, s53
	v_readlane_b32 s4, v235, 34
	v_readlane_b32 s5, v235, 35
	s_mov_b32 s56, s55
	s_mul_i32 s46, s53, 0x360000
	s_lshl_b32 s57, s55, 9
	s_add_u32 s46, s46, s57
	s_add_u32 s46, s46, 0xfae6000
	s_add_u32 s46, s46, s4
	s_addc_u32 s47, s5, 0
	s_mul_i32 s50, s53, 0x30000
	s_lshl_b32 s57, s55, 8
	s_add_u32 s50, s50, s57
	s_add_u32 s50, s50, 0x19ce5a00
	s_add_u32 s50, s50, s4
	s_addc_u32 s51, s5, 0
	s_add_u32 m0, s52, 0x0
	s_add_u32 s4, s34, 0x0
	s_addc_u32 s5, s35, 0
	global_load_lds_dwordx4 v224, s[4:5]
	s_add_u32 m0, s52, 0x1000
	s_add_u32 s4, s34, 0x11000
	s_addc_u32 s5, s35, 0
	global_load_lds_dwordx4 v224, s[4:5]
	s_add_u32 m0, s52, 0x2000
	s_add_u32 s4, s34, 0x22000
	s_addc_u32 s5, s35, 0
	global_load_lds_dwordx4 v224, s[4:5]
	s_add_u32 m0, s52, 0x3000
	s_add_u32 s4, s34, 0x33000
	s_addc_u32 s5, s35, 0
	global_load_lds_dwordx4 v224, s[4:5]
	s_add_u32 m0, s52, 0x4000
	s_add_u32 s4, s34, 0x44000
	s_addc_u32 s5, s35, 0
	global_load_lds_dwordx4 v224, s[4:5]
	s_add_u32 m0, s52, 0x5000
	s_add_u32 s4, s34, 0x55000
	s_addc_u32 s5, s35, 0
	global_load_lds_dwordx4 v224, s[4:5]
	s_add_u32 m0, s52, 0x6000
	s_add_u32 s4, s34, 0x66000
	s_addc_u32 s5, s35, 0
	global_load_lds_dwordx4 v224, s[4:5]
	s_add_u32 m0, s52, 0x7000
	s_add_u32 s4, s34, 0x77000
	s_addc_u32 s5, s35, 0
	global_load_lds_dwordx4 v224, s[4:5]
	s_add_u32 m0, s52, 0x8000
	s_add_u32 s4, s36, 0x0
	s_addc_u32 s5, s37, 0
	global_load_lds_dwordx4 v168, s[4:5]
	s_add_u32 m0, s52, 0x9000
	s_add_u32 s4, s36, 0x11000
	s_addc_u32 s5, s37, 0
	global_load_lds_dwordx4 v168, s[4:5]
	s_add_u32 m0, s52, 0xa000
	s_add_u32 s4, s36, 0x22000
	s_addc_u32 s5, s37, 0
	global_load_lds_dwordx4 v168, s[4:5]
	s_add_u32 m0, s52, 0xb000
	s_add_u32 s4, s36, 0x33000
	s_addc_u32 s5, s37, 0
	global_load_lds_dwordx4 v168, s[4:5]
	s_add_u32 s34, s34, 0x80
	s_addc_u32 s35, s35, 0
	s_add_u32 s36, s36, 0x80
	s_addc_u32 s37, s37, 0
.Lip_tile:
	v_mov_b32_e32 v0, 0
	v_mov_b32_e32 v1, 0
	v_mov_b32_e32 v2, 0
	v_mov_b32_e32 v3, 0
	v_mov_b32_e32 v4, 0
	v_mov_b32_e32 v5, 0
	v_mov_b32_e32 v6, 0
	v_mov_b32_e32 v7, 0
	v_mov_b32_e32 v8, 0
	v_mov_b32_e32 v9, 0
	v_mov_b32_e32 v10, 0
	v_mov_b32_e32 v11, 0
	v_mov_b32_e32 v12, 0
	v_mov_b32_e32 v13, 0
	v_mov_b32_e32 v14, 0
	v_mov_b32_e32 v15, 0
	v_mov_b32_e32 v16, 0
	v_mov_b32_e32 v17, 0
	v_mov_b32_e32 v18, 0
	v_mov_b32_e32 v19, 0
	v_mov_b32_e32 v20, 0
	v_mov_b32_e32 v21, 0
	v_mov_b32_e32 v22, 0
	v_mov_b32_e32 v23, 0
	v_mov_b32_e32 v24, 0
	v_mov_b32_e32 v25, 0
	v_mov_b32_e32 v26, 0
	v_mov_b32_e32 v27, 0
	v_mov_b32_e32 v28, 0
	v_mov_b32_e32 v29, 0
	v_mov_b32_e32 v30, 0
	v_mov_b32_e32 v31, 0
	v_mov_b32_e32 v32, 0
	v_mov_b32_e32 v33, 0
	v_mov_b32_e32 v34, 0
	v_mov_b32_e32 v35, 0
	v_mov_b32_e32 v36, 0
	v_mov_b32_e32 v37, 0
	v_mov_b32_e32 v38, 0
	v_mov_b32_e32 v39, 0
	v_mov_b32_e32 v40, 0
	v_mov_b32_e32 v41, 0
	v_mov_b32_e32 v42, 0
	v_mov_b32_e32 v43, 0
	v_mov_b32_e32 v44, 0
	v_mov_b32_e32 v45, 0
	v_mov_b32_e32 v46, 0
	v_mov_b32_e32 v47, 0
	v_mov_b32_e32 v48, 0
	v_mov_b32_e32 v49, 0
	v_mov_b32_e32 v50, 0
	v_mov_b32_e32 v51, 0
	v_mov_b32_e32 v52, 0
	v_mov_b32_e32 v53, 0
	v_mov_b32_e32 v54, 0
	v_mov_b32_e32 v55, 0
	v_mov_b32_e32 v56, 0
	v_mov_b32_e32 v57, 0
	v_mov_b32_e32 v58, 0
	v_mov_b32_e32 v59, 0
	v_mov_b32_e32 v60, 0
	v_mov_b32_e32 v61, 0
	v_mov_b32_e32 v62, 0
	v_mov_b32_e32 v63, 0
	v_mov_b32_e32 v64, 0
	v_mov_b32_e32 v65, 0
	v_mov_b32_e32 v66, 0
	v_mov_b32_e32 v67, 0
	v_mov_b32_e32 v68, 0
	v_mov_b32_e32 v69, 0
	v_mov_b32_e32 v70, 0
	v_mov_b32_e32 v71, 0
	v_mov_b32_e32 v72, 0
	v_mov_b32_e32 v73, 0
	v_mov_b32_e32 v74, 0
	v_mov_b32_e32 v75, 0
	v_mov_b32_e32 v76, 0
	v_mov_b32_e32 v77, 0
	v_mov_b32_e32 v78, 0
	v_mov_b32_e32 v79, 0
	v_mov_b32_e32 v80, 0
	v_mov_b32_e32 v81, 0
	v_mov_b32_e32 v82, 0
	v_mov_b32_e32 v83, 0
	v_mov_b32_e32 v84, 0
	v_mov_b32_e32 v85, 0
	v_mov_b32_e32 v86, 0
	v_mov_b32_e32 v87, 0
	v_mov_b32_e32 v88, 0
	v_mov_b32_e32 v89, 0
	v_mov_b32_e32 v90, 0
	v_mov_b32_e32 v91, 0
	v_mov_b32_e32 v92, 0
	v_mov_b32_e32 v93, 0
	v_mov_b32_e32 v94, 0
	v_mov_b32_e32 v95, 0
	v_mov_b32_e32 v96, 0
	v_mov_b32_e32 v97, 0
	v_mov_b32_e32 v98, 0
	v_mov_b32_e32 v99, 0
	v_mov_b32_e32 v100, 0
	v_mov_b32_e32 v101, 0
	v_mov_b32_e32 v102, 0
	v_mov_b32_e32 v103, 0
	v_mov_b32_e32 v104, 0
	v_mov_b32_e32 v105, 0
	v_mov_b32_e32 v106, 0
	v_mov_b32_e32 v107, 0
	v_mov_b32_e32 v108, 0
	v_mov_b32_e32 v109, 0
	v_mov_b32_e32 v110, 0
	v_mov_b32_e32 v111, 0
	v_mov_b32_e32 v112, 0
	v_mov_b32_e32 v113, 0
	v_mov_b32_e32 v114, 0
	v_mov_b32_e32 v115, 0
	v_mov_b32_e32 v116, 0
	v_mov_b32_e32 v117, 0
	v_mov_b32_e32 v118, 0
	v_mov_b32_e32 v119, 0
	v_mov_b32_e32 v120, 0
	v_mov_b32_e32 v121, 0
	v_mov_b32_e32 v122, 0
	v_mov_b32_e32 v123, 0
	v_mov_b32_e32 v124, 0
	v_mov_b32_e32 v125, 0
	v_mov_b32_e32 v126, 0
	v_mov_b32_e32 v127, 0
	s_mov_b32 s53, 0
.Lip_k:
	s_waitcnt vmcnt(0)
	s_barrier
	ds_read_b128 v[204:207], v222
	ds_read_b128 v[208:211], v222 offset:2048
	ds_read_b128 v[212:215], v222 offset:4096
	ds_read_b128 v[216:219], v222 offset:6144
	ds_read_b128 a[0:3], v223
	ds_read_b128 a[4:7], v223 offset:2048
	ds_read_b128 a[8:11], v223 offset:4096
	ds_read_b128 a[12:15], v223 offset:6144
	ds_read_b128 v[136:139], v220
	ds_read_b128 v[140:143], v220 offset:2048
	ds_read_b128 v[144:147], v220 offset:4096
	ds_read_b128 v[148:151], v220 offset:6144
	ds_read_b128 v[152:155], v220 offset:8192
	ds_read_b128 v[156:159], v220 offset:10240
	ds_read_b128 v[160:163], v220 offset:12288
	ds_read_b128 v[164:167], v220 offset:14336
	s_waitcnt lgkmcnt(7)
	v_mfma_f32_16x16x32_bf16 v[0:3], v[136:139], v[204:207], v[0:3]
	v_mfma_f32_16x16x32_bf16 v[4:7], v[136:139], v[208:211], v[4:7]
	v_mfma_f32_16x16x32_bf16 v[8:11], v[136:139], v[212:215], v[8:11]
	v_mfma_f32_16x16x32_bf16 v[12:15], v[136:139], v[216:219], v[12:15]
	ds_read_b128 v[136:139], v221
	s_waitcnt lgkmcnt(7)
	v_mfma_f32_16x16x32_bf16 v[16:19], v[140:143], v[204:207], v[16:19]
	v_mfma_f32_16x16x32_bf16 v[20:23], v[140:143], v[208:211], v[20:23]
	v_mfma_f32_16x16x32_bf16 v[24:27], v[140:143], v[212:215], v[24:27]
	v_mfma_f32_16x16x32_bf16 v[28:31], v[140:143], v[216:219], v[28:31]
	ds_read_b128 v[140:143], v221 offset:2048
	s_waitcnt lgkmcnt(7)
	v_mfma_f32_16x16x32_bf16 v[32:35], v[144:147], v[204:207], v[32:35]
	v_mfma_f32_16x16x32_bf16 v[36:39], v[144:147], v[208:211], v[36:39]
	v_mfma_f32_16x16x32_bf16 v[40:43], v[144:147], v[212:215], v[40:43]
	v_mfma_f32_16x16x32_bf16 v[44:47], v[144:147], v[216:219], v[44:47]
	ds_read_b128 v[144:147], v221 offset:4096
	s_waitcnt lgkmcnt(7)
	v_mfma_f32_16x16x32_bf16 v[48:51], v[148:151], v[204:207], v[48:51]
	v_mfma_f32_16x16x32_bf16 v[52:55], v[148:151], v[208:211], v[52:55]
	v_mfma_f32_16x16x32_bf16 v[56:59], v[148:151], v[212:215], v[56:59]
	v_mfma_f32_16x16x32_bf16 v[60:63], v[148:151], v[216:219], v[60:63]
	ds_read_b128 v[148:151], v221 offset:6144
	s_waitcnt lgkmcnt(7)
	v_mfma_f32_16x16x32_bf16 v[64:67], v[152:155], v[204:207], v[64:67]
	v_mfma_f32_16x16x32_bf16 v[68:71], v[152:155], v[208:211], v[68:71]
	v_mfma_f32_16x16x32_bf16 v[72:75], v[152:155], v[212:215], v[72:75]
	v_mfma_f32_16x16x32_bf16 v[76:79], v[152:155], v[216:219], v[76:79]
	ds_read_b128 v[152:155], v221 offset:8192
	s_waitcnt lgkmcnt(7)
	v_mfma_f32_16x16x32_bf16 v[80:83], v[156:159], v[204:207], v[80:83]
	v_mfma_f32_16x16x32_bf16 v[84:87], v[156:159], v[208:211], v[84:87]
	v_mfma_f32_16x16x32_bf16 v[88:91], v[156:159], v[212:215], v[88:91]
	v_mfma_f32_16x16x32_bf16 v[92:95], v[156:159], v[216:219], v[92:95]
	ds_read_b128 v[156:159], v221 offset:10240
	s_waitcnt lgkmcnt(7)
	v_mfma_f32_16x16x32_bf16 v[96:99], v[160:163], v[204:207], v[96:99]
	v_mfma_f32_16x16x32_bf16 v[100:103], v[160:163], v[208:211], v[100:103]
	v_mfma_f32_16x16x32_bf16 v[104:107], v[160:163], v[212:215], v[104:107]
	v_mfma_f32_16x16x32_bf16 v[108:111], v[160:163], v[216:219], v[108:111]
	ds_read_b128 v[160:163], v221 offset:12288
	s_waitcnt lgkmcnt(7)
	v_mfma_f32_16x16x32_bf16 v[112:115], v[164:167], v[204:207], v[112:115]
	v_mfma_f32_16x16x32_bf16 v[116:119], v[164:167], v[208:211], v[116:119]
	v_mfma_f32_16x16x32_bf16 v[120:123], v[164:167], v[212:215], v[120:123]
	v_mfma_f32_16x16x32_bf16 v[124:127], v[164:167], v[216:219], v[124:127]
	ds_read_b128 v[164:167], v221 offset:14336
	s_waitcnt lgkmcnt(0)
	s_barrier
	s_cmp_eq_u32 s53, 15
	s_cbranch_scc1 .Lip_last
	s_add_u32 m0, s52, 0x0
	s_add_u32 s4, s34, 0x0
	s_addc_u32 s5, s35, 0
	global_load_lds_dwordx4 v224, s[4:5]
	s_add_u32 m0, s52, 0x1000
	s_add_u32 s4, s34, 0x11000
	s_addc_u32 s5, s35, 0
	global_load_lds_dwordx4 v224, s[4:5]
	s_add_u32 m0, s52, 0x2000
	s_add_u32 s4, s34, 0x22000
	s_addc_u32 s5, s35, 0
	global_load_lds_dwordx4 v224, s[4:5]
	s_add_u32 m0, s52, 0x3000
	s_add_u32 s4, s34, 0x33000
	s_addc_u32 s5, s35, 0
	global_load_lds_dwordx4 v224, s[4:5]
	s_add_u32 m0, s52, 0x4000
	s_add_u32 s4, s34, 0x44000
	s_addc_u32 s5, s35, 0
	global_load_lds_dwordx4 v224, s[4:5]
	s_add_u32 m0, s52, 0x5000
	s_add_u32 s4, s34, 0x55000
	s_addc_u32 s5, s35, 0
	global_load_lds_dwordx4 v224, s[4:5]
	s_add_u32 m0, s52, 0x6000
	s_add_u32 s4, s34, 0x66000
	s_addc_u32 s5, s35, 0
	global_load_lds_dwordx4 v224, s[4:5]
	s_add_u32 m0, s52, 0x7000
	s_add_u32 s4, s34, 0x77000
	s_addc_u32 s5, s35, 0
	global_load_lds_dwordx4 v224, s[4:5]
	s_add_u32 m0, s52, 0x8000
	s_add_u32 s4, s36, 0x0
	s_addc_u32 s5, s37, 0
	global_load_lds_dwordx4 v168, s[4:5]
	s_add_u32 m0, s52, 0x9000
	s_add_u32 s4, s36, 0x11000
	s_addc_u32 s5, s37, 0
	global_load_lds_dwordx4 v168, s[4:5]
	s_add_u32 m0, s52, 0xa000
	s_add_u32 s4, s36, 0x22000
	s_addc_u32 s5, s37, 0
	global_load_lds_dwordx4 v168, s[4:5]
	s_add_u32 m0, s52, 0xb000
	s_add_u32 s4, s36, 0x33000
	s_addc_u32 s5, s37, 0
	global_load_lds_dwordx4 v168, s[4:5]
	s_add_u32 s34, s34, 0x80
	s_addc_u32 s35, s35, 0
	s_add_u32 s36, s36, 0x80
	s_addc_u32 s37, s37, 0
	v_mfma_f32_16x16x32_bf16 v[0:3], v[136:139], a[0:3], v[0:3]
	v_mfma_f32_16x16x32_bf16 v[4:7], v[136:139], a[4:7], v[4:7]
	v_mfma_f32_16x16x32_bf16 v[8:11], v[136:139], a[8:11], v[8:11]
	v_mfma_f32_16x16x32_bf16 v[12:15], v[136:139], a[12:15], v[12:15]
	v_mfma_f32_16x16x32_bf16 v[16:19], v[140:143], a[0:3], v[16:19]
	v_mfma_f32_16x16x32_bf16 v[20:23], v[140:143], a[4:7], v[20:23]
	v_mfma_f32_16x16x32_bf16 v[24:27], v[140:143], a[8:11], v[24:27]
	v_mfma_f32_16x16x32_bf16 v[28:31], v[140:143], a[12:15], v[28:31]
	v_mfma_f32_16x16x32_bf16 v[32:35], v[144:147], a[0:3], v[32:35]
	v_mfma_f32_16x16x32_bf16 v[36:39], v[144:147], a[4:7], v[36:39]
	v_mfma_f32_16x16x32_bf16 v[40:43], v[144:147], a[8:11], v[40:43]
	v_mfma_f32_16x16x32_bf16 v[44:47], v[144:147], a[12:15], v[44:47]
	v_mfma_f32_16x16x32_bf16 v[48:51], v[148:151], a[0:3], v[48:51]
	v_mfma_f32_16x16x32_bf16 v[52:55], v[148:151], a[4:7], v[52:55]
	v_mfma_f32_16x16x32_bf16 v[56:59], v[148:151], a[8:11], v[56:59]
	v_mfma_f32_16x16x32_bf16 v[60:63], v[148:151], a[12:15], v[60:63]
	v_mfma_f32_16x16x32_bf16 v[64:67], v[152:155], a[0:3], v[64:67]
	v_mfma_f32_16x16x32_bf16 v[68:71], v[152:155], a[4:7], v[68:71]
	v_mfma_f32_16x16x32_bf16 v[72:75], v[152:155], a[8:11], v[72:75]
	v_mfma_f32_16x16x32_bf16 v[76:79], v[152:155], a[12:15], v[76:79]
	v_mfma_f32_16x16x32_bf16 v[80:83], v[156:159], a[0:3], v[80:83]
	v_mfma_f32_16x16x32_bf16 v[84:87], v[156:159], a[4:7], v[84:87]
	v_mfma_f32_16x16x32_bf16 v[88:91], v[156:159], a[8:11], v[88:91]
	v_mfma_f32_16x16x32_bf16 v[92:95], v[156:159], a[12:15], v[92:95]
	v_mfma_f32_16x16x32_bf16 v[96:99], v[160:163], a[0:3], v[96:99]
	v_mfma_f32_16x16x32_bf16 v[100:103], v[160:163], a[4:7], v[100:103]
	v_mfma_f32_16x16x32_bf16 v[104:107], v[160:163], a[8:11], v[104:107]
	v_mfma_f32_16x16x32_bf16 v[108:111], v[160:163], a[12:15], v[108:111]
	v_mfma_f32_16x16x32_bf16 v[112:115], v[164:167], a[0:3], v[112:115]
	v_mfma_f32_16x16x32_bf16 v[116:119], v[164:167], a[4:7], v[116:119]
	v_mfma_f32_16x16x32_bf16 v[120:123], v[164:167], a[8:11], v[120:123]
	v_mfma_f32_16x16x32_bf16 v[124:127], v[164:167], a[12:15], v[124:127]
	s_add_u32 s53, s53, 1
	s_branch .Lip_k
.Lip_last:
	v_readlane_b32 s55, v235, 33
	s_add_u32 s54, s54, s55
	s_cmp_ge_u32 s54, 1296
	s_cbranch_scc1 .Lip_nopf
	s_lshr_b32 s55, s54, 4
	s_mul_hi_u32 s55, s55, 0x55555556
	s_mul_i32 s53, s55, 48
	s_sub_u32 s53, s54, s53
	v_readlane_b32 s4, v235, 34
	v_readlane_b32 s5, v235, 35
	s_mul_i32 s34, s53, 0x88000
	s_add_u32 s34, s34, 0xe166000
	s_add_u32 s34, s34, s4
	s_addc_u32 s35, s5, 0
	s_mul_i32 s36, s55, 0x44000
	s_add_u32 s36, s36, s40
	s_addc_u32 s37, s41, 0
	s_add_u32 m0, s52, 0x0
	s_add_u32 s4, s34, 0x0
	s_addc_u32 s5, s35, 0
	global_load_lds_dwordx4 v224, s[4:5]
	s_add_u32 m0, s52, 0x1000
	s_add_u32 s4, s34, 0x11000
	s_addc_u32 s5, s35, 0
	global_load_lds_dwordx4 v224, s[4:5]
	s_add_u32 m0, s52, 0x2000
	s_add_u32 s4, s34, 0x22000
	s_addc_u32 s5, s35, 0
	global_load_lds_dwordx4 v224, s[4:5]
	s_add_u32 m0, s52, 0x3000
	s_add_u32 s4, s34, 0x33000
	s_addc_u32 s5, s35, 0
	global_load_lds_dwordx4 v224, s[4:5]
	s_add_u32 m0, s52, 0x4000
	s_add_u32 s4, s34, 0x44000
	s_addc_u32 s5, s35, 0
	global_load_lds_dwordx4 v224, s[4:5]
	s_add_u32 m0, s52, 0x5000
	s_add_u32 s4, s34, 0x55000
	s_addc_u32 s5, s35, 0
	global_load_lds_dwordx4 v224, s[4:5]
	s_add_u32 m0, s52, 0x6000
	s_add_u32 s4, s34, 0x66000
	s_addc_u32 s5, s35, 0
	global_load_lds_dwordx4 v224, s[4:5]
	s_add_u32 m0, s52, 0x7000
	s_add_u32 s4, s34, 0x77000
	s_addc_u32 s5, s35, 0
	global_load_lds_dwordx4 v224, s[4:5]
	s_add_u32 m0, s52, 0x8000
	s_add_u32 s4, s36, 0x0
	s_addc_u32 s5, s37, 0
	global_load_lds_dwordx4 v168, s[4:5]
	s_add_u32 m0, s52, 0x9000
	s_add_u32 s4, s36, 0x11000
	s_addc_u32 s5, s37, 0
	global_load_lds_dwordx4 v168, s[4:5]
	s_add_u32 m0, s52, 0xa000
	s_add_u32 s4, s36, 0x22000
	s_addc_u32 s5, s37, 0
	global_load_lds_dwordx4 v168, s[4:5]
	s_add_u32 m0, s52, 0xb000
	s_add_u32 s4, s36, 0x33000
	s_addc_u32 s5, s37, 0
	global_load_lds_dwordx4 v168, s[4:5]
	s_add_u32 s34, s34, 0x80
	s_addc_u32 s35, s35, 0
	s_add_u32 s36, s36, 0x80
	s_addc_u32 s37, s37, 0
.Lip_nopf:
	v_mfma_f32_16x16x32_bf16 v[0:3], v[136:139], a[0:3], v[0:3]
	v_mfma_f32_16x16x32_bf16 v[4:7], v[136:139], a[4:7], v[4:7]
	v_mfma_f32_16x16x32_bf16 v[8:11], v[136:139], a[8:11], v[8:11]
	v_mfma_f32_16x16x32_bf16 v[12:15], v[136:139], a[12:15], v[12:15]
	v_mfma_f32_16x16x32_bf16 v[16:19], v[140:143], a[0:3], v[16:19]
	v_mfma_f32_16x16x32_bf16 v[20:23], v[140:143], a[4:7], v[20:23]
	v_mfma_f32_16x16x32_bf16 v[24:27], v[140:143], a[8:11], v[24:27]
	v_mfma_f32_16x16x32_bf16 v[28:31], v[140:143], a[12:15], v[28:31]
	v_mfma_f32_16x16x32_bf16 v[32:35], v[144:147], a[0:3], v[32:35]
	v_mfma_f32_16x16x32_bf16 v[36:39], v[144:147], a[4:7], v[36:39]
	v_mfma_f32_16x16x32_bf16 v[40:43], v[144:147], a[8:11], v[40:43]
	v_mfma_f32_16x16x32_bf16 v[44:47], v[144:147], a[12:15], v[44:47]
	v_mfma_f32_16x16x32_bf16 v[48:51], v[148:151], a[0:3], v[48:51]
	v_mfma_f32_16x16x32_bf16 v[52:55], v[148:151], a[4:7], v[52:55]
	v_mfma_f32_16x16x32_bf16 v[56:59], v[148:151], a[8:11], v[56:59]
	v_mfma_f32_16x16x32_bf16 v[60:63], v[148:151], a[12:15], v[60:63]
	v_mfma_f32_16x16x32_bf16 v[64:67], v[152:155], a[0:3], v[64:67]
	v_mfma_f32_16x16x32_bf16 v[68:71], v[152:155], a[4:7], v[68:71]
	v_mfma_f32_16x16x32_bf16 v[72:75], v[152:155], a[8:11], v[72:75]
	v_mfma_f32_16x16x32_bf16 v[76:79], v[152:155], a[12:15], v[76:79]
	v_mfma_f32_16x16x32_bf16 v[80:83], v[156:159], a[0:3], v[80:83]
	v_mfma_f32_16x16x32_bf16 v[84:87], v[156:159], a[4:7], v[84:87]
	v_mfma_f32_16x16x32_bf16 v[88:91], v[156:159], a[8:11], v[88:91]
	v_mfma_f32_16x16x32_bf16 v[92:95], v[156:159], a[12:15], v[92:95]
	v_mfma_f32_16x16x32_bf16 v[96:99], v[160:163], a[0:3], v[96:99]
	v_mfma_f32_16x16x32_bf16 v[100:103], v[160:163], a[4:7], v[100:103]
	v_mfma_f32_16x16x32_bf16 v[104:107], v[160:163], a[8:11], v[104:107]
	v_mfma_f32_16x16x32_bf16 v[108:111], v[160:163], a[12:15], v[108:111]
	v_mfma_f32_16x16x32_bf16 v[112:115], v[164:167], a[0:3], v[112:115]
	v_mfma_f32_16x16x32_bf16 v[116:119], v[164:167], a[4:7], v[116:119]
	v_mfma_f32_16x16x32_bf16 v[120:123], v[164:167], a[8:11], v[120:123]
	v_mfma_f32_16x16x32_bf16 v[124:127], v[164:167], a[12:15], v[124:127]
	s_nop 7
	s_nop 7
	v_mov_b32_e32 v226, s46
	v_mov_b32_e32 v227, s47
	v_add_co_u32_e32 v226, vcc, v226, v225
	s_nop 1
	v_addc_co_u32_e32 v227, vcc, 0, v227, vcc
	v_mov_b32_e32 v228, v0
	v_mov_b32_e32 v229, v4
	v_mov_b32_e32 v230, v8
	v_mov_b32_e32 v231, v12
	global_store_dwordx2 v[226:227], v[228:229], off
	global_store_dwordx2 v[226:227], v[230:231], off offset:128
	s_mov_b64 s[4:5], 0x3600
	v_lshl_add_u64 v[226:227], v[226:227], 0, s[4:5]
	v_mov_b32_e32 v228, v1
	v_mov_b32_e32 v229, v5
	v_mov_b32_e32 v230, v9
	v_mov_b32_e32 v231, v13
	global_store_dwordx2 v[226:227], v[228:229], off
	global_store_dwordx2 v[226:227], v[230:231], off offset:128
	s_mov_b64 s[4:5], 0x3600
	v_lshl_add_u64 v[226:227], v[226:227], 0, s[4:5]
	v_mov_b32_e32 v228, v2
	v_mov_b32_e32 v229, v6
	v_mov_b32_e32 v230, v10
	v_mov_b32_e32 v231, v14
	global_store_dwordx2 v[226:227], v[228:229], off
	global_store_dwordx2 v[226:227], v[230:231], off offset:128
	s_mov_b64 s[4:5], 0x3600
	v_lshl_add_u64 v[226:227], v[226:227], 0, s[4:5]
	v_mov_b32_e32 v228, v3
	v_mov_b32_e32 v229, v7
	v_mov_b32_e32 v230, v11
	v_mov_b32_e32 v231, v15
	global_store_dwordx2 v[226:227], v[228:229], off
	global_store_dwordx2 v[226:227], v[230:231], off offset:128
	s_mov_b64 s[4:5], 0x2be00
	v_lshl_add_u64 v[226:227], v[226:227], 0, s[4:5]
	v_mov_b32_e32 v228, v16
	v_mov_b32_e32 v229, v20
	v_mov_b32_e32 v230, v24
	v_mov_b32_e32 v231, v28
	global_store_dwordx2 v[226:227], v[228:229], off
	global_store_dwordx2 v[226:227], v[230:231], off offset:128
	s_mov_b64 s[4:5], 0x3600
	v_lshl_add_u64 v[226:227], v[226:227], 0, s[4:5]
	v_mov_b32_e32 v228, v17
	v_mov_b32_e32 v229, v21
	v_mov_b32_e32 v230, v25
	v_mov_b32_e32 v231, v29
	global_store_dwordx2 v[226:227], v[228:229], off
	global_store_dwordx2 v[226:227], v[230:231], off offset:128
	s_mov_b64 s[4:5], 0x3600
	v_lshl_add_u64 v[226:227], v[226:227], 0, s[4:5]
	v_mov_b32_e32 v228, v18
	v_mov_b32_e32 v229, v22
	v_mov_b32_e32 v230, v26
	v_mov_b32_e32 v231, v30
	global_store_dwordx2 v[226:227], v[228:229], off
	global_store_dwordx2 v[226:227], v[230:231], off offset:128
	s_mov_b64 s[4:5], 0x3600
	v_lshl_add_u64 v[226:227], v[226:227], 0, s[4:5]
	v_mov_b32_e32 v228, v19
	v_mov_b32_e32 v229, v23
	v_mov_b32_e32 v230, v27
	v_mov_b32_e32 v231, v31
	global_store_dwordx2 v[226:227], v[228:229], off
	global_store_dwordx2 v[226:227], v[230:231], off offset:128
	s_mov_b64 s[4:5], 0x2be00
	v_lshl_add_u64 v[226:227], v[226:227], 0, s[4:5]
	v_mov_b32_e32 v228, v32
	v_mov_b32_e32 v229, v36
	v_mov_b32_e32 v230, v40
	v_mov_b32_e32 v231, v44
	global_store_dwordx2 v[226:227], v[228:229], off
	global_store_dwordx2 v[226:227], v[230:231], off offset:128
	s_mov_b64 s[4:5], 0x3600
	v_lshl_add_u64 v[226:227], v[226:227], 0, s[4:5]
	v_mov_b32_e32 v228, v33
	v_mov_b32_e32 v229, v37
	v_mov_b32_e32 v230, v41
	v_mov_b32_e32 v231, v45
	global_store_dwordx2 v[226:227], v[228:229], off
	global_store_dwordx2 v[226:227], v[230:231], off offset:128
	s_mov_b64 s[4:5], 0x3600
	v_lshl_add_u64 v[226:227], v[226:227], 0, s[4:5]
	v_mov_b32_e32 v228, v34
	v_mov_b32_e32 v229, v38
	v_mov_b32_e32 v230, v42
	v_mov_b32_e32 v231, v46
	global_store_dwordx2 v[226:227], v[228:229], off
	global_store_dwordx2 v[226:227], v[230:231], off offset:128
	s_mov_b64 s[4:5], 0x3600
	v_lshl_add_u64 v[226:227], v[226:227], 0, s[4:5]
	v_mov_b32_e32 v228, v35
	v_mov_b32_e32 v229, v39
	v_mov_b32_e32 v230, v43
	v_mov_b32_e32 v231, v47
	global_store_dwordx2 v[226:227], v[228:229], off
	global_store_dwordx2 v[226:227], v[230:231], off offset:128
	s_mov_b64 s[4:5], 0x2be00
	v_lshl_add_u64 v[226:227], v[226:227], 0, s[4:5]
	v_mov_b32_e32 v228, v48
	v_mov_b32_e32 v229, v52
	v_mov_b32_e32 v230, v56
	v_mov_b32_e32 v231, v60
	global_store_dwordx2 v[226:227], v[228:229], off
	global_store_dwordx2 v[226:227], v[230:231], off offset:128
	s_mov_b64 s[4:5], 0x3600
	v_lshl_add_u64 v[226:227], v[226:227], 0, s[4:5]
	v_mov_b32_e32 v228, v49
	v_mov_b32_e32 v229, v53
	v_mov_b32_e32 v230, v57
	v_mov_b32_e32 v231, v61
	global_store_dwordx2 v[226:227], v[228:229], off
	global_store_dwordx2 v[226:227], v[230:231], off offset:128
	s_mov_b64 s[4:5], 0x3600
	v_lshl_add_u64 v[226:227], v[226:227], 0, s[4:5]
	v_mov_b32_e32 v228, v50
	v_mov_b32_e32 v229, v54
	v_mov_b32_e32 v230, v58
	v_mov_b32_e32 v231, v62
	global_store_dwordx2 v[226:227], v[228:229], off
	global_store_dwordx2 v[226:227], v[230:231], off offset:128
	s_mov_b64 s[4:5], 0x3600
	v_lshl_add_u64 v[226:227], v[226:227], 0, s[4:5]
	v_mov_b32_e32 v228, v51
	v_mov_b32_e32 v229, v55
	v_mov_b32_e32 v230, v59
	v_mov_b32_e32 v231, v63
	global_store_dwordx2 v[226:227], v[228:229], off
	global_store_dwordx2 v[226:227], v[230:231], off offset:128
	s_mov_b64 s[4:5], 0x2be00
	v_lshl_add_u64 v[226:227], v[226:227], 0, s[4:5]
	v_mov_b32_e32 v228, v64
	v_mov_b32_e32 v229, v68
	v_mov_b32_e32 v230, v72
	v_mov_b32_e32 v231, v76
	global_store_dwordx2 v[226:227], v[228:229], off
	global_store_dwordx2 v[226:227], v[230:231], off offset:128
	s_mov_b64 s[4:5], 0x3600
	v_lshl_add_u64 v[226:227], v[226:227], 0, s[4:5]
	v_mov_b32_e32 v228, v65
	v_mov_b32_e32 v229, v69
	v_mov_b32_e32 v230, v73
	v_mov_b32_e32 v231, v77
	global_store_dwordx2 v[226:227], v[228:229], off
	global_store_dwordx2 v[226:227], v[230:231], off offset:128
	s_mov_b64 s[4:5], 0x3600
	v_lshl_add_u64 v[226:227], v[226:227], 0, s[4:5]
	v_mov_b32_e32 v228, v66
	v_mov_b32_e32 v229, v70
	v_mov_b32_e32 v230, v74
	v_mov_b32_e32 v231, v78
	global_store_dwordx2 v[226:227], v[228:229], off
	global_store_dwordx2 v[226:227], v[230:231], off offset:128
	s_mov_b64 s[4:5], 0x3600
	v_lshl_add_u64 v[226:227], v[226:227], 0, s[4:5]
	v_mov_b32_e32 v228, v67
	v_mov_b32_e32 v229, v71
	v_mov_b32_e32 v230, v75
	v_mov_b32_e32 v231, v79
	global_store_dwordx2 v[226:227], v[228:229], off
	global_store_dwordx2 v[226:227], v[230:231], off offset:128
	s_mov_b64 s[4:5], 0x2be00
	v_lshl_add_u64 v[226:227], v[226:227], 0, s[4:5]
	v_mov_b32_e32 v228, v80
	v_mov_b32_e32 v229, v84
	v_mov_b32_e32 v230, v88
	v_mov_b32_e32 v231, v92
	global_store_dwordx2 v[226:227], v[228:229], off
	global_store_dwordx2 v[226:227], v[230:231], off offset:128
	s_mov_b64 s[4:5], 0x3600
	v_lshl_add_u64 v[226:227], v[226:227], 0, s[4:5]
	v_mov_b32_e32 v228, v81
	v_mov_b32_e32 v229, v85
	v_mov_b32_e32 v230, v89
	v_mov_b32_e32 v231, v93
	global_store_dwordx2 v[226:227], v[228:229], off
	global_store_dwordx2 v[226:227], v[230:231], off offset:128
	s_mov_b64 s[4:5], 0x3600
	v_lshl_add_u64 v[226:227], v[226:227], 0, s[4:5]
	v_mov_b32_e32 v228, v82
	v_mov_b32_e32 v229, v86
	v_mov_b32_e32 v230, v90
	v_mov_b32_e32 v231, v94
	global_store_dwordx2 v[226:227], v[228:229], off
	global_store_dwordx2 v[226:227], v[230:231], off offset:128
	s_mov_b64 s[4:5], 0x3600
	v_lshl_add_u64 v[226:227], v[226:227], 0, s[4:5]
	v_mov_b32_e32 v228, v83
	v_mov_b32_e32 v229, v87
	v_mov_b32_e32 v230, v91
	v_mov_b32_e32 v231, v95
	global_store_dwordx2 v[226:227], v[228:229], off
	global_store_dwordx2 v[226:227], v[230:231], off offset:128
	s_mov_b64 s[4:5], 0x2be00
	v_lshl_add_u64 v[226:227], v[226:227], 0, s[4:5]
	v_mov_b32_e32 v228, v96
	v_mov_b32_e32 v229, v100
	v_mov_b32_e32 v230, v104
	v_mov_b32_e32 v231, v108
	global_store_dwordx2 v[226:227], v[228:229], off
	global_store_dwordx2 v[226:227], v[230:231], off offset:128
	s_mov_b64 s[4:5], 0x3600
	v_lshl_add_u64 v[226:227], v[226:227], 0, s[4:5]
	v_mov_b32_e32 v228, v97
	v_mov_b32_e32 v229, v101
	v_mov_b32_e32 v230, v105
	v_mov_b32_e32 v231, v109
	global_store_dwordx2 v[226:227], v[228:229], off
	global_store_dwordx2 v[226:227], v[230:231], off offset:128
	s_mov_b64 s[4:5], 0x3600
	v_lshl_add_u64 v[226:227], v[226:227], 0, s[4:5]
	v_mov_b32_e32 v228, v98
	v_mov_b32_e32 v229, v102
	v_mov_b32_e32 v230, v106
	v_mov_b32_e32 v231, v110
	global_store_dwordx2 v[226:227], v[228:229], off
	global_store_dwordx2 v[226:227], v[230:231], off offset:128
	s_mov_b64 s[4:5], 0x3600
	v_lshl_add_u64 v[226:227], v[226:227], 0, s[4:5]
	v_mov_b32_e32 v228, v99
	v_mov_b32_e32 v229, v103
	v_mov_b32_e32 v230, v107
	v_mov_b32_e32 v231, v111
	global_store_dwordx2 v[226:227], v[228:229], off
	global_store_dwordx2 v[226:227], v[230:231], off offset:128
	s_mov_b64 s[4:5], 0x2be00
	v_lshl_add_u64 v[226:227], v[226:227], 0, s[4:5]
	v_mov_b32_e32 v228, v112
	v_mov_b32_e32 v229, v116
	v_mov_b32_e32 v230, v120
	v_mov_b32_e32 v231, v124
	global_store_dwordx2 v[226:227], v[228:229], off
	global_store_dwordx2 v[226:227], v[230:231], off offset:128
	s_mov_b64 s[4:5], 0x3600
	v_lshl_add_u64 v[226:227], v[226:227], 0, s[4:5]
	v_mov_b32_e32 v228, v113
	v_mov_b32_e32 v229, v117
	v_mov_b32_e32 v230, v121
	v_mov_b32_e32 v231, v125
	global_store_dwordx2 v[226:227], v[228:229], off
	global_store_dwordx2 v[226:227], v[230:231], off offset:128
	s_mov_b64 s[4:5], 0x3600
	v_lshl_add_u64 v[226:227], v[226:227], 0, s[4:5]
	v_mov_b32_e32 v228, v114
	v_mov_b32_e32 v229, v118
	v_mov_b32_e32 v230, v122
	v_mov_b32_e32 v231, v126
	global_store_dwordx2 v[226:227], v[228:229], off
	global_store_dwordx2 v[226:227], v[230:231], off offset:128
	s_mov_b64 s[4:5], 0x3600
	v_lshl_add_u64 v[226:227], v[226:227], 0, s[4:5]
	v_mov_b32_e32 v228, v115
	v_mov_b32_e32 v229, v119
	v_mov_b32_e32 v230, v123
	v_mov_b32_e32 v231, v127
	global_store_dwordx2 v[226:227], v[228:229], off
	global_store_dwordx2 v[226:227], v[230:231], off offset:128
	s_sub_u32 s57, s56, 6
	s_cmp_gt_u32 s57, 2
	s_cbranch_scc1 .Lip_nolin
.Lip_lin0:
	s_cmp_lg_u32 s57, 0
	s_cbranch_scc1 .Lip_lin1
	v_mov_b32_e32 v226, s50
	v_mov_b32_e32 v227, s51
	v_add_co_u32_e32 v226, vcc, v226, v169
	s_nop 1
	v_addc_co_u32_e32 v227, vcc, 0, v227, vcc
	v_add_f32_e32 v228, v0, v0
	v_mul_f32_e32 v228, 0x3fb8aa3b, v228
	v_exp_f32_e32 v228, v228
	s_nop 0
	v_add_f32_e32 v229, 1.0, v228
	v_div_scale_f32 v230, s[4:5], v229, v229, 2.0
	v_rcp_f32_e32 v231, v230
	v_div_scale_f32 v232, vcc, 2.0, v229, 2.0
	v_fma_f32 v131, -v230, v231, 1.0
	v_fmac_f32_e32 v231, v131, v231
	v_mul_f32_e32 v233, v232, v231
	v_fma_f32 v131, -v230, v233, v232
	v_fmac_f32_e32 v233, v131, v231
	v_fma_f32 v230, -v230, v233, v232
	v_div_fmas_f32 v230, v230, v231, v233
	v_div_fixup_f32 v135, v230, v229, 2.0
	v_sub_f32_e32 v135, 1.0, v135
	v_add_f32_e32 v228, v4, v4
	v_mul_f32_e32 v228, 0x3fb8aa3b, v228
	v_exp_f32_e32 v228, v228
	s_nop 0
	v_add_f32_e32 v229, 1.0, v228
	v_div_scale_f32 v230, s[4:5], v229, v229, 2.0
	v_rcp_f32_e32 v231, v230
	v_div_scale_f32 v232, vcc, 2.0, v229, 2.0
	v_fma_f32 v131, -v230, v231, 1.0
	v_fmac_f32_e32 v231, v131, v231
	v_mul_f32_e32 v233, v232, v231
	v_fma_f32 v131, -v230, v233, v232
	v_fmac_f32_e32 v233, v131, v231
	v_fma_f32 v230, -v230, v233, v232
	v_div_fmas_f32 v230, v230, v231, v233
	v_div_fixup_f32 v133, v230, v229, 2.0
	v_sub_f32_e32 v133, 1.0, v133
	v_cvt_pk_bf16_f32 v133, v135, v133
	global_store_dword v[226:227], v133, off
	v_add_f32_e32 v228, v8, v8
	v_mul_f32_e32 v228, 0x3fb8aa3b, v228
	v_exp_f32_e32 v228, v228
	s_nop 0
	v_add_f32_e32 v229, 1.0, v228
	v_div_scale_f32 v230, s[4:5], v229, v229, 2.0
	v_rcp_f32_e32 v231, v230
	v_div_scale_f32 v232, vcc, 2.0, v229, 2.0
	v_fma_f32 v131, -v230, v231, 1.0
	v_fmac_f32_e32 v231, v131, v231
	v_mul_f32_e32 v233, v232, v231
	v_fma_f32 v131, -v230, v233, v232
	v_fmac_f32_e32 v233, v131, v231
	v_fma_f32 v230, -v230, v233, v232
	v_div_fmas_f32 v230, v230, v231, v233
	v_div_fixup_f32 v135, v230, v229, 2.0
	v_sub_f32_e32 v135, 1.0, v135
	v_add_f32_e32 v228, v12, v12
	v_mul_f32_e32 v228, 0x3fb8aa3b, v228
	v_exp_f32_e32 v228, v228
	s_nop 0
	v_add_f32_e32 v229, 1.0, v228
	v_div_scale_f32 v230, s[4:5], v229, v229, 2.0
	v_rcp_f32_e32 v231, v230
	v_div_scale_f32 v232, vcc, 2.0, v229, 2.0
	v_fma_f32 v131, -v230, v231, 1.0
	v_fmac_f32_e32 v231, v131, v231
	v_mul_f32_e32 v233, v232, v231
	v_fma_f32 v131, -v230, v233, v232
	v_fmac_f32_e32 v233, v131, v231
	v_fma_f32 v230, -v230, v233, v232
	v_div_fmas_f32 v230, v230, v231, v233
	v_div_fixup_f32 v133, v230, v229, 2.0
	v_sub_f32_e32 v133, 1.0, v133
	v_cvt_pk_bf16_f32 v133, v135, v133
	global_store_dword v[226:227], v133, off offset:64
	s_mov_b64 s[4:5], 0x300
	v_lshl_add_u64 v[226:227], v[226:227], 0, s[4:5]
	v_add_f32_e32 v228, v1, v1
	v_mul_f32_e32 v228, 0x3fb8aa3b, v228
	v_exp_f32_e32 v228, v228
	s_nop 0
	v_add_f32_e32 v229, 1.0, v228
	v_div_scale_f32 v230, s[4:5], v229, v229, 2.0
	v_rcp_f32_e32 v231, v230
	v_div_scale_f32 v232, vcc, 2.0, v229, 2.0
	v_fma_f32 v131, -v230, v231, 1.0
	v_fmac_f32_e32 v231, v131, v231
	v_mul_f32_e32 v233, v232, v231
	v_fma_f32 v131, -v230, v233, v232
	v_fmac_f32_e32 v233, v131, v231
	v_fma_f32 v230, -v230, v233, v232
	v_div_fmas_f32 v230, v230, v231, v233
	v_div_fixup_f32 v135, v230, v229, 2.0
	v_sub_f32_e32 v135, 1.0, v135
	v_add_f32_e32 v228, v5, v5
	v_mul_f32_e32 v228, 0x3fb8aa3b, v228
	v_exp_f32_e32 v228, v228
	s_nop 0
	v_add_f32_e32 v229, 1.0, v228
	v_div_scale_f32 v230, s[4:5], v229, v229, 2.0
	v_rcp_f32_e32 v231, v230
	v_div_scale_f32 v232, vcc, 2.0, v229, 2.0
	v_fma_f32 v131, -v230, v231, 1.0
	v_fmac_f32_e32 v231, v131, v231
	v_mul_f32_e32 v233, v232, v231
	v_fma_f32 v131, -v230, v233, v232
	v_fmac_f32_e32 v233, v131, v231
	v_fma_f32 v230, -v230, v233, v232
	v_div_fmas_f32 v230, v230, v231, v233
	v_div_fixup_f32 v133, v230, v229, 2.0
	v_sub_f32_e32 v133, 1.0, v133
	v_cvt_pk_bf16_f32 v133, v135, v133
	global_store_dword v[226:227], v133, off
	v_add_f32_e32 v228, v9, v9
	v_mul_f32_e32 v228, 0x3fb8aa3b, v228
	v_exp_f32_e32 v228, v228
	s_nop 0
	v_add_f32_e32 v229, 1.0, v228
	v_div_scale_f32 v230, s[4:5], v229, v229, 2.0
	v_rcp_f32_e32 v231, v230
	v_div_scale_f32 v232, vcc, 2.0, v229, 2.0
	v_fma_f32 v131, -v230, v231, 1.0
	v_fmac_f32_e32 v231, v131, v231
	v_mul_f32_e32 v233, v232, v231
	v_fma_f32 v131, -v230, v233, v232
	v_fmac_f32_e32 v233, v131, v231
	v_fma_f32 v230, -v230, v233, v232
	v_div_fmas_f32 v230, v230, v231, v233
	v_div_fixup_f32 v135, v230, v229, 2.0
	v_sub_f32_e32 v135, 1.0, v135
	v_add_f32_e32 v228, v13, v13
	v_mul_f32_e32 v228, 0x3fb8aa3b, v228
	v_exp_f32_e32 v228, v228
	s_nop 0
	v_add_f32_e32 v229, 1.0, v228
	v_div_scale_f32 v230, s[4:5], v229, v229, 2.0
	v_rcp_f32_e32 v231, v230
	v_div_scale_f32 v232, vcc, 2.0, v229, 2.0
	v_fma_f32 v131, -v230, v231, 1.0
	v_fmac_f32_e32 v231, v131, v231
	v_mul_f32_e32 v233, v232, v231
	v_fma_f32 v131, -v230, v233, v232
	v_fmac_f32_e32 v233, v131, v231
	v_fma_f32 v230, -v230, v233, v232
	v_div_fmas_f32 v230, v230, v231, v233
	v_div_fixup_f32 v133, v230, v229, 2.0
	v_sub_f32_e32 v133, 1.0, v133
	v_cvt_pk_bf16_f32 v133, v135, v133
	global_store_dword v[226:227], v133, off offset:64
	s_mov_b64 s[4:5], 0x300
	v_lshl_add_u64 v[226:227], v[226:227], 0, s[4:5]
	v_add_f32_e32 v228, v2, v2
	v_mul_f32_e32 v228, 0x3fb8aa3b, v228
	v_exp_f32_e32 v228, v228
	s_nop 0
	v_add_f32_e32 v229, 1.0, v228
	v_div_scale_f32 v230, s[4:5], v229, v229, 2.0
	v_rcp_f32_e32 v231, v230
	v_div_scale_f32 v232, vcc, 2.0, v229, 2.0
	v_fma_f32 v131, -v230, v231, 1.0
	v_fmac_f32_e32 v231, v131, v231
	v_mul_f32_e32 v233, v232, v231
	v_fma_f32 v131, -v230, v233, v232
	v_fmac_f32_e32 v233, v131, v231
	v_fma_f32 v230, -v230, v233, v232
	v_div_fmas_f32 v230, v230, v231, v233
	v_div_fixup_f32 v135, v230, v229, 2.0
	v_sub_f32_e32 v135, 1.0, v135
	v_add_f32_e32 v228, v6, v6
	v_mul_f32_e32 v228, 0x3fb8aa3b, v228
	v_exp_f32_e32 v228, v228
	s_nop 0
	v_add_f32_e32 v229, 1.0, v228
	v_div_scale_f32 v230, s[4:5], v229, v229, 2.0
	v_rcp_f32_e32 v231, v230
	v_div_scale_f32 v232, vcc, 2.0, v229, 2.0
	v_fma_f32 v131, -v230, v231, 1.0
	v_fmac_f32_e32 v231, v131, v231
	v_mul_f32_e32 v233, v232, v231
	v_fma_f32 v131, -v230, v233, v232
	v_fmac_f32_e32 v233, v131, v231
	v_fma_f32 v230, -v230, v233, v232
	v_div_fmas_f32 v230, v230, v231, v233
	v_div_fixup_f32 v133, v230, v229, 2.0
	v_sub_f32_e32 v133, 1.0, v133
	v_cvt_pk_bf16_f32 v133, v135, v133
	global_store_dword v[226:227], v133, off
	v_add_f32_e32 v228, v10, v10
	v_mul_f32_e32 v228, 0x3fb8aa3b, v228
	v_exp_f32_e32 v228, v228
	s_nop 0
	v_add_f32_e32 v229, 1.0, v228
	v_div_scale_f32 v230, s[4:5], v229, v229, 2.0
	v_rcp_f32_e32 v231, v230
	v_div_scale_f32 v232, vcc, 2.0, v229, 2.0
	v_fma_f32 v131, -v230, v231, 1.0
	v_fmac_f32_e32 v231, v131, v231
	v_mul_f32_e32 v233, v232, v231
	v_fma_f32 v131, -v230, v233, v232
	v_fmac_f32_e32 v233, v131, v231
	v_fma_f32 v230, -v230, v233, v232
	v_div_fmas_f32 v230, v230, v231, v233
	v_div_fixup_f32 v135, v230, v229, 2.0
	v_sub_f32_e32 v135, 1.0, v135
	v_add_f32_e32 v228, v14, v14
	v_mul_f32_e32 v228, 0x3fb8aa3b, v228
	v_exp_f32_e32 v228, v228
	s_nop 0
	v_add_f32_e32 v229, 1.0, v228
	v_div_scale_f32 v230, s[4:5], v229, v229, 2.0
	v_rcp_f32_e32 v231, v230
	v_div_scale_f32 v232, vcc, 2.0, v229, 2.0
	v_fma_f32 v131, -v230, v231, 1.0
	v_fmac_f32_e32 v231, v131, v231
	v_mul_f32_e32 v233, v232, v231
	v_fma_f32 v131, -v230, v233, v232
	v_fmac_f32_e32 v233, v131, v231
	v_fma_f32 v230, -v230, v233, v232
	v_div_fmas_f32 v230, v230, v231, v233
	v_div_fixup_f32 v133, v230, v229, 2.0
	v_sub_f32_e32 v133, 1.0, v133
	v_cvt_pk_bf16_f32 v133, v135, v133
	global_store_dword v[226:227], v133, off offset:64
	s_mov_b64 s[4:5], 0x300
	v_lshl_add_u64 v[226:227], v[226:227], 0, s[4:5]
	v_add_f32_e32 v228, v3, v3
	v_mul_f32_e32 v228, 0x3fb8aa3b, v228
	v_exp_f32_e32 v228, v228
	s_nop 0
	v_add_f32_e32 v229, 1.0, v228
	v_div_scale_f32 v230, s[4:5], v229, v229, 2.0
	v_rcp_f32_e32 v231, v230
	v_div_scale_f32 v232, vcc, 2.0, v229, 2.0
	v_fma_f32 v131, -v230, v231, 1.0
	v_fmac_f32_e32 v231, v131, v231
	v_mul_f32_e32 v233, v232, v231
	v_fma_f32 v131, -v230, v233, v232
	v_fmac_f32_e32 v233, v131, v231
	v_fma_f32 v230, -v230, v233, v232
	v_div_fmas_f32 v230, v230, v231, v233
	v_div_fixup_f32 v135, v230, v229, 2.0
	v_sub_f32_e32 v135, 1.0, v135
	v_add_f32_e32 v228, v7, v7
	v_mul_f32_e32 v228, 0x3fb8aa3b, v228
	v_exp_f32_e32 v228, v228
	s_nop 0
	v_add_f32_e32 v229, 1.0, v228
	v_div_scale_f32 v230, s[4:5], v229, v229, 2.0
	v_rcp_f32_e32 v231, v230
	v_div_scale_f32 v232, vcc, 2.0, v229, 2.0
	v_fma_f32 v131, -v230, v231, 1.0
	v_fmac_f32_e32 v231, v131, v231
	v_mul_f32_e32 v233, v232, v231
	v_fma_f32 v131, -v230, v233, v232
	v_fmac_f32_e32 v233, v131, v231
	v_fma_f32 v230, -v230, v233, v232
	v_div_fmas_f32 v230, v230, v231, v233
	v_div_fixup_f32 v133, v230, v229, 2.0
	v_sub_f32_e32 v133, 1.0, v133
	v_cvt_pk_bf16_f32 v133, v135, v133
	global_store_dword v[226:227], v133, off
	v_add_f32_e32 v228, v11, v11
	v_mul_f32_e32 v228, 0x3fb8aa3b, v228
	v_exp_f32_e32 v228, v228
	s_nop 0
	v_add_f32_e32 v229, 1.0, v228
	v_div_scale_f32 v230, s[4:5], v229, v229, 2.0
	v_rcp_f32_e32 v231, v230
	v_div_scale_f32 v232, vcc, 2.0, v229, 2.0
	v_fma_f32 v131, -v230, v231, 1.0
	v_fmac_f32_e32 v231, v131, v231
	v_mul_f32_e32 v233, v232, v231
	v_fma_f32 v131, -v230, v233, v232
	v_fmac_f32_e32 v233, v131, v231
	v_fma_f32 v230, -v230, v233, v232
	v_div_fmas_f32 v230, v230, v231, v233
	v_div_fixup_f32 v135, v230, v229, 2.0
	v_sub_f32_e32 v135, 1.0, v135
	v_add_f32_e32 v228, v15, v15
	v_mul_f32_e32 v228, 0x3fb8aa3b, v228
	v_exp_f32_e32 v228, v228
	s_nop 0
	v_add_f32_e32 v229, 1.0, v228
	v_div_scale_f32 v230, s[4:5], v229, v229, 2.0
	v_rcp_f32_e32 v231, v230
	v_div_scale_f32 v232, vcc, 2.0, v229, 2.0
	v_fma_f32 v131, -v230, v231, 1.0
	v_fmac_f32_e32 v231, v131, v231
	v_mul_f32_e32 v233, v232, v231
	v_fma_f32 v131, -v230, v233, v232
	v_fmac_f32_e32 v233, v131, v231
	v_fma_f32 v230, -v230, v233, v232
	v_div_fmas_f32 v230, v230, v231, v233
	v_div_fixup_f32 v133, v230, v229, 2.0
	v_sub_f32_e32 v133, 1.0, v133
	v_cvt_pk_bf16_f32 v133, v135, v133
	global_store_dword v[226:227], v133, off offset:64
	s_mov_b64 s[4:5], 0x2700
	v_lshl_add_u64 v[226:227], v[226:227], 0, s[4:5]
	v_add_f32_e32 v228, v16, v16
	v_mul_f32_e32 v228, 0x3fb8aa3b, v228
	v_exp_f32_e32 v228, v228
	s_nop 0
	v_add_f32_e32 v229, 1.0, v228
	v_div_scale_f32 v230, s[4:5], v229, v229, 2.0
	v_rcp_f32_e32 v231, v230
	v_div_scale_f32 v232, vcc, 2.0, v229, 2.0
	v_fma_f32 v131, -v230, v231, 1.0
	v_fmac_f32_e32 v231, v131, v231
	v_mul_f32_e32 v233, v232, v231
	v_fma_f32 v131, -v230, v233, v232
	v_fmac_f32_e32 v233, v131, v231
	v_fma_f32 v230, -v230, v233, v232
	v_div_fmas_f32 v230, v230, v231, v233
	v_div_fixup_f32 v135, v230, v229, 2.0
	v_sub_f32_e32 v135, 1.0, v135
	v_add_f32_e32 v228, v20, v20
	v_mul_f32_e32 v228, 0x3fb8aa3b, v228
	v_exp_f32_e32 v228, v228
	s_nop 0
	v_add_f32_e32 v229, 1.0, v228
	v_div_scale_f32 v230, s[4:5], v229, v229, 2.0
	v_rcp_f32_e32 v231, v230
	v_div_scale_f32 v232, vcc, 2.0, v229, 2.0
	v_fma_f32 v131, -v230, v231, 1.0
	v_fmac_f32_e32 v231, v131, v231
	v_mul_f32_e32 v233, v232, v231
	v_fma_f32 v131, -v230, v233, v232
	v_fmac_f32_e32 v233, v131, v231
	v_fma_f32 v230, -v230, v233, v232
	v_div_fmas_f32 v230, v230, v231, v233
	v_div_fixup_f32 v133, v230, v229, 2.0
	v_sub_f32_e32 v133, 1.0, v133
	v_cvt_pk_bf16_f32 v133, v135, v133
	global_store_dword v[226:227], v133, off
	v_add_f32_e32 v228, v24, v24
	v_mul_f32_e32 v228, 0x3fb8aa3b, v228
	v_exp_f32_e32 v228, v228
	s_nop 0
	v_add_f32_e32 v229, 1.0, v228
	v_div_scale_f32 v230, s[4:5], v229, v229, 2.0
	v_rcp_f32_e32 v231, v230
	v_div_scale_f32 v232, vcc, 2.0, v229, 2.0
	v_fma_f32 v131, -v230, v231, 1.0
	v_fmac_f32_e32 v231, v131, v231
	v_mul_f32_e32 v233, v232, v231
	v_fma_f32 v131, -v230, v233, v232
	v_fmac_f32_e32 v233, v131, v231
	v_fma_f32 v230, -v230, v233, v232
	v_div_fmas_f32 v230, v230, v231, v233
	v_div_fixup_f32 v135, v230, v229, 2.0
	v_sub_f32_e32 v135, 1.0, v135
	v_add_f32_e32 v228, v28, v28
	v_mul_f32_e32 v228, 0x3fb8aa3b, v228
	v_exp_f32_e32 v228, v228
	s_nop 0
	v_add_f32_e32 v229, 1.0, v228
	v_div_scale_f32 v230, s[4:5], v229, v229, 2.0
	v_rcp_f32_e32 v231, v230
	v_div_scale_f32 v232, vcc, 2.0, v229, 2.0
	v_fma_f32 v131, -v230, v231, 1.0
	v_fmac_f32_e32 v231, v131, v231
	v_mul_f32_e32 v233, v232, v231
	v_fma_f32 v131, -v230, v233, v232
	v_fmac_f32_e32 v233, v131, v231
	v_fma_f32 v230, -v230, v233, v232
	v_div_fmas_f32 v230, v230, v231, v233
	v_div_fixup_f32 v133, v230, v229, 2.0
	v_sub_f32_e32 v133, 1.0, v133
	v_cvt_pk_bf16_f32 v133, v135, v133
	global_store_dword v[226:227], v133, off offset:64
	s_mov_b64 s[4:5], 0x300
	v_lshl_add_u64 v[226:227], v[226:227], 0, s[4:5]
	v_add_f32_e32 v228, v17, v17
	v_mul_f32_e32 v228, 0x3fb8aa3b, v228
	v_exp_f32_e32 v228, v228
	s_nop 0
	v_add_f32_e32 v229, 1.0, v228
	v_div_scale_f32 v230, s[4:5], v229, v229, 2.0
	v_rcp_f32_e32 v231, v230
	v_div_scale_f32 v232, vcc, 2.0, v229, 2.0
	v_fma_f32 v131, -v230, v231, 1.0
	v_fmac_f32_e32 v231, v131, v231
	v_mul_f32_e32 v233, v232, v231
	v_fma_f32 v131, -v230, v233, v232
	v_fmac_f32_e32 v233, v131, v231
	v_fma_f32 v230, -v230, v233, v232
	v_div_fmas_f32 v230, v230, v231, v233
	v_div_fixup_f32 v135, v230, v229, 2.0
	v_sub_f32_e32 v135, 1.0, v135
	v_add_f32_e32 v228, v21, v21
	v_mul_f32_e32 v228, 0x3fb8aa3b, v228
	v_exp_f32_e32 v228, v228
	s_nop 0
	v_add_f32_e32 v229, 1.0, v228
	v_div_scale_f32 v230, s[4:5], v229, v229, 2.0
	v_rcp_f32_e32 v231, v230
	v_div_scale_f32 v232, vcc, 2.0, v229, 2.0
	v_fma_f32 v131, -v230, v231, 1.0
	v_fmac_f32_e32 v231, v131, v231
	v_mul_f32_e32 v233, v232, v231
	v_fma_f32 v131, -v230, v233, v232
	v_fmac_f32_e32 v233, v131, v231
	v_fma_f32 v230, -v230, v233, v232
	v_div_fmas_f32 v230, v230, v231, v233
	v_div_fixup_f32 v133, v230, v229, 2.0
	v_sub_f32_e32 v133, 1.0, v133
	v_cvt_pk_bf16_f32 v133, v135, v133
	global_store_dword v[226:227], v133, off
	v_add_f32_e32 v228, v25, v25
	v_mul_f32_e32 v228, 0x3fb8aa3b, v228
	v_exp_f32_e32 v228, v228
	s_nop 0
	v_add_f32_e32 v229, 1.0, v228
	v_div_scale_f32 v230, s[4:5], v229, v229, 2.0
	v_rcp_f32_e32 v231, v230
	v_div_scale_f32 v232, vcc, 2.0, v229, 2.0
	v_fma_f32 v131, -v230, v231, 1.0
	v_fmac_f32_e32 v231, v131, v231
	v_mul_f32_e32 v233, v232, v231
	v_fma_f32 v131, -v230, v233, v232
	v_fmac_f32_e32 v233, v131, v231
	v_fma_f32 v230, -v230, v233, v232
	v_div_fmas_f32 v230, v230, v231, v233
	v_div_fixup_f32 v135, v230, v229, 2.0
	v_sub_f32_e32 v135, 1.0, v135
	v_add_f32_e32 v228, v29, v29
	v_mul_f32_e32 v228, 0x3fb8aa3b, v228
	v_exp_f32_e32 v228, v228
	s_nop 0
	v_add_f32_e32 v229, 1.0, v228
	v_div_scale_f32 v230, s[4:5], v229, v229, 2.0
	v_rcp_f32_e32 v231, v230
	v_div_scale_f32 v232, vcc, 2.0, v229, 2.0
	v_fma_f32 v131, -v230, v231, 1.0
	v_fmac_f32_e32 v231, v131, v231
	v_mul_f32_e32 v233, v232, v231
	v_fma_f32 v131, -v230, v233, v232
	v_fmac_f32_e32 v233, v131, v231
	v_fma_f32 v230, -v230, v233, v232
	v_div_fmas_f32 v230, v230, v231, v233
	v_div_fixup_f32 v133, v230, v229, 2.0
	v_sub_f32_e32 v133, 1.0, v133
	v_cvt_pk_bf16_f32 v133, v135, v133
	global_store_dword v[226:227], v133, off offset:64
	s_mov_b64 s[4:5], 0x300
	v_lshl_add_u64 v[226:227], v[226:227], 0, s[4:5]
	v_add_f32_e32 v228, v18, v18
	v_mul_f32_e32 v228, 0x3fb8aa3b, v228
	v_exp_f32_e32 v228, v228
	s_nop 0
	v_add_f32_e32 v229, 1.0, v228
	v_div_scale_f32 v230, s[4:5], v229, v229, 2.0
	v_rcp_f32_e32 v231, v230
	v_div_scale_f32 v232, vcc, 2.0, v229, 2.0
	v_fma_f32 v131, -v230, v231, 1.0
	v_fmac_f32_e32 v231, v131, v231
	v_mul_f32_e32 v233, v232, v231
	v_fma_f32 v131, -v230, v233, v232
	v_fmac_f32_e32 v233, v131, v231
	v_fma_f32 v230, -v230, v233, v232
	v_div_fmas_f32 v230, v230, v231, v233
	v_div_fixup_f32 v135, v230, v229, 2.0
	v_sub_f32_e32 v135, 1.0, v135
	v_add_f32_e32 v228, v22, v22
	v_mul_f32_e32 v228, 0x3fb8aa3b, v228
	v_exp_f32_e32 v228, v228
	s_nop 0
	v_add_f32_e32 v229, 1.0, v228
	v_div_scale_f32 v230, s[4:5], v229, v229, 2.0
	v_rcp_f32_e32 v231, v230
	v_div_scale_f32 v232, vcc, 2.0, v229, 2.0
	v_fma_f32 v131, -v230, v231, 1.0
	v_fmac_f32_e32 v231, v131, v231
	v_mul_f32_e32 v233, v232, v231
	v_fma_f32 v131, -v230, v233, v232
	v_fmac_f32_e32 v233, v131, v231
	v_fma_f32 v230, -v230, v233, v232
	v_div_fmas_f32 v230, v230, v231, v233
	v_div_fixup_f32 v133, v230, v229, 2.0
	v_sub_f32_e32 v133, 1.0, v133
	v_cvt_pk_bf16_f32 v133, v135, v133
	global_store_dword v[226:227], v133, off
	v_add_f32_e32 v228, v26, v26
	v_mul_f32_e32 v228, 0x3fb8aa3b, v228
	v_exp_f32_e32 v228, v228
	s_nop 0
	v_add_f32_e32 v229, 1.0, v228
	v_div_scale_f32 v230, s[4:5], v229, v229, 2.0
	v_rcp_f32_e32 v231, v230
	v_div_scale_f32 v232, vcc, 2.0, v229, 2.0
	v_fma_f32 v131, -v230, v231, 1.0
	v_fmac_f32_e32 v231, v131, v231
	v_mul_f32_e32 v233, v232, v231
	v_fma_f32 v131, -v230, v233, v232
	v_fmac_f32_e32 v233, v131, v231
	v_fma_f32 v230, -v230, v233, v232
	v_div_fmas_f32 v230, v230, v231, v233
	v_div_fixup_f32 v135, v230, v229, 2.0
	v_sub_f32_e32 v135, 1.0, v135
	v_add_f32_e32 v228, v30, v30
	v_mul_f32_e32 v228, 0x3fb8aa3b, v228
	v_exp_f32_e32 v228, v228
	s_nop 0
	v_add_f32_e32 v229, 1.0, v228
	v_div_scale_f32 v230, s[4:5], v229, v229, 2.0
	v_rcp_f32_e32 v231, v230
	v_div_scale_f32 v232, vcc, 2.0, v229, 2.0
	v_fma_f32 v131, -v230, v231, 1.0
	v_fmac_f32_e32 v231, v131, v231
	v_mul_f32_e32 v233, v232, v231
	v_fma_f32 v131, -v230, v233, v232
	v_fmac_f32_e32 v233, v131, v231
	v_fma_f32 v230, -v230, v233, v232
	v_div_fmas_f32 v230, v230, v231, v233
	v_div_fixup_f32 v133, v230, v229, 2.0
	v_sub_f32_e32 v133, 1.0, v133
	v_cvt_pk_bf16_f32 v133, v135, v133
	global_store_dword v[226:227], v133, off offset:64
	s_mov_b64 s[4:5], 0x300
	v_lshl_add_u64 v[226:227], v[226:227], 0, s[4:5]
	v_add_f32_e32 v228, v19, v19
	v_mul_f32_e32 v228, 0x3fb8aa3b, v228
	v_exp_f32_e32 v228, v228
	s_nop 0
	v_add_f32_e32 v229, 1.0, v228
	v_div_scale_f32 v230, s[4:5], v229, v229, 2.0
	v_rcp_f32_e32 v231, v230
	v_div_scale_f32 v232, vcc, 2.0, v229, 2.0
	v_fma_f32 v131, -v230, v231, 1.0
	v_fmac_f32_e32 v231, v131, v231
	v_mul_f32_e32 v233, v232, v231
	v_fma_f32 v131, -v230, v233, v232
	v_fmac_f32_e32 v233, v131, v231
	v_fma_f32 v230, -v230, v233, v232
	v_div_fmas_f32 v230, v230, v231, v233
	v_div_fixup_f32 v135, v230, v229, 2.0
	v_sub_f32_e32 v135, 1.0, v135
	v_add_f32_e32 v228, v23, v23
	v_mul_f32_e32 v228, 0x3fb8aa3b, v228
	v_exp_f32_e32 v228, v228
	s_nop 0
	v_add_f32_e32 v229, 1.0, v228
	v_div_scale_f32 v230, s[4:5], v229, v229, 2.0
	v_rcp_f32_e32 v231, v230
	v_div_scale_f32 v232, vcc, 2.0, v229, 2.0
	v_fma_f32 v131, -v230, v231, 1.0
	v_fmac_f32_e32 v231, v131, v231
	v_mul_f32_e32 v233, v232, v231
	v_fma_f32 v131, -v230, v233, v232
	v_fmac_f32_e32 v233, v131, v231
	v_fma_f32 v230, -v230, v233, v232
	v_div_fmas_f32 v230, v230, v231, v233
	v_div_fixup_f32 v133, v230, v229, 2.0
	v_sub_f32_e32 v133, 1.0, v133
	v_cvt_pk_bf16_f32 v133, v135, v133
	global_store_dword v[226:227], v133, off
	v_add_f32_e32 v228, v27, v27
	v_mul_f32_e32 v228, 0x3fb8aa3b, v228
	v_exp_f32_e32 v228, v228
	s_nop 0
	v_add_f32_e32 v229, 1.0, v228
	v_div_scale_f32 v230, s[4:5], v229, v229, 2.0
	v_rcp_f32_e32 v231, v230
	v_div_scale_f32 v232, vcc, 2.0, v229, 2.0
	v_fma_f32 v131, -v230, v231, 1.0
	v_fmac_f32_e32 v231, v131, v231
	v_mul_f32_e32 v233, v232, v231
	v_fma_f32 v131, -v230, v233, v232
	v_fmac_f32_e32 v233, v131, v231
	v_fma_f32 v230, -v230, v233, v232
	v_div_fmas_f32 v230, v230, v231, v233
	v_div_fixup_f32 v135, v230, v229, 2.0
	v_sub_f32_e32 v135, 1.0, v135
	v_add_f32_e32 v228, v31, v31
	v_mul_f32_e32 v228, 0x3fb8aa3b, v228
	v_exp_f32_e32 v228, v228
	s_nop 0
	v_add_f32_e32 v229, 1.0, v228
	v_div_scale_f32 v230, s[4:5], v229, v229, 2.0
	v_rcp_f32_e32 v231, v230
	v_div_scale_f32 v232, vcc, 2.0, v229, 2.0
	v_fma_f32 v131, -v230, v231, 1.0
	v_fmac_f32_e32 v231, v131, v231
	v_mul_f32_e32 v233, v232, v231
	v_fma_f32 v131, -v230, v233, v232
	v_fmac_f32_e32 v233, v131, v231
	v_fma_f32 v230, -v230, v233, v232
	v_div_fmas_f32 v230, v230, v231, v233
	v_div_fixup_f32 v133, v230, v229, 2.0
	v_sub_f32_e32 v133, 1.0, v133
	v_cvt_pk_bf16_f32 v133, v135, v133
	global_store_dword v[226:227], v133, off offset:64
	s_mov_b64 s[4:5], 0x2700
	v_lshl_add_u64 v[226:227], v[226:227], 0, s[4:5]
	v_add_f32_e32 v228, v32, v32
	v_mul_f32_e32 v228, 0x3fb8aa3b, v228
	v_exp_f32_e32 v228, v228
	s_nop 0
	v_add_f32_e32 v229, 1.0, v228
	v_div_scale_f32 v230, s[4:5], v229, v229, 2.0
	v_rcp_f32_e32 v231, v230
	v_div_scale_f32 v232, vcc, 2.0, v229, 2.0
	v_fma_f32 v131, -v230, v231, 1.0
	v_fmac_f32_e32 v231, v131, v231
	v_mul_f32_e32 v233, v232, v231
	v_fma_f32 v131, -v230, v233, v232
	v_fmac_f32_e32 v233, v131, v231
	v_fma_f32 v230, -v230, v233, v232
	v_div_fmas_f32 v230, v230, v231, v233
	v_div_fixup_f32 v135, v230, v229, 2.0
	v_sub_f32_e32 v135, 1.0, v135
	v_add_f32_e32 v228, v36, v36
	v_mul_f32_e32 v228, 0x3fb8aa3b, v228
	v_exp_f32_e32 v228, v228
	s_nop 0
	v_add_f32_e32 v229, 1.0, v228
	v_div_scale_f32 v230, s[4:5], v229, v229, 2.0
	v_rcp_f32_e32 v231, v230
	v_div_scale_f32 v232, vcc, 2.0, v229, 2.0
	v_fma_f32 v131, -v230, v231, 1.0
	v_fmac_f32_e32 v231, v131, v231
	v_mul_f32_e32 v233, v232, v231
	v_fma_f32 v131, -v230, v233, v232
	v_fmac_f32_e32 v233, v131, v231
	v_fma_f32 v230, -v230, v233, v232
	v_div_fmas_f32 v230, v230, v231, v233
	v_div_fixup_f32 v133, v230, v229, 2.0
	v_sub_f32_e32 v133, 1.0, v133
	v_cvt_pk_bf16_f32 v133, v135, v133
	global_store_dword v[226:227], v133, off
	v_add_f32_e32 v228, v40, v40
	v_mul_f32_e32 v228, 0x3fb8aa3b, v228
	v_exp_f32_e32 v228, v228
	s_nop 0
	v_add_f32_e32 v229, 1.0, v228
	v_div_scale_f32 v230, s[4:5], v229, v229, 2.0
	v_rcp_f32_e32 v231, v230
	v_div_scale_f32 v232, vcc, 2.0, v229, 2.0
	v_fma_f32 v131, -v230, v231, 1.0
	v_fmac_f32_e32 v231, v131, v231
	v_mul_f32_e32 v233, v232, v231
	v_fma_f32 v131, -v230, v233, v232
	v_fmac_f32_e32 v233, v131, v231
	v_fma_f32 v230, -v230, v233, v232
	v_div_fmas_f32 v230, v230, v231, v233
	v_div_fixup_f32 v135, v230, v229, 2.0
	v_sub_f32_e32 v135, 1.0, v135
	v_add_f32_e32 v228, v44, v44
	v_mul_f32_e32 v228, 0x3fb8aa3b, v228
	v_exp_f32_e32 v228, v228
	s_nop 0
	v_add_f32_e32 v229, 1.0, v228
	v_div_scale_f32 v230, s[4:5], v229, v229, 2.0
	v_rcp_f32_e32 v231, v230
	v_div_scale_f32 v232, vcc, 2.0, v229, 2.0
	v_fma_f32 v131, -v230, v231, 1.0
	v_fmac_f32_e32 v231, v131, v231
	v_mul_f32_e32 v233, v232, v231
	v_fma_f32 v131, -v230, v233, v232
	v_fmac_f32_e32 v233, v131, v231
	v_fma_f32 v230, -v230, v233, v232
	v_div_fmas_f32 v230, v230, v231, v233
	v_div_fixup_f32 v133, v230, v229, 2.0
	v_sub_f32_e32 v133, 1.0, v133
	v_cvt_pk_bf16_f32 v133, v135, v133
	global_store_dword v[226:227], v133, off offset:64
	s_mov_b64 s[4:5], 0x300
	v_lshl_add_u64 v[226:227], v[226:227], 0, s[4:5]
	v_add_f32_e32 v228, v33, v33
	v_mul_f32_e32 v228, 0x3fb8aa3b, v228
	v_exp_f32_e32 v228, v228
	s_nop 0
	v_add_f32_e32 v229, 1.0, v228
	v_div_scale_f32 v230, s[4:5], v229, v229, 2.0
	v_rcp_f32_e32 v231, v230
	v_div_scale_f32 v232, vcc, 2.0, v229, 2.0
	v_fma_f32 v131, -v230, v231, 1.0
	v_fmac_f32_e32 v231, v131, v231
	v_mul_f32_e32 v233, v232, v231
	v_fma_f32 v131, -v230, v233, v232
	v_fmac_f32_e32 v233, v131, v231
	v_fma_f32 v230, -v230, v233, v232
	v_div_fmas_f32 v230, v230, v231, v233
	v_div_fixup_f32 v135, v230, v229, 2.0
	v_sub_f32_e32 v135, 1.0, v135
	v_add_f32_e32 v228, v37, v37
	v_mul_f32_e32 v228, 0x3fb8aa3b, v228
	v_exp_f32_e32 v228, v228
	s_nop 0
	v_add_f32_e32 v229, 1.0, v228
	v_div_scale_f32 v230, s[4:5], v229, v229, 2.0
	v_rcp_f32_e32 v231, v230
	v_div_scale_f32 v232, vcc, 2.0, v229, 2.0
	v_fma_f32 v131, -v230, v231, 1.0
	v_fmac_f32_e32 v231, v131, v231
	v_mul_f32_e32 v233, v232, v231
	v_fma_f32 v131, -v230, v233, v232
	v_fmac_f32_e32 v233, v131, v231
	v_fma_f32 v230, -v230, v233, v232
	v_div_fmas_f32 v230, v230, v231, v233
	v_div_fixup_f32 v133, v230, v229, 2.0
	v_sub_f32_e32 v133, 1.0, v133
	v_cvt_pk_bf16_f32 v133, v135, v133
	global_store_dword v[226:227], v133, off
	v_add_f32_e32 v228, v41, v41
	v_mul_f32_e32 v228, 0x3fb8aa3b, v228
	v_exp_f32_e32 v228, v228
	s_nop 0
	v_add_f32_e32 v229, 1.0, v228
	v_div_scale_f32 v230, s[4:5], v229, v229, 2.0
	v_rcp_f32_e32 v231, v230
	v_div_scale_f32 v232, vcc, 2.0, v229, 2.0
	v_fma_f32 v131, -v230, v231, 1.0
	v_fmac_f32_e32 v231, v131, v231
	v_mul_f32_e32 v233, v232, v231
	v_fma_f32 v131, -v230, v233, v232
	v_fmac_f32_e32 v233, v131, v231
	v_fma_f32 v230, -v230, v233, v232
	v_div_fmas_f32 v230, v230, v231, v233
	v_div_fixup_f32 v135, v230, v229, 2.0
	v_sub_f32_e32 v135, 1.0, v135
	v_add_f32_e32 v228, v45, v45
	v_mul_f32_e32 v228, 0x3fb8aa3b, v228
	v_exp_f32_e32 v228, v228
	s_nop 0
	v_add_f32_e32 v229, 1.0, v228
	v_div_scale_f32 v230, s[4:5], v229, v229, 2.0
	v_rcp_f32_e32 v231, v230
	v_div_scale_f32 v232, vcc, 2.0, v229, 2.0
	v_fma_f32 v131, -v230, v231, 1.0
	v_fmac_f32_e32 v231, v131, v231
	v_mul_f32_e32 v233, v232, v231
	v_fma_f32 v131, -v230, v233, v232
	v_fmac_f32_e32 v233, v131, v231
	v_fma_f32 v230, -v230, v233, v232
	v_div_fmas_f32 v230, v230, v231, v233
	v_div_fixup_f32 v133, v230, v229, 2.0
	v_sub_f32_e32 v133, 1.0, v133
	v_cvt_pk_bf16_f32 v133, v135, v133
	global_store_dword v[226:227], v133, off offset:64
	s_mov_b64 s[4:5], 0x300
	v_lshl_add_u64 v[226:227], v[226:227], 0, s[4:5]
	v_add_f32_e32 v228, v34, v34
	v_mul_f32_e32 v228, 0x3fb8aa3b, v228
	v_exp_f32_e32 v228, v228
	s_nop 0
	v_add_f32_e32 v229, 1.0, v228
	v_div_scale_f32 v230, s[4:5], v229, v229, 2.0
	v_rcp_f32_e32 v231, v230
	v_div_scale_f32 v232, vcc, 2.0, v229, 2.0
	v_fma_f32 v131, -v230, v231, 1.0
	v_fmac_f32_e32 v231, v131, v231
	v_mul_f32_e32 v233, v232, v231
	v_fma_f32 v131, -v230, v233, v232
	v_fmac_f32_e32 v233, v131, v231
	v_fma_f32 v230, -v230, v233, v232
	v_div_fmas_f32 v230, v230, v231, v233
	v_div_fixup_f32 v135, v230, v229, 2.0
	v_sub_f32_e32 v135, 1.0, v135
	v_add_f32_e32 v228, v38, v38
	v_mul_f32_e32 v228, 0x3fb8aa3b, v228
	v_exp_f32_e32 v228, v228
	s_nop 0
	v_add_f32_e32 v229, 1.0, v228
	v_div_scale_f32 v230, s[4:5], v229, v229, 2.0
	v_rcp_f32_e32 v231, v230
	v_div_scale_f32 v232, vcc, 2.0, v229, 2.0
	v_fma_f32 v131, -v230, v231, 1.0
	v_fmac_f32_e32 v231, v131, v231
	v_mul_f32_e32 v233, v232, v231
	v_fma_f32 v131, -v230, v233, v232
	v_fmac_f32_e32 v233, v131, v231
	v_fma_f32 v230, -v230, v233, v232
	v_div_fmas_f32 v230, v230, v231, v233
	v_div_fixup_f32 v133, v230, v229, 2.0
	v_sub_f32_e32 v133, 1.0, v133
	v_cvt_pk_bf16_f32 v133, v135, v133
	global_store_dword v[226:227], v133, off
	v_add_f32_e32 v228, v42, v42
	v_mul_f32_e32 v228, 0x3fb8aa3b, v228
	v_exp_f32_e32 v228, v228
	s_nop 0
	v_add_f32_e32 v229, 1.0, v228
	v_div_scale_f32 v230, s[4:5], v229, v229, 2.0
	v_rcp_f32_e32 v231, v230
	v_div_scale_f32 v232, vcc, 2.0, v229, 2.0
	v_fma_f32 v131, -v230, v231, 1.0
	v_fmac_f32_e32 v231, v131, v231
	v_mul_f32_e32 v233, v232, v231
	v_fma_f32 v131, -v230, v233, v232
	v_fmac_f32_e32 v233, v131, v231
	v_fma_f32 v230, -v230, v233, v232
	v_div_fmas_f32 v230, v230, v231, v233
	v_div_fixup_f32 v135, v230, v229, 2.0
	v_sub_f32_e32 v135, 1.0, v135
	v_add_f32_e32 v228, v46, v46
	v_mul_f32_e32 v228, 0x3fb8aa3b, v228
	v_exp_f32_e32 v228, v228
	s_nop 0
	v_add_f32_e32 v229, 1.0, v228
	v_div_scale_f32 v230, s[4:5], v229, v229, 2.0
	v_rcp_f32_e32 v231, v230
	v_div_scale_f32 v232, vcc, 2.0, v229, 2.0
	v_fma_f32 v131, -v230, v231, 1.0
	v_fmac_f32_e32 v231, v131, v231
	v_mul_f32_e32 v233, v232, v231
	v_fma_f32 v131, -v230, v233, v232
	v_fmac_f32_e32 v233, v131, v231
	v_fma_f32 v230, -v230, v233, v232
	v_div_fmas_f32 v230, v230, v231, v233
	v_div_fixup_f32 v133, v230, v229, 2.0
	v_sub_f32_e32 v133, 1.0, v133
	v_cvt_pk_bf16_f32 v133, v135, v133
	global_store_dword v[226:227], v133, off offset:64
	s_mov_b64 s[4:5], 0x300
	v_lshl_add_u64 v[226:227], v[226:227], 0, s[4:5]
	v_add_f32_e32 v228, v35, v35
	v_mul_f32_e32 v228, 0x3fb8aa3b, v228
	v_exp_f32_e32 v228, v228
	s_nop 0
	v_add_f32_e32 v229, 1.0, v228
	v_div_scale_f32 v230, s[4:5], v229, v229, 2.0
	v_rcp_f32_e32 v231, v230
	v_div_scale_f32 v232, vcc, 2.0, v229, 2.0
	v_fma_f32 v131, -v230, v231, 1.0
	v_fmac_f32_e32 v231, v131, v231
	v_mul_f32_e32 v233, v232, v231
	v_fma_f32 v131, -v230, v233, v232
	v_fmac_f32_e32 v233, v131, v231
	v_fma_f32 v230, -v230, v233, v232
	v_div_fmas_f32 v230, v230, v231, v233
	v_div_fixup_f32 v135, v230, v229, 2.0
	v_sub_f32_e32 v135, 1.0, v135
	v_add_f32_e32 v228, v39, v39
	v_mul_f32_e32 v228, 0x3fb8aa3b, v228
	v_exp_f32_e32 v228, v228
	s_nop 0
	v_add_f32_e32 v229, 1.0, v228
	v_div_scale_f32 v230, s[4:5], v229, v229, 2.0
	v_rcp_f32_e32 v231, v230
	v_div_scale_f32 v232, vcc, 2.0, v229, 2.0
	v_fma_f32 v131, -v230, v231, 1.0
	v_fmac_f32_e32 v231, v131, v231
	v_mul_f32_e32 v233, v232, v231
	v_fma_f32 v131, -v230, v233, v232
	v_fmac_f32_e32 v233, v131, v231
	v_fma_f32 v230, -v230, v233, v232
	v_div_fmas_f32 v230, v230, v231, v233
	v_div_fixup_f32 v133, v230, v229, 2.0
	v_sub_f32_e32 v133, 1.0, v133
	v_cvt_pk_bf16_f32 v133, v135, v133
	global_store_dword v[226:227], v133, off
	v_add_f32_e32 v228, v43, v43
	v_mul_f32_e32 v228, 0x3fb8aa3b, v228
	v_exp_f32_e32 v228, v228
	s_nop 0
	v_add_f32_e32 v229, 1.0, v228
	v_div_scale_f32 v230, s[4:5], v229, v229, 2.0
	v_rcp_f32_e32 v231, v230
	v_div_scale_f32 v232, vcc, 2.0, v229, 2.0
	v_fma_f32 v131, -v230, v231, 1.0
	v_fmac_f32_e32 v231, v131, v231
	v_mul_f32_e32 v233, v232, v231
	v_fma_f32 v131, -v230, v233, v232
	v_fmac_f32_e32 v233, v131, v231
	v_fma_f32 v230, -v230, v233, v232
	v_div_fmas_f32 v230, v230, v231, v233
	v_div_fixup_f32 v135, v230, v229, 2.0
	v_sub_f32_e32 v135, 1.0, v135
	v_add_f32_e32 v228, v47, v47
	v_mul_f32_e32 v228, 0x3fb8aa3b, v228
	v_exp_f32_e32 v228, v228
	s_nop 0
	v_add_f32_e32 v229, 1.0, v228
	v_div_scale_f32 v230, s[4:5], v229, v229, 2.0
	v_rcp_f32_e32 v231, v230
	v_div_scale_f32 v232, vcc, 2.0, v229, 2.0
	v_fma_f32 v131, -v230, v231, 1.0
	v_fmac_f32_e32 v231, v131, v231
	v_mul_f32_e32 v233, v232, v231
	v_fma_f32 v131, -v230, v233, v232
	v_fmac_f32_e32 v233, v131, v231
	v_fma_f32 v230, -v230, v233, v232
	v_div_fmas_f32 v230, v230, v231, v233
	v_div_fixup_f32 v133, v230, v229, 2.0
	v_sub_f32_e32 v133, 1.0, v133
	v_cvt_pk_bf16_f32 v133, v135, v133
	global_store_dword v[226:227], v133, off offset:64
	s_mov_b64 s[4:5], 0x2700
	v_lshl_add_u64 v[226:227], v[226:227], 0, s[4:5]
	v_add_f32_e32 v228, v48, v48
	v_mul_f32_e32 v228, 0x3fb8aa3b, v228
	v_exp_f32_e32 v228, v228
	s_nop 0
	v_add_f32_e32 v229, 1.0, v228
	v_div_scale_f32 v230, s[4:5], v229, v229, 2.0
	v_rcp_f32_e32 v231, v230
	v_div_scale_f32 v232, vcc, 2.0, v229, 2.0
	v_fma_f32 v131, -v230, v231, 1.0
	v_fmac_f32_e32 v231, v131, v231
	v_mul_f32_e32 v233, v232, v231
	v_fma_f32 v131, -v230, v233, v232
	v_fmac_f32_e32 v233, v131, v231
	v_fma_f32 v230, -v230, v233, v232
	v_div_fmas_f32 v230, v230, v231, v233
	v_div_fixup_f32 v135, v230, v229, 2.0
	v_sub_f32_e32 v135, 1.0, v135
	v_add_f32_e32 v228, v52, v52
	v_mul_f32_e32 v228, 0x3fb8aa3b, v228
	v_exp_f32_e32 v228, v228
	s_nop 0
	v_add_f32_e32 v229, 1.0, v228
	v_div_scale_f32 v230, s[4:5], v229, v229, 2.0
	v_rcp_f32_e32 v231, v230
	v_div_scale_f32 v232, vcc, 2.0, v229, 2.0
	v_fma_f32 v131, -v230, v231, 1.0
	v_fmac_f32_e32 v231, v131, v231
	v_mul_f32_e32 v233, v232, v231
	v_fma_f32 v131, -v230, v233, v232
	v_fmac_f32_e32 v233, v131, v231
	v_fma_f32 v230, -v230, v233, v232
	v_div_fmas_f32 v230, v230, v231, v233
	v_div_fixup_f32 v133, v230, v229, 2.0
	v_sub_f32_e32 v133, 1.0, v133
	v_cvt_pk_bf16_f32 v133, v135, v133
	global_store_dword v[226:227], v133, off
	v_add_f32_e32 v228, v56, v56
	v_mul_f32_e32 v228, 0x3fb8aa3b, v228
	v_exp_f32_e32 v228, v228
	s_nop 0
	v_add_f32_e32 v229, 1.0, v228
	v_div_scale_f32 v230, s[4:5], v229, v229, 2.0
	v_rcp_f32_e32 v231, v230
	v_div_scale_f32 v232, vcc, 2.0, v229, 2.0
	v_fma_f32 v131, -v230, v231, 1.0
	v_fmac_f32_e32 v231, v131, v231
	v_mul_f32_e32 v233, v232, v231
	v_fma_f32 v131, -v230, v233, v232
	v_fmac_f32_e32 v233, v131, v231
	v_fma_f32 v230, -v230, v233, v232
	v_div_fmas_f32 v230, v230, v231, v233
	v_div_fixup_f32 v135, v230, v229, 2.0
	v_sub_f32_e32 v135, 1.0, v135
	v_add_f32_e32 v228, v60, v60
	v_mul_f32_e32 v228, 0x3fb8aa3b, v228
	v_exp_f32_e32 v228, v228
	s_nop 0
	v_add_f32_e32 v229, 1.0, v228
	v_div_scale_f32 v230, s[4:5], v229, v229, 2.0
	v_rcp_f32_e32 v231, v230
	v_div_scale_f32 v232, vcc, 2.0, v229, 2.0
	v_fma_f32 v131, -v230, v231, 1.0
	v_fmac_f32_e32 v231, v131, v231
	v_mul_f32_e32 v233, v232, v231
	v_fma_f32 v131, -v230, v233, v232
	v_fmac_f32_e32 v233, v131, v231
	v_fma_f32 v230, -v230, v233, v232
	v_div_fmas_f32 v230, v230, v231, v233
	v_div_fixup_f32 v133, v230, v229, 2.0
	v_sub_f32_e32 v133, 1.0, v133
	v_cvt_pk_bf16_f32 v133, v135, v133
	global_store_dword v[226:227], v133, off offset:64
	s_mov_b64 s[4:5], 0x300
	v_lshl_add_u64 v[226:227], v[226:227], 0, s[4:5]
	v_add_f32_e32 v228, v49, v49
	v_mul_f32_e32 v228, 0x3fb8aa3b, v228
	v_exp_f32_e32 v228, v228
	s_nop 0
	v_add_f32_e32 v229, 1.0, v228
	v_div_scale_f32 v230, s[4:5], v229, v229, 2.0
	v_rcp_f32_e32 v231, v230
	v_div_scale_f32 v232, vcc, 2.0, v229, 2.0
	v_fma_f32 v131, -v230, v231, 1.0
	v_fmac_f32_e32 v231, v131, v231
	v_mul_f32_e32 v233, v232, v231
	v_fma_f32 v131, -v230, v233, v232
	v_fmac_f32_e32 v233, v131, v231
	v_fma_f32 v230, -v230, v233, v232
	v_div_fmas_f32 v230, v230, v231, v233
	v_div_fixup_f32 v135, v230, v229, 2.0
	v_sub_f32_e32 v135, 1.0, v135
	v_add_f32_e32 v228, v53, v53
	v_mul_f32_e32 v228, 0x3fb8aa3b, v228
	v_exp_f32_e32 v228, v228
	s_nop 0
	v_add_f32_e32 v229, 1.0, v228
	v_div_scale_f32 v230, s[4:5], v229, v229, 2.0
	v_rcp_f32_e32 v231, v230
	v_div_scale_f32 v232, vcc, 2.0, v229, 2.0
	v_fma_f32 v131, -v230, v231, 1.0
	v_fmac_f32_e32 v231, v131, v231
	v_mul_f32_e32 v233, v232, v231
	v_fma_f32 v131, -v230, v233, v232
	v_fmac_f32_e32 v233, v131, v231
	v_fma_f32 v230, -v230, v233, v232
	v_div_fmas_f32 v230, v230, v231, v233
	v_div_fixup_f32 v133, v230, v229, 2.0
	v_sub_f32_e32 v133, 1.0, v133
	v_cvt_pk_bf16_f32 v133, v135, v133
	global_store_dword v[226:227], v133, off
	v_add_f32_e32 v228, v57, v57
	v_mul_f32_e32 v228, 0x3fb8aa3b, v228
	v_exp_f32_e32 v228, v228
	s_nop 0
	v_add_f32_e32 v229, 1.0, v228
	v_div_scale_f32 v230, s[4:5], v229, v229, 2.0
	v_rcp_f32_e32 v231, v230
	v_div_scale_f32 v232, vcc, 2.0, v229, 2.0
	v_fma_f32 v131, -v230, v231, 1.0
	v_fmac_f32_e32 v231, v131, v231
	v_mul_f32_e32 v233, v232, v231
	v_fma_f32 v131, -v230, v233, v232
	v_fmac_f32_e32 v233, v131, v231
	v_fma_f32 v230, -v230, v233, v232
	v_div_fmas_f32 v230, v230, v231, v233
	v_div_fixup_f32 v135, v230, v229, 2.0
	v_sub_f32_e32 v135, 1.0, v135
	v_add_f32_e32 v228, v61, v61
	v_mul_f32_e32 v228, 0x3fb8aa3b, v228
	v_exp_f32_e32 v228, v228
	s_nop 0
	v_add_f32_e32 v229, 1.0, v228
	v_div_scale_f32 v230, s[4:5], v229, v229, 2.0
	v_rcp_f32_e32 v231, v230
	v_div_scale_f32 v232, vcc, 2.0, v229, 2.0
	v_fma_f32 v131, -v230, v231, 1.0
	v_fmac_f32_e32 v231, v131, v231
	v_mul_f32_e32 v233, v232, v231
	v_fma_f32 v131, -v230, v233, v232
	v_fmac_f32_e32 v233, v131, v231
	v_fma_f32 v230, -v230, v233, v232
	v_div_fmas_f32 v230, v230, v231, v233
	v_div_fixup_f32 v133, v230, v229, 2.0
	v_sub_f32_e32 v133, 1.0, v133
	v_cvt_pk_bf16_f32 v133, v135, v133
	global_store_dword v[226:227], v133, off offset:64
	s_mov_b64 s[4:5], 0x300
	v_lshl_add_u64 v[226:227], v[226:227], 0, s[4:5]
	v_add_f32_e32 v228, v50, v50
	v_mul_f32_e32 v228, 0x3fb8aa3b, v228
	v_exp_f32_e32 v228, v228
	s_nop 0
	v_add_f32_e32 v229, 1.0, v228
	v_div_scale_f32 v230, s[4:5], v229, v229, 2.0
	v_rcp_f32_e32 v231, v230
	v_div_scale_f32 v232, vcc, 2.0, v229, 2.0
	v_fma_f32 v131, -v230, v231, 1.0
	v_fmac_f32_e32 v231, v131, v231
	v_mul_f32_e32 v233, v232, v231
	v_fma_f32 v131, -v230, v233, v232
	v_fmac_f32_e32 v233, v131, v231
	v_fma_f32 v230, -v230, v233, v232
	v_div_fmas_f32 v230, v230, v231, v233
	v_div_fixup_f32 v135, v230, v229, 2.0
	v_sub_f32_e32 v135, 1.0, v135
	v_add_f32_e32 v228, v54, v54
	v_mul_f32_e32 v228, 0x3fb8aa3b, v228
	v_exp_f32_e32 v228, v228
	s_nop 0
	v_add_f32_e32 v229, 1.0, v228
	v_div_scale_f32 v230, s[4:5], v229, v229, 2.0
	v_rcp_f32_e32 v231, v230
	v_div_scale_f32 v232, vcc, 2.0, v229, 2.0
	v_fma_f32 v131, -v230, v231, 1.0
	v_fmac_f32_e32 v231, v131, v231
	v_mul_f32_e32 v233, v232, v231
	v_fma_f32 v131, -v230, v233, v232
	v_fmac_f32_e32 v233, v131, v231
	v_fma_f32 v230, -v230, v233, v232
	v_div_fmas_f32 v230, v230, v231, v233
	v_div_fixup_f32 v133, v230, v229, 2.0
	v_sub_f32_e32 v133, 1.0, v133
	v_cvt_pk_bf16_f32 v133, v135, v133
	global_store_dword v[226:227], v133, off
	v_add_f32_e32 v228, v58, v58
	v_mul_f32_e32 v228, 0x3fb8aa3b, v228
	v_exp_f32_e32 v228, v228
	s_nop 0
	v_add_f32_e32 v229, 1.0, v228
	v_div_scale_f32 v230, s[4:5], v229, v229, 2.0
	v_rcp_f32_e32 v231, v230
	v_div_scale_f32 v232, vcc, 2.0, v229, 2.0
	v_fma_f32 v131, -v230, v231, 1.0
	v_fmac_f32_e32 v231, v131, v231
	v_mul_f32_e32 v233, v232, v231
	v_fma_f32 v131, -v230, v233, v232
	v_fmac_f32_e32 v233, v131, v231
	v_fma_f32 v230, -v230, v233, v232
	v_div_fmas_f32 v230, v230, v231, v233
	v_div_fixup_f32 v135, v230, v229, 2.0
	v_sub_f32_e32 v135, 1.0, v135
	v_add_f32_e32 v228, v62, v62
	v_mul_f32_e32 v228, 0x3fb8aa3b, v228
	v_exp_f32_e32 v228, v228
	s_nop 0
	v_add_f32_e32 v229, 1.0, v228
	v_div_scale_f32 v230, s[4:5], v229, v229, 2.0
	v_rcp_f32_e32 v231, v230
	v_div_scale_f32 v232, vcc, 2.0, v229, 2.0
	v_fma_f32 v131, -v230, v231, 1.0
	v_fmac_f32_e32 v231, v131, v231
	v_mul_f32_e32 v233, v232, v231
	v_fma_f32 v131, -v230, v233, v232
	v_fmac_f32_e32 v233, v131, v231
	v_fma_f32 v230, -v230, v233, v232
	v_div_fmas_f32 v230, v230, v231, v233
	v_div_fixup_f32 v133, v230, v229, 2.0
	v_sub_f32_e32 v133, 1.0, v133
	v_cvt_pk_bf16_f32 v133, v135, v133
	global_store_dword v[226:227], v133, off offset:64
	s_mov_b64 s[4:5], 0x300
	v_lshl_add_u64 v[226:227], v[226:227], 0, s[4:5]
	v_add_f32_e32 v228, v51, v51
	v_mul_f32_e32 v228, 0x3fb8aa3b, v228
	v_exp_f32_e32 v228, v228
	s_nop 0
	v_add_f32_e32 v229, 1.0, v228
	v_div_scale_f32 v230, s[4:5], v229, v229, 2.0
	v_rcp_f32_e32 v231, v230
	v_div_scale_f32 v232, vcc, 2.0, v229, 2.0
	v_fma_f32 v131, -v230, v231, 1.0
	v_fmac_f32_e32 v231, v131, v231
	v_mul_f32_e32 v233, v232, v231
	v_fma_f32 v131, -v230, v233, v232
	v_fmac_f32_e32 v233, v131, v231
	v_fma_f32 v230, -v230, v233, v232
	v_div_fmas_f32 v230, v230, v231, v233
	v_div_fixup_f32 v135, v230, v229, 2.0
	v_sub_f32_e32 v135, 1.0, v135
	v_add_f32_e32 v228, v55, v55
	v_mul_f32_e32 v228, 0x3fb8aa3b, v228
	v_exp_f32_e32 v228, v228
	s_nop 0
	v_add_f32_e32 v229, 1.0, v228
	v_div_scale_f32 v230, s[4:5], v229, v229, 2.0
	v_rcp_f32_e32 v231, v230
	v_div_scale_f32 v232, vcc, 2.0, v229, 2.0
	v_fma_f32 v131, -v230, v231, 1.0
	v_fmac_f32_e32 v231, v131, v231
	v_mul_f32_e32 v233, v232, v231
	v_fma_f32 v131, -v230, v233, v232
	v_fmac_f32_e32 v233, v131, v231
	v_fma_f32 v230, -v230, v233, v232
	v_div_fmas_f32 v230, v230, v231, v233
	v_div_fixup_f32 v133, v230, v229, 2.0
	v_sub_f32_e32 v133, 1.0, v133
	v_cvt_pk_bf16_f32 v133, v135, v133
	global_store_dword v[226:227], v133, off
	v_add_f32_e32 v228, v59, v59
	v_mul_f32_e32 v228, 0x3fb8aa3b, v228
	v_exp_f32_e32 v228, v228
	s_nop 0
	v_add_f32_e32 v229, 1.0, v228
	v_div_scale_f32 v230, s[4:5], v229, v229, 2.0
	v_rcp_f32_e32 v231, v230
	v_div_scale_f32 v232, vcc, 2.0, v229, 2.0
	v_fma_f32 v131, -v230, v231, 1.0
	v_fmac_f32_e32 v231, v131, v231
	v_mul_f32_e32 v233, v232, v231
	v_fma_f32 v131, -v230, v233, v232
	v_fmac_f32_e32 v233, v131, v231
	v_fma_f32 v230, -v230, v233, v232
	v_div_fmas_f32 v230, v230, v231, v233
	v_div_fixup_f32 v135, v230, v229, 2.0
	v_sub_f32_e32 v135, 1.0, v135
	v_add_f32_e32 v228, v63, v63
	v_mul_f32_e32 v228, 0x3fb8aa3b, v228
	v_exp_f32_e32 v228, v228
	s_nop 0
	v_add_f32_e32 v229, 1.0, v228
	v_div_scale_f32 v230, s[4:5], v229, v229, 2.0
	v_rcp_f32_e32 v231, v230
	v_div_scale_f32 v232, vcc, 2.0, v229, 2.0
	v_fma_f32 v131, -v230, v231, 1.0
	v_fmac_f32_e32 v231, v131, v231
	v_mul_f32_e32 v233, v232, v231
	v_fma_f32 v131, -v230, v233, v232
	v_fmac_f32_e32 v233, v131, v231
	v_fma_f32 v230, -v230, v233, v232
	v_div_fmas_f32 v230, v230, v231, v233
	v_div_fixup_f32 v133, v230, v229, 2.0
	v_sub_f32_e32 v133, 1.0, v133
	v_cvt_pk_bf16_f32 v133, v135, v133
	global_store_dword v[226:227], v133, off offset:64
	s_mov_b64 s[4:5], 0x2700
	v_lshl_add_u64 v[226:227], v[226:227], 0, s[4:5]
	v_add_f32_e32 v228, v64, v64
	v_mul_f32_e32 v228, 0x3fb8aa3b, v228
	v_exp_f32_e32 v228, v228
	s_nop 0
	v_add_f32_e32 v229, 1.0, v228
	v_div_scale_f32 v230, s[4:5], v229, v229, 2.0
	v_rcp_f32_e32 v231, v230
	v_div_scale_f32 v232, vcc, 2.0, v229, 2.0
	v_fma_f32 v131, -v230, v231, 1.0
	v_fmac_f32_e32 v231, v131, v231
	v_mul_f32_e32 v233, v232, v231
	v_fma_f32 v131, -v230, v233, v232
	v_fmac_f32_e32 v233, v131, v231
	v_fma_f32 v230, -v230, v233, v232
	v_div_fmas_f32 v230, v230, v231, v233
	v_div_fixup_f32 v135, v230, v229, 2.0
	v_sub_f32_e32 v135, 1.0, v135
	v_add_f32_e32 v228, v68, v68
	v_mul_f32_e32 v228, 0x3fb8aa3b, v228
	v_exp_f32_e32 v228, v228
	s_nop 0
	v_add_f32_e32 v229, 1.0, v228
	v_div_scale_f32 v230, s[4:5], v229, v229, 2.0
	v_rcp_f32_e32 v231, v230
	v_div_scale_f32 v232, vcc, 2.0, v229, 2.0
	v_fma_f32 v131, -v230, v231, 1.0
	v_fmac_f32_e32 v231, v131, v231
	v_mul_f32_e32 v233, v232, v231
	v_fma_f32 v131, -v230, v233, v232
	v_fmac_f32_e32 v233, v131, v231
	v_fma_f32 v230, -v230, v233, v232
	v_div_fmas_f32 v230, v230, v231, v233
	v_div_fixup_f32 v133, v230, v229, 2.0
	v_sub_f32_e32 v133, 1.0, v133
	v_cvt_pk_bf16_f32 v133, v135, v133
	global_store_dword v[226:227], v133, off
	v_add_f32_e32 v228, v72, v72
	v_mul_f32_e32 v228, 0x3fb8aa3b, v228
	v_exp_f32_e32 v228, v228
	s_nop 0
	v_add_f32_e32 v229, 1.0, v228
	v_div_scale_f32 v230, s[4:5], v229, v229, 2.0
	v_rcp_f32_e32 v231, v230
	v_div_scale_f32 v232, vcc, 2.0, v229, 2.0
	v_fma_f32 v131, -v230, v231, 1.0
	v_fmac_f32_e32 v231, v131, v231
	v_mul_f32_e32 v233, v232, v231
	v_fma_f32 v131, -v230, v233, v232
	v_fmac_f32_e32 v233, v131, v231
	v_fma_f32 v230, -v230, v233, v232
	v_div_fmas_f32 v230, v230, v231, v233
	v_div_fixup_f32 v135, v230, v229, 2.0
	v_sub_f32_e32 v135, 1.0, v135
	v_add_f32_e32 v228, v76, v76
	v_mul_f32_e32 v228, 0x3fb8aa3b, v228
	v_exp_f32_e32 v228, v228
	s_nop 0
	v_add_f32_e32 v229, 1.0, v228
	v_div_scale_f32 v230, s[4:5], v229, v229, 2.0
	v_rcp_f32_e32 v231, v230
	v_div_scale_f32 v232, vcc, 2.0, v229, 2.0
	v_fma_f32 v131, -v230, v231, 1.0
	v_fmac_f32_e32 v231, v131, v231
	v_mul_f32_e32 v233, v232, v231
	v_fma_f32 v131, -v230, v233, v232
	v_fmac_f32_e32 v233, v131, v231
	v_fma_f32 v230, -v230, v233, v232
	v_div_fmas_f32 v230, v230, v231, v233
	v_div_fixup_f32 v133, v230, v229, 2.0
	v_sub_f32_e32 v133, 1.0, v133
	v_cvt_pk_bf16_f32 v133, v135, v133
	global_store_dword v[226:227], v133, off offset:64
	s_mov_b64 s[4:5], 0x300
	v_lshl_add_u64 v[226:227], v[226:227], 0, s[4:5]
	v_add_f32_e32 v228, v65, v65
	v_mul_f32_e32 v228, 0x3fb8aa3b, v228
	v_exp_f32_e32 v228, v228
	s_nop 0
	v_add_f32_e32 v229, 1.0, v228
	v_div_scale_f32 v230, s[4:5], v229, v229, 2.0
	v_rcp_f32_e32 v231, v230
	v_div_scale_f32 v232, vcc, 2.0, v229, 2.0
	v_fma_f32 v131, -v230, v231, 1.0
	v_fmac_f32_e32 v231, v131, v231
	v_mul_f32_e32 v233, v232, v231
	v_fma_f32 v131, -v230, v233, v232
	v_fmac_f32_e32 v233, v131, v231
	v_fma_f32 v230, -v230, v233, v232
	v_div_fmas_f32 v230, v230, v231, v233
	v_div_fixup_f32 v135, v230, v229, 2.0
	v_sub_f32_e32 v135, 1.0, v135
	v_add_f32_e32 v228, v69, v69
	v_mul_f32_e32 v228, 0x3fb8aa3b, v228
	v_exp_f32_e32 v228, v228
	s_nop 0
	v_add_f32_e32 v229, 1.0, v228
	v_div_scale_f32 v230, s[4:5], v229, v229, 2.0
	v_rcp_f32_e32 v231, v230
	v_div_scale_f32 v232, vcc, 2.0, v229, 2.0
	v_fma_f32 v131, -v230, v231, 1.0
	v_fmac_f32_e32 v231, v131, v231
	v_mul_f32_e32 v233, v232, v231
	v_fma_f32 v131, -v230, v233, v232
	v_fmac_f32_e32 v233, v131, v231
	v_fma_f32 v230, -v230, v233, v232
	v_div_fmas_f32 v230, v230, v231, v233
	v_div_fixup_f32 v133, v230, v229, 2.0
	v_sub_f32_e32 v133, 1.0, v133
	v_cvt_pk_bf16_f32 v133, v135, v133
	global_store_dword v[226:227], v133, off
	v_add_f32_e32 v228, v73, v73
	v_mul_f32_e32 v228, 0x3fb8aa3b, v228
	v_exp_f32_e32 v228, v228
	s_nop 0
	v_add_f32_e32 v229, 1.0, v228
	v_div_scale_f32 v230, s[4:5], v229, v229, 2.0
	v_rcp_f32_e32 v231, v230
	v_div_scale_f32 v232, vcc, 2.0, v229, 2.0
	v_fma_f32 v131, -v230, v231, 1.0
	v_fmac_f32_e32 v231, v131, v231
	v_mul_f32_e32 v233, v232, v231
	v_fma_f32 v131, -v230, v233, v232
	v_fmac_f32_e32 v233, v131, v231
	v_fma_f32 v230, -v230, v233, v232
	v_div_fmas_f32 v230, v230, v231, v233
	v_div_fixup_f32 v135, v230, v229, 2.0
	v_sub_f32_e32 v135, 1.0, v135
	v_add_f32_e32 v228, v77, v77
	v_mul_f32_e32 v228, 0x3fb8aa3b, v228
	v_exp_f32_e32 v228, v228
	s_nop 0
	v_add_f32_e32 v229, 1.0, v228
	v_div_scale_f32 v230, s[4:5], v229, v229, 2.0
	v_rcp_f32_e32 v231, v230
	v_div_scale_f32 v232, vcc, 2.0, v229, 2.0
	v_fma_f32 v131, -v230, v231, 1.0
	v_fmac_f32_e32 v231, v131, v231
	v_mul_f32_e32 v233, v232, v231
	v_fma_f32 v131, -v230, v233, v232
	v_fmac_f32_e32 v233, v131, v231
	v_fma_f32 v230, -v230, v233, v232
	v_div_fmas_f32 v230, v230, v231, v233
	v_div_fixup_f32 v133, v230, v229, 2.0
	v_sub_f32_e32 v133, 1.0, v133
	v_cvt_pk_bf16_f32 v133, v135, v133
	global_store_dword v[226:227], v133, off offset:64
	s_mov_b64 s[4:5], 0x300
	v_lshl_add_u64 v[226:227], v[226:227], 0, s[4:5]
	v_add_f32_e32 v228, v66, v66
	v_mul_f32_e32 v228, 0x3fb8aa3b, v228
	v_exp_f32_e32 v228, v228
	s_nop 0
	v_add_f32_e32 v229, 1.0, v228
	v_div_scale_f32 v230, s[4:5], v229, v229, 2.0
	v_rcp_f32_e32 v231, v230
	v_div_scale_f32 v232, vcc, 2.0, v229, 2.0
	v_fma_f32 v131, -v230, v231, 1.0
	v_fmac_f32_e32 v231, v131, v231
	v_mul_f32_e32 v233, v232, v231
	v_fma_f32 v131, -v230, v233, v232
	v_fmac_f32_e32 v233, v131, v231
	v_fma_f32 v230, -v230, v233, v232
	v_div_fmas_f32 v230, v230, v231, v233
	v_div_fixup_f32 v135, v230, v229, 2.0
	v_sub_f32_e32 v135, 1.0, v135
	v_add_f32_e32 v228, v70, v70
	v_mul_f32_e32 v228, 0x3fb8aa3b, v228
	v_exp_f32_e32 v228, v228
	s_nop 0
	v_add_f32_e32 v229, 1.0, v228
	v_div_scale_f32 v230, s[4:5], v229, v229, 2.0
	v_rcp_f32_e32 v231, v230
	v_div_scale_f32 v232, vcc, 2.0, v229, 2.0
	v_fma_f32 v131, -v230, v231, 1.0
	v_fmac_f32_e32 v231, v131, v231
	v_mul_f32_e32 v233, v232, v231
	v_fma_f32 v131, -v230, v233, v232
	v_fmac_f32_e32 v233, v131, v231
	v_fma_f32 v230, -v230, v233, v232
	v_div_fmas_f32 v230, v230, v231, v233
	v_div_fixup_f32 v133, v230, v229, 2.0
	v_sub_f32_e32 v133, 1.0, v133
	v_cvt_pk_bf16_f32 v133, v135, v133
	global_store_dword v[226:227], v133, off
	v_add_f32_e32 v228, v74, v74
	v_mul_f32_e32 v228, 0x3fb8aa3b, v228
	v_exp_f32_e32 v228, v228
	s_nop 0
	v_add_f32_e32 v229, 1.0, v228
	v_div_scale_f32 v230, s[4:5], v229, v229, 2.0
	v_rcp_f32_e32 v231, v230
	v_div_scale_f32 v232, vcc, 2.0, v229, 2.0
	v_fma_f32 v131, -v230, v231, 1.0
	v_fmac_f32_e32 v231, v131, v231
	v_mul_f32_e32 v233, v232, v231
	v_fma_f32 v131, -v230, v233, v232
	v_fmac_f32_e32 v233, v131, v231
	v_fma_f32 v230, -v230, v233, v232
	v_div_fmas_f32 v230, v230, v231, v233
	v_div_fixup_f32 v135, v230, v229, 2.0
	v_sub_f32_e32 v135, 1.0, v135
	v_add_f32_e32 v228, v78, v78
	v_mul_f32_e32 v228, 0x3fb8aa3b, v228
	v_exp_f32_e32 v228, v228
	s_nop 0
	v_add_f32_e32 v229, 1.0, v228
	v_div_scale_f32 v230, s[4:5], v229, v229, 2.0
	v_rcp_f32_e32 v231, v230
	v_div_scale_f32 v232, vcc, 2.0, v229, 2.0
	v_fma_f32 v131, -v230, v231, 1.0
	v_fmac_f32_e32 v231, v131, v231
	v_mul_f32_e32 v233, v232, v231
	v_fma_f32 v131, -v230, v233, v232
	v_fmac_f32_e32 v233, v131, v231
	v_fma_f32 v230, -v230, v233, v232
	v_div_fmas_f32 v230, v230, v231, v233
	v_div_fixup_f32 v133, v230, v229, 2.0
	v_sub_f32_e32 v133, 1.0, v133
	v_cvt_pk_bf16_f32 v133, v135, v133
	global_store_dword v[226:227], v133, off offset:64
	s_mov_b64 s[4:5], 0x300
	v_lshl_add_u64 v[226:227], v[226:227], 0, s[4:5]
	v_add_f32_e32 v228, v67, v67
	v_mul_f32_e32 v228, 0x3fb8aa3b, v228
	v_exp_f32_e32 v228, v228
	s_nop 0
	v_add_f32_e32 v229, 1.0, v228
	v_div_scale_f32 v230, s[4:5], v229, v229, 2.0
	v_rcp_f32_e32 v231, v230
	v_div_scale_f32 v232, vcc, 2.0, v229, 2.0
	v_fma_f32 v131, -v230, v231, 1.0
	v_fmac_f32_e32 v231, v131, v231
	v_mul_f32_e32 v233, v232, v231
	v_fma_f32 v131, -v230, v233, v232
	v_fmac_f32_e32 v233, v131, v231
	v_fma_f32 v230, -v230, v233, v232
	v_div_fmas_f32 v230, v230, v231, v233
	v_div_fixup_f32 v135, v230, v229, 2.0
	v_sub_f32_e32 v135, 1.0, v135
	v_add_f32_e32 v228, v71, v71
	v_mul_f32_e32 v228, 0x3fb8aa3b, v228
	v_exp_f32_e32 v228, v228
	s_nop 0
	v_add_f32_e32 v229, 1.0, v228
	v_div_scale_f32 v230, s[4:5], v229, v229, 2.0
	v_rcp_f32_e32 v231, v230
	v_div_scale_f32 v232, vcc, 2.0, v229, 2.0
	v_fma_f32 v131, -v230, v231, 1.0
	v_fmac_f32_e32 v231, v131, v231
	v_mul_f32_e32 v233, v232, v231
	v_fma_f32 v131, -v230, v233, v232
	v_fmac_f32_e32 v233, v131, v231
	v_fma_f32 v230, -v230, v233, v232
	v_div_fmas_f32 v230, v230, v231, v233
	v_div_fixup_f32 v133, v230, v229, 2.0
	v_sub_f32_e32 v133, 1.0, v133
	v_cvt_pk_bf16_f32 v133, v135, v133
	global_store_dword v[226:227], v133, off
	v_add_f32_e32 v228, v75, v75
	v_mul_f32_e32 v228, 0x3fb8aa3b, v228
	v_exp_f32_e32 v228, v228
	s_nop 0
	v_add_f32_e32 v229, 1.0, v228
	v_div_scale_f32 v230, s[4:5], v229, v229, 2.0
	v_rcp_f32_e32 v231, v230
	v_div_scale_f32 v232, vcc, 2.0, v229, 2.0
	v_fma_f32 v131, -v230, v231, 1.0
	v_fmac_f32_e32 v231, v131, v231
	v_mul_f32_e32 v233, v232, v231
	v_fma_f32 v131, -v230, v233, v232
	v_fmac_f32_e32 v233, v131, v231
	v_fma_f32 v230, -v230, v233, v232
	v_div_fmas_f32 v230, v230, v231, v233
	v_div_fixup_f32 v135, v230, v229, 2.0
	v_sub_f32_e32 v135, 1.0, v135
	v_add_f32_e32 v228, v79, v79
	v_mul_f32_e32 v228, 0x3fb8aa3b, v228
	v_exp_f32_e32 v228, v228
	s_nop 0
	v_add_f32_e32 v229, 1.0, v228
	v_div_scale_f32 v230, s[4:5], v229, v229, 2.0
	v_rcp_f32_e32 v231, v230
	v_div_scale_f32 v232, vcc, 2.0, v229, 2.0
	v_fma_f32 v131, -v230, v231, 1.0
	v_fmac_f32_e32 v231, v131, v231
	v_mul_f32_e32 v233, v232, v231
	v_fma_f32 v131, -v230, v233, v232
	v_fmac_f32_e32 v233, v131, v231
	v_fma_f32 v230, -v230, v233, v232
	v_div_fmas_f32 v230, v230, v231, v233
	v_div_fixup_f32 v133, v230, v229, 2.0
	v_sub_f32_e32 v133, 1.0, v133
	v_cvt_pk_bf16_f32 v133, v135, v133
	global_store_dword v[226:227], v133, off offset:64
	s_mov_b64 s[4:5], 0x2700
	v_lshl_add_u64 v[226:227], v[226:227], 0, s[4:5]
	v_add_f32_e32 v228, v80, v80
	v_mul_f32_e32 v228, 0x3fb8aa3b, v228
	v_exp_f32_e32 v228, v228
	s_nop 0
	v_add_f32_e32 v229, 1.0, v228
	v_div_scale_f32 v230, s[4:5], v229, v229, 2.0
	v_rcp_f32_e32 v231, v230
	v_div_scale_f32 v232, vcc, 2.0, v229, 2.0
	v_fma_f32 v131, -v230, v231, 1.0
	v_fmac_f32_e32 v231, v131, v231
	v_mul_f32_e32 v233, v232, v231
	v_fma_f32 v131, -v230, v233, v232
	v_fmac_f32_e32 v233, v131, v231
	v_fma_f32 v230, -v230, v233, v232
	v_div_fmas_f32 v230, v230, v231, v233
	v_div_fixup_f32 v135, v230, v229, 2.0
	v_sub_f32_e32 v135, 1.0, v135
	v_add_f32_e32 v228, v84, v84
	v_mul_f32_e32 v228, 0x3fb8aa3b, v228
	v_exp_f32_e32 v228, v228
	s_nop 0
	v_add_f32_e32 v229, 1.0, v228
	v_div_scale_f32 v230, s[4:5], v229, v229, 2.0
	v_rcp_f32_e32 v231, v230
	v_div_scale_f32 v232, vcc, 2.0, v229, 2.0
	v_fma_f32 v131, -v230, v231, 1.0
	v_fmac_f32_e32 v231, v131, v231
	v_mul_f32_e32 v233, v232, v231
	v_fma_f32 v131, -v230, v233, v232
	v_fmac_f32_e32 v233, v131, v231
	v_fma_f32 v230, -v230, v233, v232
	v_div_fmas_f32 v230, v230, v231, v233
	v_div_fixup_f32 v133, v230, v229, 2.0
	v_sub_f32_e32 v133, 1.0, v133
	v_cvt_pk_bf16_f32 v133, v135, v133
	global_store_dword v[226:227], v133, off
	v_add_f32_e32 v228, v88, v88
	v_mul_f32_e32 v228, 0x3fb8aa3b, v228
	v_exp_f32_e32 v228, v228
	s_nop 0
	v_add_f32_e32 v229, 1.0, v228
	v_div_scale_f32 v230, s[4:5], v229, v229, 2.0
	v_rcp_f32_e32 v231, v230
	v_div_scale_f32 v232, vcc, 2.0, v229, 2.0
	v_fma_f32 v131, -v230, v231, 1.0
	v_fmac_f32_e32 v231, v131, v231
	v_mul_f32_e32 v233, v232, v231
	v_fma_f32 v131, -v230, v233, v232
	v_fmac_f32_e32 v233, v131, v231
	v_fma_f32 v230, -v230, v233, v232
	v_div_fmas_f32 v230, v230, v231, v233
	v_div_fixup_f32 v135, v230, v229, 2.0
	v_sub_f32_e32 v135, 1.0, v135
	v_add_f32_e32 v228, v92, v92
	v_mul_f32_e32 v228, 0x3fb8aa3b, v228
	v_exp_f32_e32 v228, v228
	s_nop 0
	v_add_f32_e32 v229, 1.0, v228
	v_div_scale_f32 v230, s[4:5], v229, v229, 2.0
	v_rcp_f32_e32 v231, v230
	v_div_scale_f32 v232, vcc, 2.0, v229, 2.0
	v_fma_f32 v131, -v230, v231, 1.0
	v_fmac_f32_e32 v231, v131, v231
	v_mul_f32_e32 v233, v232, v231
	v_fma_f32 v131, -v230, v233, v232
	v_fmac_f32_e32 v233, v131, v231
	v_fma_f32 v230, -v230, v233, v232
	v_div_fmas_f32 v230, v230, v231, v233
	v_div_fixup_f32 v133, v230, v229, 2.0
	v_sub_f32_e32 v133, 1.0, v133
	v_cvt_pk_bf16_f32 v133, v135, v133
	global_store_dword v[226:227], v133, off offset:64
	s_mov_b64 s[4:5], 0x300
	v_lshl_add_u64 v[226:227], v[226:227], 0, s[4:5]
	v_add_f32_e32 v228, v81, v81
	v_mul_f32_e32 v228, 0x3fb8aa3b, v228
	v_exp_f32_e32 v228, v228
	s_nop 0
	v_add_f32_e32 v229, 1.0, v228
	v_div_scale_f32 v230, s[4:5], v229, v229, 2.0
	v_rcp_f32_e32 v231, v230
	v_div_scale_f32 v232, vcc, 2.0, v229, 2.0
	v_fma_f32 v131, -v230, v231, 1.0
	v_fmac_f32_e32 v231, v131, v231
	v_mul_f32_e32 v233, v232, v231
	v_fma_f32 v131, -v230, v233, v232
	v_fmac_f32_e32 v233, v131, v231
	v_fma_f32 v230, -v230, v233, v232
	v_div_fmas_f32 v230, v230, v231, v233
	v_div_fixup_f32 v135, v230, v229, 2.0
	v_sub_f32_e32 v135, 1.0, v135
	v_add_f32_e32 v228, v85, v85
	v_mul_f32_e32 v228, 0x3fb8aa3b, v228
	v_exp_f32_e32 v228, v228
	s_nop 0
	v_add_f32_e32 v229, 1.0, v228
	v_div_scale_f32 v230, s[4:5], v229, v229, 2.0
	v_rcp_f32_e32 v231, v230
	v_div_scale_f32 v232, vcc, 2.0, v229, 2.0
	v_fma_f32 v131, -v230, v231, 1.0
	v_fmac_f32_e32 v231, v131, v231
	v_mul_f32_e32 v233, v232, v231
	v_fma_f32 v131, -v230, v233, v232
	v_fmac_f32_e32 v233, v131, v231
	v_fma_f32 v230, -v230, v233, v232
	v_div_fmas_f32 v230, v230, v231, v233
	v_div_fixup_f32 v133, v230, v229, 2.0
	v_sub_f32_e32 v133, 1.0, v133
	v_cvt_pk_bf16_f32 v133, v135, v133
	global_store_dword v[226:227], v133, off
	v_add_f32_e32 v228, v89, v89
	v_mul_f32_e32 v228, 0x3fb8aa3b, v228
	v_exp_f32_e32 v228, v228
	s_nop 0
	v_add_f32_e32 v229, 1.0, v228
	v_div_scale_f32 v230, s[4:5], v229, v229, 2.0
	v_rcp_f32_e32 v231, v230
	v_div_scale_f32 v232, vcc, 2.0, v229, 2.0
	v_fma_f32 v131, -v230, v231, 1.0
	v_fmac_f32_e32 v231, v131, v231
	v_mul_f32_e32 v233, v232, v231
	v_fma_f32 v131, -v230, v233, v232
	v_fmac_f32_e32 v233, v131, v231
	v_fma_f32 v230, -v230, v233, v232
	v_div_fmas_f32 v230, v230, v231, v233
	v_div_fixup_f32 v135, v230, v229, 2.0
	v_sub_f32_e32 v135, 1.0, v135
	v_add_f32_e32 v228, v93, v93
	v_mul_f32_e32 v228, 0x3fb8aa3b, v228
	v_exp_f32_e32 v228, v228
	s_nop 0
	v_add_f32_e32 v229, 1.0, v228
	v_div_scale_f32 v230, s[4:5], v229, v229, 2.0
	v_rcp_f32_e32 v231, v230
	v_div_scale_f32 v232, vcc, 2.0, v229, 2.0
	v_fma_f32 v131, -v230, v231, 1.0
	v_fmac_f32_e32 v231, v131, v231
	v_mul_f32_e32 v233, v232, v231
	v_fma_f32 v131, -v230, v233, v232
	v_fmac_f32_e32 v233, v131, v231
	v_fma_f32 v230, -v230, v233, v232
	v_div_fmas_f32 v230, v230, v231, v233
	v_div_fixup_f32 v133, v230, v229, 2.0
	v_sub_f32_e32 v133, 1.0, v133
	v_cvt_pk_bf16_f32 v133, v135, v133
	global_store_dword v[226:227], v133, off offset:64
	s_mov_b64 s[4:5], 0x300
	v_lshl_add_u64 v[226:227], v[226:227], 0, s[4:5]
	v_add_f32_e32 v228, v82, v82
	v_mul_f32_e32 v228, 0x3fb8aa3b, v228
	v_exp_f32_e32 v228, v228
	s_nop 0
	v_add_f32_e32 v229, 1.0, v228
	v_div_scale_f32 v230, s[4:5], v229, v229, 2.0
	v_rcp_f32_e32 v231, v230
	v_div_scale_f32 v232, vcc, 2.0, v229, 2.0
	v_fma_f32 v131, -v230, v231, 1.0
	v_fmac_f32_e32 v231, v131, v231
	v_mul_f32_e32 v233, v232, v231
	v_fma_f32 v131, -v230, v233, v232
	v_fmac_f32_e32 v233, v131, v231
	v_fma_f32 v230, -v230, v233, v232
	v_div_fmas_f32 v230, v230, v231, v233
	v_div_fixup_f32 v135, v230, v229, 2.0
	v_sub_f32_e32 v135, 1.0, v135
	v_add_f32_e32 v228, v86, v86
	v_mul_f32_e32 v228, 0x3fb8aa3b, v228
	v_exp_f32_e32 v228, v228
	s_nop 0
	v_add_f32_e32 v229, 1.0, v228
	v_div_scale_f32 v230, s[4:5], v229, v229, 2.0
	v_rcp_f32_e32 v231, v230
	v_div_scale_f32 v232, vcc, 2.0, v229, 2.0
	v_fma_f32 v131, -v230, v231, 1.0
	v_fmac_f32_e32 v231, v131, v231
	v_mul_f32_e32 v233, v232, v231
	v_fma_f32 v131, -v230, v233, v232
	v_fmac_f32_e32 v233, v131, v231
	v_fma_f32 v230, -v230, v233, v232
	v_div_fmas_f32 v230, v230, v231, v233
	v_div_fixup_f32 v133, v230, v229, 2.0
	v_sub_f32_e32 v133, 1.0, v133
	v_cvt_pk_bf16_f32 v133, v135, v133
	global_store_dword v[226:227], v133, off
	v_add_f32_e32 v228, v90, v90
	v_mul_f32_e32 v228, 0x3fb8aa3b, v228
	v_exp_f32_e32 v228, v228
	s_nop 0
	v_add_f32_e32 v229, 1.0, v228
	v_div_scale_f32 v230, s[4:5], v229, v229, 2.0
	v_rcp_f32_e32 v231, v230
	v_div_scale_f32 v232, vcc, 2.0, v229, 2.0
	v_fma_f32 v131, -v230, v231, 1.0
	v_fmac_f32_e32 v231, v131, v231
	v_mul_f32_e32 v233, v232, v231
	v_fma_f32 v131, -v230, v233, v232
	v_fmac_f32_e32 v233, v131, v231
	v_fma_f32 v230, -v230, v233, v232
	v_div_fmas_f32 v230, v230, v231, v233
	v_div_fixup_f32 v135, v230, v229, 2.0
	v_sub_f32_e32 v135, 1.0, v135
	v_add_f32_e32 v228, v94, v94
	v_mul_f32_e32 v228, 0x3fb8aa3b, v228
	v_exp_f32_e32 v228, v228
	s_nop 0
	v_add_f32_e32 v229, 1.0, v228
	v_div_scale_f32 v230, s[4:5], v229, v229, 2.0
	v_rcp_f32_e32 v231, v230
	v_div_scale_f32 v232, vcc, 2.0, v229, 2.0
	v_fma_f32 v131, -v230, v231, 1.0
	v_fmac_f32_e32 v231, v131, v231
	v_mul_f32_e32 v233, v232, v231
	v_fma_f32 v131, -v230, v233, v232
	v_fmac_f32_e32 v233, v131, v231
	v_fma_f32 v230, -v230, v233, v232
	v_div_fmas_f32 v230, v230, v231, v233
	v_div_fixup_f32 v133, v230, v229, 2.0
	v_sub_f32_e32 v133, 1.0, v133
	v_cvt_pk_bf16_f32 v133, v135, v133
	global_store_dword v[226:227], v133, off offset:64
	s_mov_b64 s[4:5], 0x300
	v_lshl_add_u64 v[226:227], v[226:227], 0, s[4:5]
	v_add_f32_e32 v228, v83, v83
	v_mul_f32_e32 v228, 0x3fb8aa3b, v228
	v_exp_f32_e32 v228, v228
	s_nop 0
	v_add_f32_e32 v229, 1.0, v228
	v_div_scale_f32 v230, s[4:5], v229, v229, 2.0
	v_rcp_f32_e32 v231, v230
	v_div_scale_f32 v232, vcc, 2.0, v229, 2.0
	v_fma_f32 v131, -v230, v231, 1.0
	v_fmac_f32_e32 v231, v131, v231
	v_mul_f32_e32 v233, v232, v231
	v_fma_f32 v131, -v230, v233, v232
	v_fmac_f32_e32 v233, v131, v231
	v_fma_f32 v230, -v230, v233, v232
	v_div_fmas_f32 v230, v230, v231, v233
	v_div_fixup_f32 v135, v230, v229, 2.0
	v_sub_f32_e32 v135, 1.0, v135
	v_add_f32_e32 v228, v87, v87
	v_mul_f32_e32 v228, 0x3fb8aa3b, v228
	v_exp_f32_e32 v228, v228
	s_nop 0
	v_add_f32_e32 v229, 1.0, v228
	v_div_scale_f32 v230, s[4:5], v229, v229, 2.0
	v_rcp_f32_e32 v231, v230
	v_div_scale_f32 v232, vcc, 2.0, v229, 2.0
	v_fma_f32 v131, -v230, v231, 1.0
	v_fmac_f32_e32 v231, v131, v231
	v_mul_f32_e32 v233, v232, v231
	v_fma_f32 v131, -v230, v233, v232
	v_fmac_f32_e32 v233, v131, v231
	v_fma_f32 v230, -v230, v233, v232
	v_div_fmas_f32 v230, v230, v231, v233
	v_div_fixup_f32 v133, v230, v229, 2.0
	v_sub_f32_e32 v133, 1.0, v133
	v_cvt_pk_bf16_f32 v133, v135, v133
	global_store_dword v[226:227], v133, off
	v_add_f32_e32 v228, v91, v91
	v_mul_f32_e32 v228, 0x3fb8aa3b, v228
	v_exp_f32_e32 v228, v228
	s_nop 0
	v_add_f32_e32 v229, 1.0, v228
	v_div_scale_f32 v230, s[4:5], v229, v229, 2.0
	v_rcp_f32_e32 v231, v230
	v_div_scale_f32 v232, vcc, 2.0, v229, 2.0
	v_fma_f32 v131, -v230, v231, 1.0
	v_fmac_f32_e32 v231, v131, v231
	v_mul_f32_e32 v233, v232, v231
	v_fma_f32 v131, -v230, v233, v232
	v_fmac_f32_e32 v233, v131, v231
	v_fma_f32 v230, -v230, v233, v232
	v_div_fmas_f32 v230, v230, v231, v233
	v_div_fixup_f32 v135, v230, v229, 2.0
	v_sub_f32_e32 v135, 1.0, v135
	v_add_f32_e32 v228, v95, v95
	v_mul_f32_e32 v228, 0x3fb8aa3b, v228
	v_exp_f32_e32 v228, v228
	s_nop 0
	v_add_f32_e32 v229, 1.0, v228
	v_div_scale_f32 v230, s[4:5], v229, v229, 2.0
	v_rcp_f32_e32 v231, v230
	v_div_scale_f32 v232, vcc, 2.0, v229, 2.0
	v_fma_f32 v131, -v230, v231, 1.0
	v_fmac_f32_e32 v231, v131, v231
	v_mul_f32_e32 v233, v232, v231
	v_fma_f32 v131, -v230, v233, v232
	v_fmac_f32_e32 v233, v131, v231
	v_fma_f32 v230, -v230, v233, v232
	v_div_fmas_f32 v230, v230, v231, v233
	v_div_fixup_f32 v133, v230, v229, 2.0
	v_sub_f32_e32 v133, 1.0, v133
	v_cvt_pk_bf16_f32 v133, v135, v133
	global_store_dword v[226:227], v133, off offset:64
	s_mov_b64 s[4:5], 0x2700
	v_lshl_add_u64 v[226:227], v[226:227], 0, s[4:5]
	v_add_f32_e32 v228, v96, v96
	v_mul_f32_e32 v228, 0x3fb8aa3b, v228
	v_exp_f32_e32 v228, v228
	s_nop 0
	v_add_f32_e32 v229, 1.0, v228
	v_div_scale_f32 v230, s[4:5], v229, v229, 2.0
	v_rcp_f32_e32 v231, v230
	v_div_scale_f32 v232, vcc, 2.0, v229, 2.0
	v_fma_f32 v131, -v230, v231, 1.0
	v_fmac_f32_e32 v231, v131, v231
	v_mul_f32_e32 v233, v232, v231
	v_fma_f32 v131, -v230, v233, v232
	v_fmac_f32_e32 v233, v131, v231
	v_fma_f32 v230, -v230, v233, v232
	v_div_fmas_f32 v230, v230, v231, v233
	v_div_fixup_f32 v135, v230, v229, 2.0
	v_sub_f32_e32 v135, 1.0, v135
	v_add_f32_e32 v228, v100, v100
	v_mul_f32_e32 v228, 0x3fb8aa3b, v228
	v_exp_f32_e32 v228, v228
	s_nop 0
	v_add_f32_e32 v229, 1.0, v228
	v_div_scale_f32 v230, s[4:5], v229, v229, 2.0
	v_rcp_f32_e32 v231, v230
	v_div_scale_f32 v232, vcc, 2.0, v229, 2.0
	v_fma_f32 v131, -v230, v231, 1.0
	v_fmac_f32_e32 v231, v131, v231
	v_mul_f32_e32 v233, v232, v231
	v_fma_f32 v131, -v230, v233, v232
	v_fmac_f32_e32 v233, v131, v231
	v_fma_f32 v230, -v230, v233, v232
	v_div_fmas_f32 v230, v230, v231, v233
	v_div_fixup_f32 v133, v230, v229, 2.0
	v_sub_f32_e32 v133, 1.0, v133
	v_cvt_pk_bf16_f32 v133, v135, v133
	global_store_dword v[226:227], v133, off
	v_add_f32_e32 v228, v104, v104
	v_mul_f32_e32 v228, 0x3fb8aa3b, v228
	v_exp_f32_e32 v228, v228
	s_nop 0
	v_add_f32_e32 v229, 1.0, v228
	v_div_scale_f32 v230, s[4:5], v229, v229, 2.0
	v_rcp_f32_e32 v231, v230
	v_div_scale_f32 v232, vcc, 2.0, v229, 2.0
	v_fma_f32 v131, -v230, v231, 1.0
	v_fmac_f32_e32 v231, v131, v231
	v_mul_f32_e32 v233, v232, v231
	v_fma_f32 v131, -v230, v233, v232
	v_fmac_f32_e32 v233, v131, v231
	v_fma_f32 v230, -v230, v233, v232
	v_div_fmas_f32 v230, v230, v231, v233
	v_div_fixup_f32 v135, v230, v229, 2.0
	v_sub_f32_e32 v135, 1.0, v135
	v_add_f32_e32 v228, v108, v108
	v_mul_f32_e32 v228, 0x3fb8aa3b, v228
	v_exp_f32_e32 v228, v228
	s_nop 0
	v_add_f32_e32 v229, 1.0, v228
	v_div_scale_f32 v230, s[4:5], v229, v229, 2.0
	v_rcp_f32_e32 v231, v230
	v_div_scale_f32 v232, vcc, 2.0, v229, 2.0
	v_fma_f32 v131, -v230, v231, 1.0
	v_fmac_f32_e32 v231, v131, v231
	v_mul_f32_e32 v233, v232, v231
	v_fma_f32 v131, -v230, v233, v232
	v_fmac_f32_e32 v233, v131, v231
	v_fma_f32 v230, -v230, v233, v232
	v_div_fmas_f32 v230, v230, v231, v233
	v_div_fixup_f32 v133, v230, v229, 2.0
	v_sub_f32_e32 v133, 1.0, v133
	v_cvt_pk_bf16_f32 v133, v135, v133
	global_store_dword v[226:227], v133, off offset:64
	s_mov_b64 s[4:5], 0x300
	v_lshl_add_u64 v[226:227], v[226:227], 0, s[4:5]
	v_add_f32_e32 v228, v97, v97
	v_mul_f32_e32 v228, 0x3fb8aa3b, v228
	v_exp_f32_e32 v228, v228
	s_nop 0
	v_add_f32_e32 v229, 1.0, v228
	v_div_scale_f32 v230, s[4:5], v229, v229, 2.0
	v_rcp_f32_e32 v231, v230
	v_div_scale_f32 v232, vcc, 2.0, v229, 2.0
	v_fma_f32 v131, -v230, v231, 1.0
	v_fmac_f32_e32 v231, v131, v231
	v_mul_f32_e32 v233, v232, v231
	v_fma_f32 v131, -v230, v233, v232
	v_fmac_f32_e32 v233, v131, v231
	v_fma_f32 v230, -v230, v233, v232
	v_div_fmas_f32 v230, v230, v231, v233
	v_div_fixup_f32 v135, v230, v229, 2.0
	v_sub_f32_e32 v135, 1.0, v135
	v_add_f32_e32 v228, v101, v101
	v_mul_f32_e32 v228, 0x3fb8aa3b, v228
	v_exp_f32_e32 v228, v228
	s_nop 0
	v_add_f32_e32 v229, 1.0, v228
	v_div_scale_f32 v230, s[4:5], v229, v229, 2.0
	v_rcp_f32_e32 v231, v230
	v_div_scale_f32 v232, vcc, 2.0, v229, 2.0
	v_fma_f32 v131, -v230, v231, 1.0
	v_fmac_f32_e32 v231, v131, v231
	v_mul_f32_e32 v233, v232, v231
	v_fma_f32 v131, -v230, v233, v232
	v_fmac_f32_e32 v233, v131, v231
	v_fma_f32 v230, -v230, v233, v232
	v_div_fmas_f32 v230, v230, v231, v233
	v_div_fixup_f32 v133, v230, v229, 2.0
	v_sub_f32_e32 v133, 1.0, v133
	v_cvt_pk_bf16_f32 v133, v135, v133
	global_store_dword v[226:227], v133, off
	v_add_f32_e32 v228, v105, v105
	v_mul_f32_e32 v228, 0x3fb8aa3b, v228
	v_exp_f32_e32 v228, v228
	s_nop 0
	v_add_f32_e32 v229, 1.0, v228
	v_div_scale_f32 v230, s[4:5], v229, v229, 2.0
	v_rcp_f32_e32 v231, v230
	v_div_scale_f32 v232, vcc, 2.0, v229, 2.0
	v_fma_f32 v131, -v230, v231, 1.0
	v_fmac_f32_e32 v231, v131, v231
	v_mul_f32_e32 v233, v232, v231
	v_fma_f32 v131, -v230, v233, v232
	v_fmac_f32_e32 v233, v131, v231
	v_fma_f32 v230, -v230, v233, v232
	v_div_fmas_f32 v230, v230, v231, v233
	v_div_fixup_f32 v135, v230, v229, 2.0
	v_sub_f32_e32 v135, 1.0, v135
	v_add_f32_e32 v228, v109, v109
	v_mul_f32_e32 v228, 0x3fb8aa3b, v228
	v_exp_f32_e32 v228, v228
	s_nop 0
	v_add_f32_e32 v229, 1.0, v228
	v_div_scale_f32 v230, s[4:5], v229, v229, 2.0
	v_rcp_f32_e32 v231, v230
	v_div_scale_f32 v232, vcc, 2.0, v229, 2.0
	v_fma_f32 v131, -v230, v231, 1.0
	v_fmac_f32_e32 v231, v131, v231
	v_mul_f32_e32 v233, v232, v231
	v_fma_f32 v131, -v230, v233, v232
	v_fmac_f32_e32 v233, v131, v231
	v_fma_f32 v230, -v230, v233, v232
	v_div_fmas_f32 v230, v230, v231, v233
	v_div_fixup_f32 v133, v230, v229, 2.0
	v_sub_f32_e32 v133, 1.0, v133
	v_cvt_pk_bf16_f32 v133, v135, v133
	global_store_dword v[226:227], v133, off offset:64
	s_mov_b64 s[4:5], 0x300
	v_lshl_add_u64 v[226:227], v[226:227], 0, s[4:5]
	v_add_f32_e32 v228, v98, v98
	v_mul_f32_e32 v228, 0x3fb8aa3b, v228
	v_exp_f32_e32 v228, v228
	s_nop 0
	v_add_f32_e32 v229, 1.0, v228
	v_div_scale_f32 v230, s[4:5], v229, v229, 2.0
	v_rcp_f32_e32 v231, v230
	v_div_scale_f32 v232, vcc, 2.0, v229, 2.0
	v_fma_f32 v131, -v230, v231, 1.0
	v_fmac_f32_e32 v231, v131, v231
	v_mul_f32_e32 v233, v232, v231
	v_fma_f32 v131, -v230, v233, v232
	v_fmac_f32_e32 v233, v131, v231
	v_fma_f32 v230, -v230, v233, v232
	v_div_fmas_f32 v230, v230, v231, v233
	v_div_fixup_f32 v135, v230, v229, 2.0
	v_sub_f32_e32 v135, 1.0, v135
	v_add_f32_e32 v228, v102, v102
	v_mul_f32_e32 v228, 0x3fb8aa3b, v228
	v_exp_f32_e32 v228, v228
	s_nop 0
	v_add_f32_e32 v229, 1.0, v228
	v_div_scale_f32 v230, s[4:5], v229, v229, 2.0
	v_rcp_f32_e32 v231, v230
	v_div_scale_f32 v232, vcc, 2.0, v229, 2.0
	v_fma_f32 v131, -v230, v231, 1.0
	v_fmac_f32_e32 v231, v131, v231
	v_mul_f32_e32 v233, v232, v231
	v_fma_f32 v131, -v230, v233, v232
	v_fmac_f32_e32 v233, v131, v231
	v_fma_f32 v230, -v230, v233, v232
	v_div_fmas_f32 v230, v230, v231, v233
	v_div_fixup_f32 v133, v230, v229, 2.0
	v_sub_f32_e32 v133, 1.0, v133
	v_cvt_pk_bf16_f32 v133, v135, v133
	global_store_dword v[226:227], v133, off
	v_add_f32_e32 v228, v106, v106
	v_mul_f32_e32 v228, 0x3fb8aa3b, v228
	v_exp_f32_e32 v228, v228
	s_nop 0
	v_add_f32_e32 v229, 1.0, v228
	v_div_scale_f32 v230, s[4:5], v229, v229, 2.0
	v_rcp_f32_e32 v231, v230
	v_div_scale_f32 v232, vcc, 2.0, v229, 2.0
	v_fma_f32 v131, -v230, v231, 1.0
	v_fmac_f32_e32 v231, v131, v231
	v_mul_f32_e32 v233, v232, v231
	v_fma_f32 v131, -v230, v233, v232
	v_fmac_f32_e32 v233, v131, v231
	v_fma_f32 v230, -v230, v233, v232
	v_div_fmas_f32 v230, v230, v231, v233
	v_div_fixup_f32 v135, v230, v229, 2.0
	v_sub_f32_e32 v135, 1.0, v135
	v_add_f32_e32 v228, v110, v110
	v_mul_f32_e32 v228, 0x3fb8aa3b, v228
	v_exp_f32_e32 v228, v228
	s_nop 0
	v_add_f32_e32 v229, 1.0, v228
	v_div_scale_f32 v230, s[4:5], v229, v229, 2.0
	v_rcp_f32_e32 v231, v230
	v_div_scale_f32 v232, vcc, 2.0, v229, 2.0
	v_fma_f32 v131, -v230, v231, 1.0
	v_fmac_f32_e32 v231, v131, v231
	v_mul_f32_e32 v233, v232, v231
	v_fma_f32 v131, -v230, v233, v232
	v_fmac_f32_e32 v233, v131, v231
	v_fma_f32 v230, -v230, v233, v232
	v_div_fmas_f32 v230, v230, v231, v233
	v_div_fixup_f32 v133, v230, v229, 2.0
	v_sub_f32_e32 v133, 1.0, v133
	v_cvt_pk_bf16_f32 v133, v135, v133
	global_store_dword v[226:227], v133, off offset:64
	s_mov_b64 s[4:5], 0x300
	v_lshl_add_u64 v[226:227], v[226:227], 0, s[4:5]
	v_add_f32_e32 v228, v99, v99
	v_mul_f32_e32 v228, 0x3fb8aa3b, v228
	v_exp_f32_e32 v228, v228
	s_nop 0
	v_add_f32_e32 v229, 1.0, v228
	v_div_scale_f32 v230, s[4:5], v229, v229, 2.0
	v_rcp_f32_e32 v231, v230
	v_div_scale_f32 v232, vcc, 2.0, v229, 2.0
	v_fma_f32 v131, -v230, v231, 1.0
	v_fmac_f32_e32 v231, v131, v231
	v_mul_f32_e32 v233, v232, v231
	v_fma_f32 v131, -v230, v233, v232
	v_fmac_f32_e32 v233, v131, v231
	v_fma_f32 v230, -v230, v233, v232
	v_div_fmas_f32 v230, v230, v231, v233
	v_div_fixup_f32 v135, v230, v229, 2.0
	v_sub_f32_e32 v135, 1.0, v135
	v_add_f32_e32 v228, v103, v103
	v_mul_f32_e32 v228, 0x3fb8aa3b, v228
	v_exp_f32_e32 v228, v228
	s_nop 0
	v_add_f32_e32 v229, 1.0, v228
	v_div_scale_f32 v230, s[4:5], v229, v229, 2.0
	v_rcp_f32_e32 v231, v230
	v_div_scale_f32 v232, vcc, 2.0, v229, 2.0
	v_fma_f32 v131, -v230, v231, 1.0
	v_fmac_f32_e32 v231, v131, v231
	v_mul_f32_e32 v233, v232, v231
	v_fma_f32 v131, -v230, v233, v232
	v_fmac_f32_e32 v233, v131, v231
	v_fma_f32 v230, -v230, v233, v232
	v_div_fmas_f32 v230, v230, v231, v233
	v_div_fixup_f32 v133, v230, v229, 2.0
	v_sub_f32_e32 v133, 1.0, v133
	v_cvt_pk_bf16_f32 v133, v135, v133
	global_store_dword v[226:227], v133, off
	v_add_f32_e32 v228, v107, v107
	v_mul_f32_e32 v228, 0x3fb8aa3b, v228
	v_exp_f32_e32 v228, v228
	s_nop 0
	v_add_f32_e32 v229, 1.0, v228
	v_div_scale_f32 v230, s[4:5], v229, v229, 2.0
	v_rcp_f32_e32 v231, v230
	v_div_scale_f32 v232, vcc, 2.0, v229, 2.0
	v_fma_f32 v131, -v230, v231, 1.0
	v_fmac_f32_e32 v231, v131, v231
	v_mul_f32_e32 v233, v232, v231
	v_fma_f32 v131, -v230, v233, v232
	v_fmac_f32_e32 v233, v131, v231
	v_fma_f32 v230, -v230, v233, v232
	v_div_fmas_f32 v230, v230, v231, v233
	v_div_fixup_f32 v135, v230, v229, 2.0
	v_sub_f32_e32 v135, 1.0, v135
	v_add_f32_e32 v228, v111, v111
	v_mul_f32_e32 v228, 0x3fb8aa3b, v228
	v_exp_f32_e32 v228, v228
	s_nop 0
	v_add_f32_e32 v229, 1.0, v228
	v_div_scale_f32 v230, s[4:5], v229, v229, 2.0
	v_rcp_f32_e32 v231, v230
	v_div_scale_f32 v232, vcc, 2.0, v229, 2.0
	v_fma_f32 v131, -v230, v231, 1.0
	v_fmac_f32_e32 v231, v131, v231
	v_mul_f32_e32 v233, v232, v231
	v_fma_f32 v131, -v230, v233, v232
	v_fmac_f32_e32 v233, v131, v231
	v_fma_f32 v230, -v230, v233, v232
	v_div_fmas_f32 v230, v230, v231, v233
	v_div_fixup_f32 v133, v230, v229, 2.0
	v_sub_f32_e32 v133, 1.0, v133
	v_cvt_pk_bf16_f32 v133, v135, v133
	global_store_dword v[226:227], v133, off offset:64
	s_mov_b64 s[4:5], 0x2700
	v_lshl_add_u64 v[226:227], v[226:227], 0, s[4:5]
	v_add_f32_e32 v228, v112, v112
	v_mul_f32_e32 v228, 0x3fb8aa3b, v228
	v_exp_f32_e32 v228, v228
	s_nop 0
	v_add_f32_e32 v229, 1.0, v228
	v_div_scale_f32 v230, s[4:5], v229, v229, 2.0
	v_rcp_f32_e32 v231, v230
	v_div_scale_f32 v232, vcc, 2.0, v229, 2.0
	v_fma_f32 v131, -v230, v231, 1.0
	v_fmac_f32_e32 v231, v131, v231
	v_mul_f32_e32 v233, v232, v231
	v_fma_f32 v131, -v230, v233, v232
	v_fmac_f32_e32 v233, v131, v231
	v_fma_f32 v230, -v230, v233, v232
	v_div_fmas_f32 v230, v230, v231, v233
	v_div_fixup_f32 v135, v230, v229, 2.0
	v_sub_f32_e32 v135, 1.0, v135
	v_add_f32_e32 v228, v116, v116
	v_mul_f32_e32 v228, 0x3fb8aa3b, v228
	v_exp_f32_e32 v228, v228
	s_nop 0
	v_add_f32_e32 v229, 1.0, v228
	v_div_scale_f32 v230, s[4:5], v229, v229, 2.0
	v_rcp_f32_e32 v231, v230
	v_div_scale_f32 v232, vcc, 2.0, v229, 2.0
	v_fma_f32 v131, -v230, v231, 1.0
	v_fmac_f32_e32 v231, v131, v231
	v_mul_f32_e32 v233, v232, v231
	v_fma_f32 v131, -v230, v233, v232
	v_fmac_f32_e32 v233, v131, v231
	v_fma_f32 v230, -v230, v233, v232
	v_div_fmas_f32 v230, v230, v231, v233
	v_div_fixup_f32 v133, v230, v229, 2.0
	v_sub_f32_e32 v133, 1.0, v133
	v_cvt_pk_bf16_f32 v133, v135, v133
	global_store_dword v[226:227], v133, off
	v_add_f32_e32 v228, v120, v120
	v_mul_f32_e32 v228, 0x3fb8aa3b, v228
	v_exp_f32_e32 v228, v228
	s_nop 0
	v_add_f32_e32 v229, 1.0, v228
	v_div_scale_f32 v230, s[4:5], v229, v229, 2.0
	v_rcp_f32_e32 v231, v230
	v_div_scale_f32 v232, vcc, 2.0, v229, 2.0
	v_fma_f32 v131, -v230, v231, 1.0
	v_fmac_f32_e32 v231, v131, v231
	v_mul_f32_e32 v233, v232, v231
	v_fma_f32 v131, -v230, v233, v232
	v_fmac_f32_e32 v233, v131, v231
	v_fma_f32 v230, -v230, v233, v232
	v_div_fmas_f32 v230, v230, v231, v233
	v_div_fixup_f32 v135, v230, v229, 2.0
	v_sub_f32_e32 v135, 1.0, v135
	v_add_f32_e32 v228, v124, v124
	v_mul_f32_e32 v228, 0x3fb8aa3b, v228
	v_exp_f32_e32 v228, v228
	s_nop 0
	v_add_f32_e32 v229, 1.0, v228
	v_div_scale_f32 v230, s[4:5], v229, v229, 2.0
	v_rcp_f32_e32 v231, v230
	v_div_scale_f32 v232, vcc, 2.0, v229, 2.0
	v_fma_f32 v131, -v230, v231, 1.0
	v_fmac_f32_e32 v231, v131, v231
	v_mul_f32_e32 v233, v232, v231
	v_fma_f32 v131, -v230, v233, v232
	v_fmac_f32_e32 v233, v131, v231
	v_fma_f32 v230, -v230, v233, v232
	v_div_fmas_f32 v230, v230, v231, v233
	v_div_fixup_f32 v133, v230, v229, 2.0
	v_sub_f32_e32 v133, 1.0, v133
	v_cvt_pk_bf16_f32 v133, v135, v133
	global_store_dword v[226:227], v133, off offset:64
	s_mov_b64 s[4:5], 0x300
	v_lshl_add_u64 v[226:227], v[226:227], 0, s[4:5]
	v_add_f32_e32 v228, v113, v113
	v_mul_f32_e32 v228, 0x3fb8aa3b, v228
	v_exp_f32_e32 v228, v228
	s_nop 0
	v_add_f32_e32 v229, 1.0, v228
	v_div_scale_f32 v230, s[4:5], v229, v229, 2.0
	v_rcp_f32_e32 v231, v230
	v_div_scale_f32 v232, vcc, 2.0, v229, 2.0
	v_fma_f32 v131, -v230, v231, 1.0
	v_fmac_f32_e32 v231, v131, v231
	v_mul_f32_e32 v233, v232, v231
	v_fma_f32 v131, -v230, v233, v232
	v_fmac_f32_e32 v233, v131, v231
	v_fma_f32 v230, -v230, v233, v232
	v_div_fmas_f32 v230, v230, v231, v233
	v_div_fixup_f32 v135, v230, v229, 2.0
	v_sub_f32_e32 v135, 1.0, v135
	v_add_f32_e32 v228, v117, v117
	v_mul_f32_e32 v228, 0x3fb8aa3b, v228
	v_exp_f32_e32 v228, v228
	s_nop 0
	v_add_f32_e32 v229, 1.0, v228
	v_div_scale_f32 v230, s[4:5], v229, v229, 2.0
	v_rcp_f32_e32 v231, v230
	v_div_scale_f32 v232, vcc, 2.0, v229, 2.0
	v_fma_f32 v131, -v230, v231, 1.0
	v_fmac_f32_e32 v231, v131, v231
	v_mul_f32_e32 v233, v232, v231
	v_fma_f32 v131, -v230, v233, v232
	v_fmac_f32_e32 v233, v131, v231
	v_fma_f32 v230, -v230, v233, v232
	v_div_fmas_f32 v230, v230, v231, v233
	v_div_fixup_f32 v133, v230, v229, 2.0
	v_sub_f32_e32 v133, 1.0, v133
	v_cvt_pk_bf16_f32 v133, v135, v133
	global_store_dword v[226:227], v133, off
	v_add_f32_e32 v228, v121, v121
	v_mul_f32_e32 v228, 0x3fb8aa3b, v228
	v_exp_f32_e32 v228, v228
	s_nop 0
	v_add_f32_e32 v229, 1.0, v228
	v_div_scale_f32 v230, s[4:5], v229, v229, 2.0
	v_rcp_f32_e32 v231, v230
	v_div_scale_f32 v232, vcc, 2.0, v229, 2.0
	v_fma_f32 v131, -v230, v231, 1.0
	v_fmac_f32_e32 v231, v131, v231
	v_mul_f32_e32 v233, v232, v231
	v_fma_f32 v131, -v230, v233, v232
	v_fmac_f32_e32 v233, v131, v231
	v_fma_f32 v230, -v230, v233, v232
	v_div_fmas_f32 v230, v230, v231, v233
	v_div_fixup_f32 v135, v230, v229, 2.0
	v_sub_f32_e32 v135, 1.0, v135
	v_add_f32_e32 v228, v125, v125
	v_mul_f32_e32 v228, 0x3fb8aa3b, v228
	v_exp_f32_e32 v228, v228
	s_nop 0
	v_add_f32_e32 v229, 1.0, v228
	v_div_scale_f32 v230, s[4:5], v229, v229, 2.0
	v_rcp_f32_e32 v231, v230
	v_div_scale_f32 v232, vcc, 2.0, v229, 2.0
	v_fma_f32 v131, -v230, v231, 1.0
	v_fmac_f32_e32 v231, v131, v231
	v_mul_f32_e32 v233, v232, v231
	v_fma_f32 v131, -v230, v233, v232
	v_fmac_f32_e32 v233, v131, v231
	v_fma_f32 v230, -v230, v233, v232
	v_div_fmas_f32 v230, v230, v231, v233
	v_div_fixup_f32 v133, v230, v229, 2.0
	v_sub_f32_e32 v133, 1.0, v133
	v_cvt_pk_bf16_f32 v133, v135, v133
	global_store_dword v[226:227], v133, off offset:64
	s_mov_b64 s[4:5], 0x300
	v_lshl_add_u64 v[226:227], v[226:227], 0, s[4:5]
	v_add_f32_e32 v228, v114, v114
	v_mul_f32_e32 v228, 0x3fb8aa3b, v228
	v_exp_f32_e32 v228, v228
	s_nop 0
	v_add_f32_e32 v229, 1.0, v228
	v_div_scale_f32 v230, s[4:5], v229, v229, 2.0
	v_rcp_f32_e32 v231, v230
	v_div_scale_f32 v232, vcc, 2.0, v229, 2.0
	v_fma_f32 v131, -v230, v231, 1.0
	v_fmac_f32_e32 v231, v131, v231
	v_mul_f32_e32 v233, v232, v231
	v_fma_f32 v131, -v230, v233, v232
	v_fmac_f32_e32 v233, v131, v231
	v_fma_f32 v230, -v230, v233, v232
	v_div_fmas_f32 v230, v230, v231, v233
	v_div_fixup_f32 v135, v230, v229, 2.0
	v_sub_f32_e32 v135, 1.0, v135
	v_add_f32_e32 v228, v118, v118
	v_mul_f32_e32 v228, 0x3fb8aa3b, v228
	v_exp_f32_e32 v228, v228
	s_nop 0
	v_add_f32_e32 v229, 1.0, v228
	v_div_scale_f32 v230, s[4:5], v229, v229, 2.0
	v_rcp_f32_e32 v231, v230
	v_div_scale_f32 v232, vcc, 2.0, v229, 2.0
	v_fma_f32 v131, -v230, v231, 1.0
	v_fmac_f32_e32 v231, v131, v231
	v_mul_f32_e32 v233, v232, v231
	v_fma_f32 v131, -v230, v233, v232
	v_fmac_f32_e32 v233, v131, v231
	v_fma_f32 v230, -v230, v233, v232
	v_div_fmas_f32 v230, v230, v231, v233
	v_div_fixup_f32 v133, v230, v229, 2.0
	v_sub_f32_e32 v133, 1.0, v133
	v_cvt_pk_bf16_f32 v133, v135, v133
	global_store_dword v[226:227], v133, off
	v_add_f32_e32 v228, v122, v122
	v_mul_f32_e32 v228, 0x3fb8aa3b, v228
	v_exp_f32_e32 v228, v228
	s_nop 0
	v_add_f32_e32 v229, 1.0, v228
	v_div_scale_f32 v230, s[4:5], v229, v229, 2.0
	v_rcp_f32_e32 v231, v230
	v_div_scale_f32 v232, vcc, 2.0, v229, 2.0
	v_fma_f32 v131, -v230, v231, 1.0
	v_fmac_f32_e32 v231, v131, v231
	v_mul_f32_e32 v233, v232, v231
	v_fma_f32 v131, -v230, v233, v232
	v_fmac_f32_e32 v233, v131, v231
	v_fma_f32 v230, -v230, v233, v232
	v_div_fmas_f32 v230, v230, v231, v233
	v_div_fixup_f32 v135, v230, v229, 2.0
	v_sub_f32_e32 v135, 1.0, v135
	v_add_f32_e32 v228, v126, v126
	v_mul_f32_e32 v228, 0x3fb8aa3b, v228
	v_exp_f32_e32 v228, v228
	s_nop 0
	v_add_f32_e32 v229, 1.0, v228
	v_div_scale_f32 v230, s[4:5], v229, v229, 2.0
	v_rcp_f32_e32 v231, v230
	v_div_scale_f32 v232, vcc, 2.0, v229, 2.0
	v_fma_f32 v131, -v230, v231, 1.0
	v_fmac_f32_e32 v231, v131, v231
	v_mul_f32_e32 v233, v232, v231
	v_fma_f32 v131, -v230, v233, v232
	v_fmac_f32_e32 v233, v131, v231
	v_fma_f32 v230, -v230, v233, v232
	v_div_fmas_f32 v230, v230, v231, v233
	v_div_fixup_f32 v133, v230, v229, 2.0
	v_sub_f32_e32 v133, 1.0, v133
	v_cvt_pk_bf16_f32 v133, v135, v133
	global_store_dword v[226:227], v133, off offset:64
	s_mov_b64 s[4:5], 0x300
	v_lshl_add_u64 v[226:227], v[226:227], 0, s[4:5]
	v_add_f32_e32 v228, v115, v115
	v_mul_f32_e32 v228, 0x3fb8aa3b, v228
	v_exp_f32_e32 v228, v228
	s_nop 0
	v_add_f32_e32 v229, 1.0, v228
	v_div_scale_f32 v230, s[4:5], v229, v229, 2.0
	v_rcp_f32_e32 v231, v230
	v_div_scale_f32 v232, vcc, 2.0, v229, 2.0
	v_fma_f32 v131, -v230, v231, 1.0
	v_fmac_f32_e32 v231, v131, v231
	v_mul_f32_e32 v233, v232, v231
	v_fma_f32 v131, -v230, v233, v232
	v_fmac_f32_e32 v233, v131, v231
	v_fma_f32 v230, -v230, v233, v232
	v_div_fmas_f32 v230, v230, v231, v233
	v_div_fixup_f32 v135, v230, v229, 2.0
	v_sub_f32_e32 v135, 1.0, v135
	v_add_f32_e32 v228, v119, v119
	v_mul_f32_e32 v228, 0x3fb8aa3b, v228
	v_exp_f32_e32 v228, v228
	s_nop 0
	v_add_f32_e32 v229, 1.0, v228
	v_div_scale_f32 v230, s[4:5], v229, v229, 2.0
	v_rcp_f32_e32 v231, v230
	v_div_scale_f32 v232, vcc, 2.0, v229, 2.0
	v_fma_f32 v131, -v230, v231, 1.0
	v_fmac_f32_e32 v231, v131, v231
	v_mul_f32_e32 v233, v232, v231
	v_fma_f32 v131, -v230, v233, v232
	v_fmac_f32_e32 v233, v131, v231
	v_fma_f32 v230, -v230, v233, v232
	v_div_fmas_f32 v230, v230, v231, v233
	v_div_fixup_f32 v133, v230, v229, 2.0
	v_sub_f32_e32 v133, 1.0, v133
	v_cvt_pk_bf16_f32 v133, v135, v133
	global_store_dword v[226:227], v133, off
	v_add_f32_e32 v228, v123, v123
	v_mul_f32_e32 v228, 0x3fb8aa3b, v228
	v_exp_f32_e32 v228, v228
	s_nop 0
	v_add_f32_e32 v229, 1.0, v228
	v_div_scale_f32 v230, s[4:5], v229, v229, 2.0
	v_rcp_f32_e32 v231, v230
	v_div_scale_f32 v232, vcc, 2.0, v229, 2.0
	v_fma_f32 v131, -v230, v231, 1.0
	v_fmac_f32_e32 v231, v131, v231
	v_mul_f32_e32 v233, v232, v231
	v_fma_f32 v131, -v230, v233, v232
	v_fmac_f32_e32 v233, v131, v231
	v_fma_f32 v230, -v230, v233, v232
	v_div_fmas_f32 v230, v230, v231, v233
	v_div_fixup_f32 v135, v230, v229, 2.0
	v_sub_f32_e32 v135, 1.0, v135
	v_add_f32_e32 v228, v127, v127
	v_mul_f32_e32 v228, 0x3fb8aa3b, v228
	v_exp_f32_e32 v228, v228
	s_nop 0
	v_add_f32_e32 v229, 1.0, v228
	v_div_scale_f32 v230, s[4:5], v229, v229, 2.0
	v_rcp_f32_e32 v231, v230
	v_div_scale_f32 v232, vcc, 2.0, v229, 2.0
	v_fma_f32 v131, -v230, v231, 1.0
	v_fmac_f32_e32 v231, v131, v231
	v_mul_f32_e32 v233, v232, v231
	v_fma_f32 v131, -v230, v233, v232
	v_fmac_f32_e32 v233, v131, v231
	v_fma_f32 v230, -v230, v233, v232
	v_div_fmas_f32 v230, v230, v231, v233
	v_div_fixup_f32 v133, v230, v229, 2.0
	v_sub_f32_e32 v133, 1.0, v133
	v_cvt_pk_bf16_f32 v133, v135, v133
	global_store_dword v[226:227], v133, off offset:64
	s_branch .Lip_nolin
.Lip_lin1:
	s_cmp_lg_u32 s57, 1
	s_cbranch_scc1 .Lip_lin2
	v_mov_b32_e32 v226, s50
	v_mov_b32_e32 v227, s51
	v_add_co_u32_e32 v226, vcc, v226, v169
	s_nop 1
	v_addc_co_u32_e32 v227, vcc, 0, v227, vcc
	v_cvt_pk_bf16_f32 v133, v0, v4
	global_store_dword v[226:227], v133, off
	v_cvt_pk_bf16_f32 v133, v8, v12
	global_store_dword v[226:227], v133, off offset:64
	s_mov_b64 s[4:5], 0x300
	v_lshl_add_u64 v[226:227], v[226:227], 0, s[4:5]
	v_cvt_pk_bf16_f32 v133, v1, v5
	global_store_dword v[226:227], v133, off
	v_cvt_pk_bf16_f32 v133, v9, v13
	global_store_dword v[226:227], v133, off offset:64
	s_mov_b64 s[4:5], 0x300
	v_lshl_add_u64 v[226:227], v[226:227], 0, s[4:5]
	v_cvt_pk_bf16_f32 v133, v2, v6
	global_store_dword v[226:227], v133, off
	v_cvt_pk_bf16_f32 v133, v10, v14
	global_store_dword v[226:227], v133, off offset:64
	s_mov_b64 s[4:5], 0x300
	v_lshl_add_u64 v[226:227], v[226:227], 0, s[4:5]
	v_cvt_pk_bf16_f32 v133, v3, v7
	global_store_dword v[226:227], v133, off
	v_cvt_pk_bf16_f32 v133, v11, v15
	global_store_dword v[226:227], v133, off offset:64
	s_mov_b64 s[4:5], 0x2700
	v_lshl_add_u64 v[226:227], v[226:227], 0, s[4:5]
	v_cvt_pk_bf16_f32 v133, v16, v20
	global_store_dword v[226:227], v133, off
	v_cvt_pk_bf16_f32 v133, v24, v28
	global_store_dword v[226:227], v133, off offset:64
	s_mov_b64 s[4:5], 0x300
	v_lshl_add_u64 v[226:227], v[226:227], 0, s[4:5]
	v_cvt_pk_bf16_f32 v133, v17, v21
	global_store_dword v[226:227], v133, off
	v_cvt_pk_bf16_f32 v133, v25, v29
	global_store_dword v[226:227], v133, off offset:64
	s_mov_b64 s[4:5], 0x300
	v_lshl_add_u64 v[226:227], v[226:227], 0, s[4:5]
	v_cvt_pk_bf16_f32 v133, v18, v22
	global_store_dword v[226:227], v133, off
	v_cvt_pk_bf16_f32 v133, v26, v30
	global_store_dword v[226:227], v133, off offset:64
	s_mov_b64 s[4:5], 0x300
	v_lshl_add_u64 v[226:227], v[226:227], 0, s[4:5]
	v_cvt_pk_bf16_f32 v133, v19, v23
	global_store_dword v[226:227], v133, off
	v_cvt_pk_bf16_f32 v133, v27, v31
	global_store_dword v[226:227], v133, off offset:64
	s_mov_b64 s[4:5], 0x2700
	v_lshl_add_u64 v[226:227], v[226:227], 0, s[4:5]
	v_cvt_pk_bf16_f32 v133, v32, v36
	global_store_dword v[226:227], v133, off
	v_cvt_pk_bf16_f32 v133, v40, v44
	global_store_dword v[226:227], v133, off offset:64
	s_mov_b64 s[4:5], 0x300
	v_lshl_add_u64 v[226:227], v[226:227], 0, s[4:5]
	v_cvt_pk_bf16_f32 v133, v33, v37
	global_store_dword v[226:227], v133, off
	v_cvt_pk_bf16_f32 v133, v41, v45
	global_store_dword v[226:227], v133, off offset:64
	s_mov_b64 s[4:5], 0x300
	v_lshl_add_u64 v[226:227], v[226:227], 0, s[4:5]
	v_cvt_pk_bf16_f32 v133, v34, v38
	global_store_dword v[226:227], v133, off
	v_cvt_pk_bf16_f32 v133, v42, v46
	global_store_dword v[226:227], v133, off offset:64
	s_mov_b64 s[4:5], 0x300
	v_lshl_add_u64 v[226:227], v[226:227], 0, s[4:5]
	v_cvt_pk_bf16_f32 v133, v35, v39
	global_store_dword v[226:227], v133, off
	v_cvt_pk_bf16_f32 v133, v43, v47
	global_store_dword v[226:227], v133, off offset:64
	s_mov_b64 s[4:5], 0x2700
	v_lshl_add_u64 v[226:227], v[226:227], 0, s[4:5]
	v_cvt_pk_bf16_f32 v133, v48, v52
	global_store_dword v[226:227], v133, off
	v_cvt_pk_bf16_f32 v133, v56, v60
	global_store_dword v[226:227], v133, off offset:64
	s_mov_b64 s[4:5], 0x300
	v_lshl_add_u64 v[226:227], v[226:227], 0, s[4:5]
	v_cvt_pk_bf16_f32 v133, v49, v53
	global_store_dword v[226:227], v133, off
	v_cvt_pk_bf16_f32 v133, v57, v61
	global_store_dword v[226:227], v133, off offset:64
	s_mov_b64 s[4:5], 0x300
	v_lshl_add_u64 v[226:227], v[226:227], 0, s[4:5]
	v_cvt_pk_bf16_f32 v133, v50, v54
	global_store_dword v[226:227], v133, off
	v_cvt_pk_bf16_f32 v133, v58, v62
	global_store_dword v[226:227], v133, off offset:64
	s_mov_b64 s[4:5], 0x300
	v_lshl_add_u64 v[226:227], v[226:227], 0, s[4:5]
	v_cvt_pk_bf16_f32 v133, v51, v55
	global_store_dword v[226:227], v133, off
	v_cvt_pk_bf16_f32 v133, v59, v63
	global_store_dword v[226:227], v133, off offset:64
	s_mov_b64 s[4:5], 0x2700
	v_lshl_add_u64 v[226:227], v[226:227], 0, s[4:5]
	v_cvt_pk_bf16_f32 v133, v64, v68
	global_store_dword v[226:227], v133, off
	v_cvt_pk_bf16_f32 v133, v72, v76
	global_store_dword v[226:227], v133, off offset:64
	s_mov_b64 s[4:5], 0x300
	v_lshl_add_u64 v[226:227], v[226:227], 0, s[4:5]
	v_cvt_pk_bf16_f32 v133, v65, v69
	global_store_dword v[226:227], v133, off
	v_cvt_pk_bf16_f32 v133, v73, v77
	global_store_dword v[226:227], v133, off offset:64
	s_mov_b64 s[4:5], 0x300
	v_lshl_add_u64 v[226:227], v[226:227], 0, s[4:5]
	v_cvt_pk_bf16_f32 v133, v66, v70
	global_store_dword v[226:227], v133, off
	v_cvt_pk_bf16_f32 v133, v74, v78
	global_store_dword v[226:227], v133, off offset:64
	s_mov_b64 s[4:5], 0x300
	v_lshl_add_u64 v[226:227], v[226:227], 0, s[4:5]
	v_cvt_pk_bf16_f32 v133, v67, v71
	global_store_dword v[226:227], v133, off
	v_cvt_pk_bf16_f32 v133, v75, v79
	global_store_dword v[226:227], v133, off offset:64
	s_mov_b64 s[4:5], 0x2700
	v_lshl_add_u64 v[226:227], v[226:227], 0, s[4:5]
	v_cvt_pk_bf16_f32 v133, v80, v84
	global_store_dword v[226:227], v133, off
	v_cvt_pk_bf16_f32 v133, v88, v92
	global_store_dword v[226:227], v133, off offset:64
	s_mov_b64 s[4:5], 0x300
	v_lshl_add_u64 v[226:227], v[226:227], 0, s[4:5]
	v_cvt_pk_bf16_f32 v133, v81, v85
	global_store_dword v[226:227], v133, off
	v_cvt_pk_bf16_f32 v133, v89, v93
	global_store_dword v[226:227], v133, off offset:64
	s_mov_b64 s[4:5], 0x300
	v_lshl_add_u64 v[226:227], v[226:227], 0, s[4:5]
	v_cvt_pk_bf16_f32 v133, v82, v86
	global_store_dword v[226:227], v133, off
	v_cvt_pk_bf16_f32 v133, v90, v94
	global_store_dword v[226:227], v133, off offset:64
	s_mov_b64 s[4:5], 0x300
	v_lshl_add_u64 v[226:227], v[226:227], 0, s[4:5]
	v_cvt_pk_bf16_f32 v133, v83, v87
	global_store_dword v[226:227], v133, off
	v_cvt_pk_bf16_f32 v133, v91, v95
	global_store_dword v[226:227], v133, off offset:64
	s_mov_b64 s[4:5], 0x2700
	v_lshl_add_u64 v[226:227], v[226:227], 0, s[4:5]
	v_cvt_pk_bf16_f32 v133, v96, v100
	global_store_dword v[226:227], v133, off
	v_cvt_pk_bf16_f32 v133, v104, v108
	global_store_dword v[226:227], v133, off offset:64
	s_mov_b64 s[4:5], 0x300
	v_lshl_add_u64 v[226:227], v[226:227], 0, s[4:5]
	v_cvt_pk_bf16_f32 v133, v97, v101
	global_store_dword v[226:227], v133, off
	v_cvt_pk_bf16_f32 v133, v105, v109
	global_store_dword v[226:227], v133, off offset:64
	s_mov_b64 s[4:5], 0x300
	v_lshl_add_u64 v[226:227], v[226:227], 0, s[4:5]
	v_cvt_pk_bf16_f32 v133, v98, v102
	global_store_dword v[226:227], v133, off
	v_cvt_pk_bf16_f32 v133, v106, v110
	global_store_dword v[226:227], v133, off offset:64
	s_mov_b64 s[4:5], 0x300
	v_lshl_add_u64 v[226:227], v[226:227], 0, s[4:5]
	v_cvt_pk_bf16_f32 v133, v99, v103
	global_store_dword v[226:227], v133, off
	v_cvt_pk_bf16_f32 v133, v107, v111
	global_store_dword v[226:227], v133, off offset:64
	s_mov_b64 s[4:5], 0x2700
	v_lshl_add_u64 v[226:227], v[226:227], 0, s[4:5]
	v_cvt_pk_bf16_f32 v133, v112, v116
	global_store_dword v[226:227], v133, off
	v_cvt_pk_bf16_f32 v133, v120, v124
	global_store_dword v[226:227], v133, off offset:64
	s_mov_b64 s[4:5], 0x300
	v_lshl_add_u64 v[226:227], v[226:227], 0, s[4:5]
	v_cvt_pk_bf16_f32 v133, v113, v117
	global_store_dword v[226:227], v133, off
	v_cvt_pk_bf16_f32 v133, v121, v125
	global_store_dword v[226:227], v133, off offset:64
	s_mov_b64 s[4:5], 0x300
	v_lshl_add_u64 v[226:227], v[226:227], 0, s[4:5]
	v_cvt_pk_bf16_f32 v133, v114, v118
	global_store_dword v[226:227], v133, off
	v_cvt_pk_bf16_f32 v133, v122, v126
	global_store_dword v[226:227], v133, off offset:64
	s_mov_b64 s[4:5], 0x300
	v_lshl_add_u64 v[226:227], v[226:227], 0, s[4:5]
	v_cvt_pk_bf16_f32 v133, v115, v119
	global_store_dword v[226:227], v133, off
	v_cvt_pk_bf16_f32 v133, v123, v127
	global_store_dword v[226:227], v133, off offset:64
	s_branch .Lip_nolin
.Lip_lin2:
	v_mov_b32_e32 v226, s50
	v_mov_b32_e32 v227, s51
	v_add_co_u32_e32 v226, vcc, v226, v169
	s_nop 1
	v_addc_co_u32_e32 v227, vcc, 0, v227, vcc
	v_mul_f32_e32 v228, 0xbfb8aa3b, v0
	v_exp_f32_e32 v228, v228
	s_nop 0
	v_add_f32_e32 v229, 1.0, v228
	v_div_scale_f32 v230, s[4:5], v229, v229, 1.0
	v_rcp_f32_e32 v231, v230
	v_div_scale_f32 v232, vcc, 1.0, v229, 1.0
	v_fma_f32 v131, -v230, v231, 1.0
	v_fmac_f32_e32 v231, v131, v231
	v_mul_f32_e32 v233, v232, v231
	v_fma_f32 v131, -v230, v233, v232
	v_fmac_f32_e32 v233, v131, v231
	v_fma_f32 v230, -v230, v233, v232
	v_div_fmas_f32 v230, v230, v231, v233
	v_div_fixup_f32 v135, v230, v229, 1.0
	v_mul_f32_e32 v228, 0xbfb8aa3b, v4
	v_exp_f32_e32 v228, v228
	s_nop 0
	v_add_f32_e32 v229, 1.0, v228
	v_div_scale_f32 v230, s[4:5], v229, v229, 1.0
	v_rcp_f32_e32 v231, v230
	v_div_scale_f32 v232, vcc, 1.0, v229, 1.0
	v_fma_f32 v131, -v230, v231, 1.0
	v_fmac_f32_e32 v231, v131, v231
	v_mul_f32_e32 v233, v232, v231
	v_fma_f32 v131, -v230, v233, v232
	v_fmac_f32_e32 v233, v131, v231
	v_fma_f32 v230, -v230, v233, v232
	v_div_fmas_f32 v230, v230, v231, v233
	v_div_fixup_f32 v133, v230, v229, 1.0
	v_cvt_pk_bf16_f32 v133, v135, v133
	global_store_dword v[226:227], v133, off
	v_mul_f32_e32 v228, 0xbfb8aa3b, v8
	v_exp_f32_e32 v228, v228
	s_nop 0
	v_add_f32_e32 v229, 1.0, v228
	v_div_scale_f32 v230, s[4:5], v229, v229, 1.0
	v_rcp_f32_e32 v231, v230
	v_div_scale_f32 v232, vcc, 1.0, v229, 1.0
	v_fma_f32 v131, -v230, v231, 1.0
	v_fmac_f32_e32 v231, v131, v231
	v_mul_f32_e32 v233, v232, v231
	v_fma_f32 v131, -v230, v233, v232
	v_fmac_f32_e32 v233, v131, v231
	v_fma_f32 v230, -v230, v233, v232
	v_div_fmas_f32 v230, v230, v231, v233
	v_div_fixup_f32 v135, v230, v229, 1.0
	v_mul_f32_e32 v228, 0xbfb8aa3b, v12
	v_exp_f32_e32 v228, v228
	s_nop 0
	v_add_f32_e32 v229, 1.0, v228
	v_div_scale_f32 v230, s[4:5], v229, v229, 1.0
	v_rcp_f32_e32 v231, v230
	v_div_scale_f32 v232, vcc, 1.0, v229, 1.0
	v_fma_f32 v131, -v230, v231, 1.0
	v_fmac_f32_e32 v231, v131, v231
	v_mul_f32_e32 v233, v232, v231
	v_fma_f32 v131, -v230, v233, v232
	v_fmac_f32_e32 v233, v131, v231
	v_fma_f32 v230, -v230, v233, v232
	v_div_fmas_f32 v230, v230, v231, v233
	v_div_fixup_f32 v133, v230, v229, 1.0
	v_cvt_pk_bf16_f32 v133, v135, v133
	global_store_dword v[226:227], v133, off offset:64
	s_mov_b64 s[4:5], 0x300
	v_lshl_add_u64 v[226:227], v[226:227], 0, s[4:5]
	v_mul_f32_e32 v228, 0xbfb8aa3b, v1
	v_exp_f32_e32 v228, v228
	s_nop 0
	v_add_f32_e32 v229, 1.0, v228
	v_div_scale_f32 v230, s[4:5], v229, v229, 1.0
	v_rcp_f32_e32 v231, v230
	v_div_scale_f32 v232, vcc, 1.0, v229, 1.0
	v_fma_f32 v131, -v230, v231, 1.0
	v_fmac_f32_e32 v231, v131, v231
	v_mul_f32_e32 v233, v232, v231
	v_fma_f32 v131, -v230, v233, v232
	v_fmac_f32_e32 v233, v131, v231
	v_fma_f32 v230, -v230, v233, v232
	v_div_fmas_f32 v230, v230, v231, v233
	v_div_fixup_f32 v135, v230, v229, 1.0
	v_mul_f32_e32 v228, 0xbfb8aa3b, v5
	v_exp_f32_e32 v228, v228
	s_nop 0
	v_add_f32_e32 v229, 1.0, v228
	v_div_scale_f32 v230, s[4:5], v229, v229, 1.0
	v_rcp_f32_e32 v231, v230
	v_div_scale_f32 v232, vcc, 1.0, v229, 1.0
	v_fma_f32 v131, -v230, v231, 1.0
	v_fmac_f32_e32 v231, v131, v231
	v_mul_f32_e32 v233, v232, v231
	v_fma_f32 v131, -v230, v233, v232
	v_fmac_f32_e32 v233, v131, v231
	v_fma_f32 v230, -v230, v233, v232
	v_div_fmas_f32 v230, v230, v231, v233
	v_div_fixup_f32 v133, v230, v229, 1.0
	v_cvt_pk_bf16_f32 v133, v135, v133
	global_store_dword v[226:227], v133, off
	v_mul_f32_e32 v228, 0xbfb8aa3b, v9
	v_exp_f32_e32 v228, v228
	s_nop 0
	v_add_f32_e32 v229, 1.0, v228
	v_div_scale_f32 v230, s[4:5], v229, v229, 1.0
	v_rcp_f32_e32 v231, v230
	v_div_scale_f32 v232, vcc, 1.0, v229, 1.0
	v_fma_f32 v131, -v230, v231, 1.0
	v_fmac_f32_e32 v231, v131, v231
	v_mul_f32_e32 v233, v232, v231
	v_fma_f32 v131, -v230, v233, v232
	v_fmac_f32_e32 v233, v131, v231
	v_fma_f32 v230, -v230, v233, v232
	v_div_fmas_f32 v230, v230, v231, v233
	v_div_fixup_f32 v135, v230, v229, 1.0
	v_mul_f32_e32 v228, 0xbfb8aa3b, v13
	v_exp_f32_e32 v228, v228
	s_nop 0
	v_add_f32_e32 v229, 1.0, v228
	v_div_scale_f32 v230, s[4:5], v229, v229, 1.0
	v_rcp_f32_e32 v231, v230
	v_div_scale_f32 v232, vcc, 1.0, v229, 1.0
	v_fma_f32 v131, -v230, v231, 1.0
	v_fmac_f32_e32 v231, v131, v231
	v_mul_f32_e32 v233, v232, v231
	v_fma_f32 v131, -v230, v233, v232
	v_fmac_f32_e32 v233, v131, v231
	v_fma_f32 v230, -v230, v233, v232
	v_div_fmas_f32 v230, v230, v231, v233
	v_div_fixup_f32 v133, v230, v229, 1.0
	v_cvt_pk_bf16_f32 v133, v135, v133
	global_store_dword v[226:227], v133, off offset:64
	s_mov_b64 s[4:5], 0x300
	v_lshl_add_u64 v[226:227], v[226:227], 0, s[4:5]
	v_mul_f32_e32 v228, 0xbfb8aa3b, v2
	v_exp_f32_e32 v228, v228
	s_nop 0
	v_add_f32_e32 v229, 1.0, v228
	v_div_scale_f32 v230, s[4:5], v229, v229, 1.0
	v_rcp_f32_e32 v231, v230
	v_div_scale_f32 v232, vcc, 1.0, v229, 1.0
	v_fma_f32 v131, -v230, v231, 1.0
	v_fmac_f32_e32 v231, v131, v231
	v_mul_f32_e32 v233, v232, v231
	v_fma_f32 v131, -v230, v233, v232
	v_fmac_f32_e32 v233, v131, v231
	v_fma_f32 v230, -v230, v233, v232
	v_div_fmas_f32 v230, v230, v231, v233
	v_div_fixup_f32 v135, v230, v229, 1.0
	v_mul_f32_e32 v228, 0xbfb8aa3b, v6
	v_exp_f32_e32 v228, v228
	s_nop 0
	v_add_f32_e32 v229, 1.0, v228
	v_div_scale_f32 v230, s[4:5], v229, v229, 1.0
	v_rcp_f32_e32 v231, v230
	v_div_scale_f32 v232, vcc, 1.0, v229, 1.0
	v_fma_f32 v131, -v230, v231, 1.0
	v_fmac_f32_e32 v231, v131, v231
	v_mul_f32_e32 v233, v232, v231
	v_fma_f32 v131, -v230, v233, v232
	v_fmac_f32_e32 v233, v131, v231
	v_fma_f32 v230, -v230, v233, v232
	v_div_fmas_f32 v230, v230, v231, v233
	v_div_fixup_f32 v133, v230, v229, 1.0
	v_cvt_pk_bf16_f32 v133, v135, v133
	global_store_dword v[226:227], v133, off
	v_mul_f32_e32 v228, 0xbfb8aa3b, v10
	v_exp_f32_e32 v228, v228
	s_nop 0
	v_add_f32_e32 v229, 1.0, v228
	v_div_scale_f32 v230, s[4:5], v229, v229, 1.0
	v_rcp_f32_e32 v231, v230
	v_div_scale_f32 v232, vcc, 1.0, v229, 1.0
	v_fma_f32 v131, -v230, v231, 1.0
	v_fmac_f32_e32 v231, v131, v231
	v_mul_f32_e32 v233, v232, v231
	v_fma_f32 v131, -v230, v233, v232
	v_fmac_f32_e32 v233, v131, v231
	v_fma_f32 v230, -v230, v233, v232
	v_div_fmas_f32 v230, v230, v231, v233
	v_div_fixup_f32 v135, v230, v229, 1.0
	v_mul_f32_e32 v228, 0xbfb8aa3b, v14
	v_exp_f32_e32 v228, v228
	s_nop 0
	v_add_f32_e32 v229, 1.0, v228
	v_div_scale_f32 v230, s[4:5], v229, v229, 1.0
	v_rcp_f32_e32 v231, v230
	v_div_scale_f32 v232, vcc, 1.0, v229, 1.0
	v_fma_f32 v131, -v230, v231, 1.0
	v_fmac_f32_e32 v231, v131, v231
	v_mul_f32_e32 v233, v232, v231
	v_fma_f32 v131, -v230, v233, v232
	v_fmac_f32_e32 v233, v131, v231
	v_fma_f32 v230, -v230, v233, v232
	v_div_fmas_f32 v230, v230, v231, v233
	v_div_fixup_f32 v133, v230, v229, 1.0
	v_cvt_pk_bf16_f32 v133, v135, v133
	global_store_dword v[226:227], v133, off offset:64
	s_mov_b64 s[4:5], 0x300
	v_lshl_add_u64 v[226:227], v[226:227], 0, s[4:5]
	v_mul_f32_e32 v228, 0xbfb8aa3b, v3
	v_exp_f32_e32 v228, v228
	s_nop 0
	v_add_f32_e32 v229, 1.0, v228
	v_div_scale_f32 v230, s[4:5], v229, v229, 1.0
	v_rcp_f32_e32 v231, v230
	v_div_scale_f32 v232, vcc, 1.0, v229, 1.0
	v_fma_f32 v131, -v230, v231, 1.0
	v_fmac_f32_e32 v231, v131, v231
	v_mul_f32_e32 v233, v232, v231
	v_fma_f32 v131, -v230, v233, v232
	v_fmac_f32_e32 v233, v131, v231
	v_fma_f32 v230, -v230, v233, v232
	v_div_fmas_f32 v230, v230, v231, v233
	v_div_fixup_f32 v135, v230, v229, 1.0
	v_mul_f32_e32 v228, 0xbfb8aa3b, v7
	v_exp_f32_e32 v228, v228
	s_nop 0
	v_add_f32_e32 v229, 1.0, v228
	v_div_scale_f32 v230, s[4:5], v229, v229, 1.0
	v_rcp_f32_e32 v231, v230
	v_div_scale_f32 v232, vcc, 1.0, v229, 1.0
	v_fma_f32 v131, -v230, v231, 1.0
	v_fmac_f32_e32 v231, v131, v231
	v_mul_f32_e32 v233, v232, v231
	v_fma_f32 v131, -v230, v233, v232
	v_fmac_f32_e32 v233, v131, v231
	v_fma_f32 v230, -v230, v233, v232
	v_div_fmas_f32 v230, v230, v231, v233
	v_div_fixup_f32 v133, v230, v229, 1.0
	v_cvt_pk_bf16_f32 v133, v135, v133
	global_store_dword v[226:227], v133, off
	v_mul_f32_e32 v228, 0xbfb8aa3b, v11
	v_exp_f32_e32 v228, v228
	s_nop 0
	v_add_f32_e32 v229, 1.0, v228
	v_div_scale_f32 v230, s[4:5], v229, v229, 1.0
	v_rcp_f32_e32 v231, v230
	v_div_scale_f32 v232, vcc, 1.0, v229, 1.0
	v_fma_f32 v131, -v230, v231, 1.0
	v_fmac_f32_e32 v231, v131, v231
	v_mul_f32_e32 v233, v232, v231
	v_fma_f32 v131, -v230, v233, v232
	v_fmac_f32_e32 v233, v131, v231
	v_fma_f32 v230, -v230, v233, v232
	v_div_fmas_f32 v230, v230, v231, v233
	v_div_fixup_f32 v135, v230, v229, 1.0
	v_mul_f32_e32 v228, 0xbfb8aa3b, v15
	v_exp_f32_e32 v228, v228
	s_nop 0
	v_add_f32_e32 v229, 1.0, v228
	v_div_scale_f32 v230, s[4:5], v229, v229, 1.0
	v_rcp_f32_e32 v231, v230
	v_div_scale_f32 v232, vcc, 1.0, v229, 1.0
	v_fma_f32 v131, -v230, v231, 1.0
	v_fmac_f32_e32 v231, v131, v231
	v_mul_f32_e32 v233, v232, v231
	v_fma_f32 v131, -v230, v233, v232
	v_fmac_f32_e32 v233, v131, v231
	v_fma_f32 v230, -v230, v233, v232
	v_div_fmas_f32 v230, v230, v231, v233
	v_div_fixup_f32 v133, v230, v229, 1.0
	v_cvt_pk_bf16_f32 v133, v135, v133
	global_store_dword v[226:227], v133, off offset:64
	s_mov_b64 s[4:5], 0x2700
	v_lshl_add_u64 v[226:227], v[226:227], 0, s[4:5]
	v_mul_f32_e32 v228, 0xbfb8aa3b, v16
	v_exp_f32_e32 v228, v228
	s_nop 0
	v_add_f32_e32 v229, 1.0, v228
	v_div_scale_f32 v230, s[4:5], v229, v229, 1.0
	v_rcp_f32_e32 v231, v230
	v_div_scale_f32 v232, vcc, 1.0, v229, 1.0
	v_fma_f32 v131, -v230, v231, 1.0
	v_fmac_f32_e32 v231, v131, v231
	v_mul_f32_e32 v233, v232, v231
	v_fma_f32 v131, -v230, v233, v232
	v_fmac_f32_e32 v233, v131, v231
	v_fma_f32 v230, -v230, v233, v232
	v_div_fmas_f32 v230, v230, v231, v233
	v_div_fixup_f32 v135, v230, v229, 1.0
	v_mul_f32_e32 v228, 0xbfb8aa3b, v20
	v_exp_f32_e32 v228, v228
	s_nop 0
	v_add_f32_e32 v229, 1.0, v228
	v_div_scale_f32 v230, s[4:5], v229, v229, 1.0
	v_rcp_f32_e32 v231, v230
	v_div_scale_f32 v232, vcc, 1.0, v229, 1.0
	v_fma_f32 v131, -v230, v231, 1.0
	v_fmac_f32_e32 v231, v131, v231
	v_mul_f32_e32 v233, v232, v231
	v_fma_f32 v131, -v230, v233, v232
	v_fmac_f32_e32 v233, v131, v231
	v_fma_f32 v230, -v230, v233, v232
	v_div_fmas_f32 v230, v230, v231, v233
	v_div_fixup_f32 v133, v230, v229, 1.0
	v_cvt_pk_bf16_f32 v133, v135, v133
	global_store_dword v[226:227], v133, off
	v_mul_f32_e32 v228, 0xbfb8aa3b, v24
	v_exp_f32_e32 v228, v228
	s_nop 0
	v_add_f32_e32 v229, 1.0, v228
	v_div_scale_f32 v230, s[4:5], v229, v229, 1.0
	v_rcp_f32_e32 v231, v230
	v_div_scale_f32 v232, vcc, 1.0, v229, 1.0
	v_fma_f32 v131, -v230, v231, 1.0
	v_fmac_f32_e32 v231, v131, v231
	v_mul_f32_e32 v233, v232, v231
	v_fma_f32 v131, -v230, v233, v232
	v_fmac_f32_e32 v233, v131, v231
	v_fma_f32 v230, -v230, v233, v232
	v_div_fmas_f32 v230, v230, v231, v233
	v_div_fixup_f32 v135, v230, v229, 1.0
	v_mul_f32_e32 v228, 0xbfb8aa3b, v28
	v_exp_f32_e32 v228, v228
	s_nop 0
	v_add_f32_e32 v229, 1.0, v228
	v_div_scale_f32 v230, s[4:5], v229, v229, 1.0
	v_rcp_f32_e32 v231, v230
	v_div_scale_f32 v232, vcc, 1.0, v229, 1.0
	v_fma_f32 v131, -v230, v231, 1.0
	v_fmac_f32_e32 v231, v131, v231
	v_mul_f32_e32 v233, v232, v231
	v_fma_f32 v131, -v230, v233, v232
	v_fmac_f32_e32 v233, v131, v231
	v_fma_f32 v230, -v230, v233, v232
	v_div_fmas_f32 v230, v230, v231, v233
	v_div_fixup_f32 v133, v230, v229, 1.0
	v_cvt_pk_bf16_f32 v133, v135, v133
	global_store_dword v[226:227], v133, off offset:64
	s_mov_b64 s[4:5], 0x300
	v_lshl_add_u64 v[226:227], v[226:227], 0, s[4:5]
	v_mul_f32_e32 v228, 0xbfb8aa3b, v17
	v_exp_f32_e32 v228, v228
	s_nop 0
	v_add_f32_e32 v229, 1.0, v228
	v_div_scale_f32 v230, s[4:5], v229, v229, 1.0
	v_rcp_f32_e32 v231, v230
	v_div_scale_f32 v232, vcc, 1.0, v229, 1.0
	v_fma_f32 v131, -v230, v231, 1.0
	v_fmac_f32_e32 v231, v131, v231
	v_mul_f32_e32 v233, v232, v231
	v_fma_f32 v131, -v230, v233, v232
	v_fmac_f32_e32 v233, v131, v231
	v_fma_f32 v230, -v230, v233, v232
	v_div_fmas_f32 v230, v230, v231, v233
	v_div_fixup_f32 v135, v230, v229, 1.0
	v_mul_f32_e32 v228, 0xbfb8aa3b, v21
	v_exp_f32_e32 v228, v228
	s_nop 0
	v_add_f32_e32 v229, 1.0, v228
	v_div_scale_f32 v230, s[4:5], v229, v229, 1.0
	v_rcp_f32_e32 v231, v230
	v_div_scale_f32 v232, vcc, 1.0, v229, 1.0
	v_fma_f32 v131, -v230, v231, 1.0
	v_fmac_f32_e32 v231, v131, v231
	v_mul_f32_e32 v233, v232, v231
	v_fma_f32 v131, -v230, v233, v232
	v_fmac_f32_e32 v233, v131, v231
	v_fma_f32 v230, -v230, v233, v232
	v_div_fmas_f32 v230, v230, v231, v233
	v_div_fixup_f32 v133, v230, v229, 1.0
	v_cvt_pk_bf16_f32 v133, v135, v133
	global_store_dword v[226:227], v133, off
	v_mul_f32_e32 v228, 0xbfb8aa3b, v25
	v_exp_f32_e32 v228, v228
	s_nop 0
	v_add_f32_e32 v229, 1.0, v228
	v_div_scale_f32 v230, s[4:5], v229, v229, 1.0
	v_rcp_f32_e32 v231, v230
	v_div_scale_f32 v232, vcc, 1.0, v229, 1.0
	v_fma_f32 v131, -v230, v231, 1.0
	v_fmac_f32_e32 v231, v131, v231
	v_mul_f32_e32 v233, v232, v231
	v_fma_f32 v131, -v230, v233, v232
	v_fmac_f32_e32 v233, v131, v231
	v_fma_f32 v230, -v230, v233, v232
	v_div_fmas_f32 v230, v230, v231, v233
	v_div_fixup_f32 v135, v230, v229, 1.0
	v_mul_f32_e32 v228, 0xbfb8aa3b, v29
	v_exp_f32_e32 v228, v228
	s_nop 0
	v_add_f32_e32 v229, 1.0, v228
	v_div_scale_f32 v230, s[4:5], v229, v229, 1.0
	v_rcp_f32_e32 v231, v230
	v_div_scale_f32 v232, vcc, 1.0, v229, 1.0
	v_fma_f32 v131, -v230, v231, 1.0
	v_fmac_f32_e32 v231, v131, v231
	v_mul_f32_e32 v233, v232, v231
	v_fma_f32 v131, -v230, v233, v232
	v_fmac_f32_e32 v233, v131, v231
	v_fma_f32 v230, -v230, v233, v232
	v_div_fmas_f32 v230, v230, v231, v233
	v_div_fixup_f32 v133, v230, v229, 1.0
	v_cvt_pk_bf16_f32 v133, v135, v133
	global_store_dword v[226:227], v133, off offset:64
	s_mov_b64 s[4:5], 0x300
	v_lshl_add_u64 v[226:227], v[226:227], 0, s[4:5]
	v_mul_f32_e32 v228, 0xbfb8aa3b, v18
	v_exp_f32_e32 v228, v228
	s_nop 0
	v_add_f32_e32 v229, 1.0, v228
	v_div_scale_f32 v230, s[4:5], v229, v229, 1.0
	v_rcp_f32_e32 v231, v230
	v_div_scale_f32 v232, vcc, 1.0, v229, 1.0
	v_fma_f32 v131, -v230, v231, 1.0
	v_fmac_f32_e32 v231, v131, v231
	v_mul_f32_e32 v233, v232, v231
	v_fma_f32 v131, -v230, v233, v232
	v_fmac_f32_e32 v233, v131, v231
	v_fma_f32 v230, -v230, v233, v232
	v_div_fmas_f32 v230, v230, v231, v233
	v_div_fixup_f32 v135, v230, v229, 1.0
	v_mul_f32_e32 v228, 0xbfb8aa3b, v22
	v_exp_f32_e32 v228, v228
	s_nop 0
	v_add_f32_e32 v229, 1.0, v228
	v_div_scale_f32 v230, s[4:5], v229, v229, 1.0
	v_rcp_f32_e32 v231, v230
	v_div_scale_f32 v232, vcc, 1.0, v229, 1.0
	v_fma_f32 v131, -v230, v231, 1.0
	v_fmac_f32_e32 v231, v131, v231
	v_mul_f32_e32 v233, v232, v231
	v_fma_f32 v131, -v230, v233, v232
	v_fmac_f32_e32 v233, v131, v231
	v_fma_f32 v230, -v230, v233, v232
	v_div_fmas_f32 v230, v230, v231, v233
	v_div_fixup_f32 v133, v230, v229, 1.0
	v_cvt_pk_bf16_f32 v133, v135, v133
	global_store_dword v[226:227], v133, off
	v_mul_f32_e32 v228, 0xbfb8aa3b, v26
	v_exp_f32_e32 v228, v228
	s_nop 0
	v_add_f32_e32 v229, 1.0, v228
	v_div_scale_f32 v230, s[4:5], v229, v229, 1.0
	v_rcp_f32_e32 v231, v230
	v_div_scale_f32 v232, vcc, 1.0, v229, 1.0
	v_fma_f32 v131, -v230, v231, 1.0
	v_fmac_f32_e32 v231, v131, v231
	v_mul_f32_e32 v233, v232, v231
	v_fma_f32 v131, -v230, v233, v232
	v_fmac_f32_e32 v233, v131, v231
	v_fma_f32 v230, -v230, v233, v232
	v_div_fmas_f32 v230, v230, v231, v233
	v_div_fixup_f32 v135, v230, v229, 1.0
	v_mul_f32_e32 v228, 0xbfb8aa3b, v30
	v_exp_f32_e32 v228, v228
	s_nop 0
	v_add_f32_e32 v229, 1.0, v228
	v_div_scale_f32 v230, s[4:5], v229, v229, 1.0
	v_rcp_f32_e32 v231, v230
	v_div_scale_f32 v232, vcc, 1.0, v229, 1.0
	v_fma_f32 v131, -v230, v231, 1.0
	v_fmac_f32_e32 v231, v131, v231
	v_mul_f32_e32 v233, v232, v231
	v_fma_f32 v131, -v230, v233, v232
	v_fmac_f32_e32 v233, v131, v231
	v_fma_f32 v230, -v230, v233, v232
	v_div_fmas_f32 v230, v230, v231, v233
	v_div_fixup_f32 v133, v230, v229, 1.0
	v_cvt_pk_bf16_f32 v133, v135, v133
	global_store_dword v[226:227], v133, off offset:64
	s_mov_b64 s[4:5], 0x300
	v_lshl_add_u64 v[226:227], v[226:227], 0, s[4:5]
	v_mul_f32_e32 v228, 0xbfb8aa3b, v19
	v_exp_f32_e32 v228, v228
	s_nop 0
	v_add_f32_e32 v229, 1.0, v228
	v_div_scale_f32 v230, s[4:5], v229, v229, 1.0
	v_rcp_f32_e32 v231, v230
	v_div_scale_f32 v232, vcc, 1.0, v229, 1.0
	v_fma_f32 v131, -v230, v231, 1.0
	v_fmac_f32_e32 v231, v131, v231
	v_mul_f32_e32 v233, v232, v231
	v_fma_f32 v131, -v230, v233, v232
	v_fmac_f32_e32 v233, v131, v231
	v_fma_f32 v230, -v230, v233, v232
	v_div_fmas_f32 v230, v230, v231, v233
	v_div_fixup_f32 v135, v230, v229, 1.0
	v_mul_f32_e32 v228, 0xbfb8aa3b, v23
	v_exp_f32_e32 v228, v228
	s_nop 0
	v_add_f32_e32 v229, 1.0, v228
	v_div_scale_f32 v230, s[4:5], v229, v229, 1.0
	v_rcp_f32_e32 v231, v230
	v_div_scale_f32 v232, vcc, 1.0, v229, 1.0
	v_fma_f32 v131, -v230, v231, 1.0
	v_fmac_f32_e32 v231, v131, v231
	v_mul_f32_e32 v233, v232, v231
	v_fma_f32 v131, -v230, v233, v232
	v_fmac_f32_e32 v233, v131, v231
	v_fma_f32 v230, -v230, v233, v232
	v_div_fmas_f32 v230, v230, v231, v233
	v_div_fixup_f32 v133, v230, v229, 1.0
	v_cvt_pk_bf16_f32 v133, v135, v133
	global_store_dword v[226:227], v133, off
	v_mul_f32_e32 v228, 0xbfb8aa3b, v27
	v_exp_f32_e32 v228, v228
	s_nop 0
	v_add_f32_e32 v229, 1.0, v228
	v_div_scale_f32 v230, s[4:5], v229, v229, 1.0
	v_rcp_f32_e32 v231, v230
	v_div_scale_f32 v232, vcc, 1.0, v229, 1.0
	v_fma_f32 v131, -v230, v231, 1.0
	v_fmac_f32_e32 v231, v131, v231
	v_mul_f32_e32 v233, v232, v231
	v_fma_f32 v131, -v230, v233, v232
	v_fmac_f32_e32 v233, v131, v231
	v_fma_f32 v230, -v230, v233, v232
	v_div_fmas_f32 v230, v230, v231, v233
	v_div_fixup_f32 v135, v230, v229, 1.0
	v_mul_f32_e32 v228, 0xbfb8aa3b, v31
	v_exp_f32_e32 v228, v228
	s_nop 0
	v_add_f32_e32 v229, 1.0, v228
	v_div_scale_f32 v230, s[4:5], v229, v229, 1.0
	v_rcp_f32_e32 v231, v230
	v_div_scale_f32 v232, vcc, 1.0, v229, 1.0
	v_fma_f32 v131, -v230, v231, 1.0
	v_fmac_f32_e32 v231, v131, v231
	v_mul_f32_e32 v233, v232, v231
	v_fma_f32 v131, -v230, v233, v232
	v_fmac_f32_e32 v233, v131, v231
	v_fma_f32 v230, -v230, v233, v232
	v_div_fmas_f32 v230, v230, v231, v233
	v_div_fixup_f32 v133, v230, v229, 1.0
	v_cvt_pk_bf16_f32 v133, v135, v133
	global_store_dword v[226:227], v133, off offset:64
	s_mov_b64 s[4:5], 0x2700
	v_lshl_add_u64 v[226:227], v[226:227], 0, s[4:5]
	v_mul_f32_e32 v228, 0xbfb8aa3b, v32
	v_exp_f32_e32 v228, v228
	s_nop 0
	v_add_f32_e32 v229, 1.0, v228
	v_div_scale_f32 v230, s[4:5], v229, v229, 1.0
	v_rcp_f32_e32 v231, v230
	v_div_scale_f32 v232, vcc, 1.0, v229, 1.0
	v_fma_f32 v131, -v230, v231, 1.0
	v_fmac_f32_e32 v231, v131, v231
	v_mul_f32_e32 v233, v232, v231
	v_fma_f32 v131, -v230, v233, v232
	v_fmac_f32_e32 v233, v131, v231
	v_fma_f32 v230, -v230, v233, v232
	v_div_fmas_f32 v230, v230, v231, v233
	v_div_fixup_f32 v135, v230, v229, 1.0
	v_mul_f32_e32 v228, 0xbfb8aa3b, v36
	v_exp_f32_e32 v228, v228
	s_nop 0
	v_add_f32_e32 v229, 1.0, v228
	v_div_scale_f32 v230, s[4:5], v229, v229, 1.0
	v_rcp_f32_e32 v231, v230
	v_div_scale_f32 v232, vcc, 1.0, v229, 1.0
	v_fma_f32 v131, -v230, v231, 1.0
	v_fmac_f32_e32 v231, v131, v231
	v_mul_f32_e32 v233, v232, v231
	v_fma_f32 v131, -v230, v233, v232
	v_fmac_f32_e32 v233, v131, v231
	v_fma_f32 v230, -v230, v233, v232
	v_div_fmas_f32 v230, v230, v231, v233
	v_div_fixup_f32 v133, v230, v229, 1.0
	v_cvt_pk_bf16_f32 v133, v135, v133
	global_store_dword v[226:227], v133, off
	v_mul_f32_e32 v228, 0xbfb8aa3b, v40
	v_exp_f32_e32 v228, v228
	s_nop 0
	v_add_f32_e32 v229, 1.0, v228
	v_div_scale_f32 v230, s[4:5], v229, v229, 1.0
	v_rcp_f32_e32 v231, v230
	v_div_scale_f32 v232, vcc, 1.0, v229, 1.0
	v_fma_f32 v131, -v230, v231, 1.0
	v_fmac_f32_e32 v231, v131, v231
	v_mul_f32_e32 v233, v232, v231
	v_fma_f32 v131, -v230, v233, v232
	v_fmac_f32_e32 v233, v131, v231
	v_fma_f32 v230, -v230, v233, v232
	v_div_fmas_f32 v230, v230, v231, v233
	v_div_fixup_f32 v135, v230, v229, 1.0
	v_mul_f32_e32 v228, 0xbfb8aa3b, v44
	v_exp_f32_e32 v228, v228
	s_nop 0
	v_add_f32_e32 v229, 1.0, v228
	v_div_scale_f32 v230, s[4:5], v229, v229, 1.0
	v_rcp_f32_e32 v231, v230
	v_div_scale_f32 v232, vcc, 1.0, v229, 1.0
	v_fma_f32 v131, -v230, v231, 1.0
	v_fmac_f32_e32 v231, v131, v231
	v_mul_f32_e32 v233, v232, v231
	v_fma_f32 v131, -v230, v233, v232
	v_fmac_f32_e32 v233, v131, v231
	v_fma_f32 v230, -v230, v233, v232
	v_div_fmas_f32 v230, v230, v231, v233
	v_div_fixup_f32 v133, v230, v229, 1.0
	v_cvt_pk_bf16_f32 v133, v135, v133
	global_store_dword v[226:227], v133, off offset:64
	s_mov_b64 s[4:5], 0x300
	v_lshl_add_u64 v[226:227], v[226:227], 0, s[4:5]
	v_mul_f32_e32 v228, 0xbfb8aa3b, v33
	v_exp_f32_e32 v228, v228
	s_nop 0
	v_add_f32_e32 v229, 1.0, v228
	v_div_scale_f32 v230, s[4:5], v229, v229, 1.0
	v_rcp_f32_e32 v231, v230
	v_div_scale_f32 v232, vcc, 1.0, v229, 1.0
	v_fma_f32 v131, -v230, v231, 1.0
	v_fmac_f32_e32 v231, v131, v231
	v_mul_f32_e32 v233, v232, v231
	v_fma_f32 v131, -v230, v233, v232
	v_fmac_f32_e32 v233, v131, v231
	v_fma_f32 v230, -v230, v233, v232
	v_div_fmas_f32 v230, v230, v231, v233
	v_div_fixup_f32 v135, v230, v229, 1.0
	v_mul_f32_e32 v228, 0xbfb8aa3b, v37
	v_exp_f32_e32 v228, v228
	s_nop 0
	v_add_f32_e32 v229, 1.0, v228
	v_div_scale_f32 v230, s[4:5], v229, v229, 1.0
	v_rcp_f32_e32 v231, v230
	v_div_scale_f32 v232, vcc, 1.0, v229, 1.0
	v_fma_f32 v131, -v230, v231, 1.0
	v_fmac_f32_e32 v231, v131, v231
	v_mul_f32_e32 v233, v232, v231
	v_fma_f32 v131, -v230, v233, v232
	v_fmac_f32_e32 v233, v131, v231
	v_fma_f32 v230, -v230, v233, v232
	v_div_fmas_f32 v230, v230, v231, v233
	v_div_fixup_f32 v133, v230, v229, 1.0
	v_cvt_pk_bf16_f32 v133, v135, v133
	global_store_dword v[226:227], v133, off
	v_mul_f32_e32 v228, 0xbfb8aa3b, v41
	v_exp_f32_e32 v228, v228
	s_nop 0
	v_add_f32_e32 v229, 1.0, v228
	v_div_scale_f32 v230, s[4:5], v229, v229, 1.0
	v_rcp_f32_e32 v231, v230
	v_div_scale_f32 v232, vcc, 1.0, v229, 1.0
	v_fma_f32 v131, -v230, v231, 1.0
	v_fmac_f32_e32 v231, v131, v231
	v_mul_f32_e32 v233, v232, v231
	v_fma_f32 v131, -v230, v233, v232
	v_fmac_f32_e32 v233, v131, v231
	v_fma_f32 v230, -v230, v233, v232
	v_div_fmas_f32 v230, v230, v231, v233
	v_div_fixup_f32 v135, v230, v229, 1.0
	v_mul_f32_e32 v228, 0xbfb8aa3b, v45
	v_exp_f32_e32 v228, v228
	s_nop 0
	v_add_f32_e32 v229, 1.0, v228
	v_div_scale_f32 v230, s[4:5], v229, v229, 1.0
	v_rcp_f32_e32 v231, v230
	v_div_scale_f32 v232, vcc, 1.0, v229, 1.0
	v_fma_f32 v131, -v230, v231, 1.0
	v_fmac_f32_e32 v231, v131, v231
	v_mul_f32_e32 v233, v232, v231
	v_fma_f32 v131, -v230, v233, v232
	v_fmac_f32_e32 v233, v131, v231
	v_fma_f32 v230, -v230, v233, v232
	v_div_fmas_f32 v230, v230, v231, v233
	v_div_fixup_f32 v133, v230, v229, 1.0
	v_cvt_pk_bf16_f32 v133, v135, v133
	global_store_dword v[226:227], v133, off offset:64
	s_mov_b64 s[4:5], 0x300
	v_lshl_add_u64 v[226:227], v[226:227], 0, s[4:5]
	v_mul_f32_e32 v228, 0xbfb8aa3b, v34
	v_exp_f32_e32 v228, v228
	s_nop 0
	v_add_f32_e32 v229, 1.0, v228
	v_div_scale_f32 v230, s[4:5], v229, v229, 1.0
	v_rcp_f32_e32 v231, v230
	v_div_scale_f32 v232, vcc, 1.0, v229, 1.0
	v_fma_f32 v131, -v230, v231, 1.0
	v_fmac_f32_e32 v231, v131, v231
	v_mul_f32_e32 v233, v232, v231
	v_fma_f32 v131, -v230, v233, v232
	v_fmac_f32_e32 v233, v131, v231
	v_fma_f32 v230, -v230, v233, v232
	v_div_fmas_f32 v230, v230, v231, v233
	v_div_fixup_f32 v135, v230, v229, 1.0
	v_mul_f32_e32 v228, 0xbfb8aa3b, v38
	v_exp_f32_e32 v228, v228
	s_nop 0
	v_add_f32_e32 v229, 1.0, v228
	v_div_scale_f32 v230, s[4:5], v229, v229, 1.0
	v_rcp_f32_e32 v231, v230
	v_div_scale_f32 v232, vcc, 1.0, v229, 1.0
	v_fma_f32 v131, -v230, v231, 1.0
	v_fmac_f32_e32 v231, v131, v231
	v_mul_f32_e32 v233, v232, v231
	v_fma_f32 v131, -v230, v233, v232
	v_fmac_f32_e32 v233, v131, v231
	v_fma_f32 v230, -v230, v233, v232
	v_div_fmas_f32 v230, v230, v231, v233
	v_div_fixup_f32 v133, v230, v229, 1.0
	v_cvt_pk_bf16_f32 v133, v135, v133
	global_store_dword v[226:227], v133, off
	v_mul_f32_e32 v228, 0xbfb8aa3b, v42
	v_exp_f32_e32 v228, v228
	s_nop 0
	v_add_f32_e32 v229, 1.0, v228
	v_div_scale_f32 v230, s[4:5], v229, v229, 1.0
	v_rcp_f32_e32 v231, v230
	v_div_scale_f32 v232, vcc, 1.0, v229, 1.0
	v_fma_f32 v131, -v230, v231, 1.0
	v_fmac_f32_e32 v231, v131, v231
	v_mul_f32_e32 v233, v232, v231
	v_fma_f32 v131, -v230, v233, v232
	v_fmac_f32_e32 v233, v131, v231
	v_fma_f32 v230, -v230, v233, v232
	v_div_fmas_f32 v230, v230, v231, v233
	v_div_fixup_f32 v135, v230, v229, 1.0
	v_mul_f32_e32 v228, 0xbfb8aa3b, v46
	v_exp_f32_e32 v228, v228
	s_nop 0
	v_add_f32_e32 v229, 1.0, v228
	v_div_scale_f32 v230, s[4:5], v229, v229, 1.0
	v_rcp_f32_e32 v231, v230
	v_div_scale_f32 v232, vcc, 1.0, v229, 1.0
	v_fma_f32 v131, -v230, v231, 1.0
	v_fmac_f32_e32 v231, v131, v231
	v_mul_f32_e32 v233, v232, v231
	v_fma_f32 v131, -v230, v233, v232
	v_fmac_f32_e32 v233, v131, v231
	v_fma_f32 v230, -v230, v233, v232
	v_div_fmas_f32 v230, v230, v231, v233
	v_div_fixup_f32 v133, v230, v229, 1.0
	v_cvt_pk_bf16_f32 v133, v135, v133
	global_store_dword v[226:227], v133, off offset:64
	s_mov_b64 s[4:5], 0x300
	v_lshl_add_u64 v[226:227], v[226:227], 0, s[4:5]
	v_mul_f32_e32 v228, 0xbfb8aa3b, v35
	v_exp_f32_e32 v228, v228
	s_nop 0
	v_add_f32_e32 v229, 1.0, v228
	v_div_scale_f32 v230, s[4:5], v229, v229, 1.0
	v_rcp_f32_e32 v231, v230
	v_div_scale_f32 v232, vcc, 1.0, v229, 1.0
	v_fma_f32 v131, -v230, v231, 1.0
	v_fmac_f32_e32 v231, v131, v231
	v_mul_f32_e32 v233, v232, v231
	v_fma_f32 v131, -v230, v233, v232
	v_fmac_f32_e32 v233, v131, v231
	v_fma_f32 v230, -v230, v233, v232
	v_div_fmas_f32 v230, v230, v231, v233
	v_div_fixup_f32 v135, v230, v229, 1.0
	v_mul_f32_e32 v228, 0xbfb8aa3b, v39
	v_exp_f32_e32 v228, v228
	s_nop 0
	v_add_f32_e32 v229, 1.0, v228
	v_div_scale_f32 v230, s[4:5], v229, v229, 1.0
	v_rcp_f32_e32 v231, v230
	v_div_scale_f32 v232, vcc, 1.0, v229, 1.0
	v_fma_f32 v131, -v230, v231, 1.0
	v_fmac_f32_e32 v231, v131, v231
	v_mul_f32_e32 v233, v232, v231
	v_fma_f32 v131, -v230, v233, v232
	v_fmac_f32_e32 v233, v131, v231
	v_fma_f32 v230, -v230, v233, v232
	v_div_fmas_f32 v230, v230, v231, v233
	v_div_fixup_f32 v133, v230, v229, 1.0
	v_cvt_pk_bf16_f32 v133, v135, v133
	global_store_dword v[226:227], v133, off
	v_mul_f32_e32 v228, 0xbfb8aa3b, v43
	v_exp_f32_e32 v228, v228
	s_nop 0
	v_add_f32_e32 v229, 1.0, v228
	v_div_scale_f32 v230, s[4:5], v229, v229, 1.0
	v_rcp_f32_e32 v231, v230
	v_div_scale_f32 v232, vcc, 1.0, v229, 1.0
	v_fma_f32 v131, -v230, v231, 1.0
	v_fmac_f32_e32 v231, v131, v231
	v_mul_f32_e32 v233, v232, v231
	v_fma_f32 v131, -v230, v233, v232
	v_fmac_f32_e32 v233, v131, v231
	v_fma_f32 v230, -v230, v233, v232
	v_div_fmas_f32 v230, v230, v231, v233
	v_div_fixup_f32 v135, v230, v229, 1.0
	v_mul_f32_e32 v228, 0xbfb8aa3b, v47
	v_exp_f32_e32 v228, v228
	s_nop 0
	v_add_f32_e32 v229, 1.0, v228
	v_div_scale_f32 v230, s[4:5], v229, v229, 1.0
	v_rcp_f32_e32 v231, v230
	v_div_scale_f32 v232, vcc, 1.0, v229, 1.0
	v_fma_f32 v131, -v230, v231, 1.0
	v_fmac_f32_e32 v231, v131, v231
	v_mul_f32_e32 v233, v232, v231
	v_fma_f32 v131, -v230, v233, v232
	v_fmac_f32_e32 v233, v131, v231
	v_fma_f32 v230, -v230, v233, v232
	v_div_fmas_f32 v230, v230, v231, v233
	v_div_fixup_f32 v133, v230, v229, 1.0
	v_cvt_pk_bf16_f32 v133, v135, v133
	global_store_dword v[226:227], v133, off offset:64
	s_mov_b64 s[4:5], 0x2700
	v_lshl_add_u64 v[226:227], v[226:227], 0, s[4:5]
	v_mul_f32_e32 v228, 0xbfb8aa3b, v48
	v_exp_f32_e32 v228, v228
	s_nop 0
	v_add_f32_e32 v229, 1.0, v228
	v_div_scale_f32 v230, s[4:5], v229, v229, 1.0
	v_rcp_f32_e32 v231, v230
	v_div_scale_f32 v232, vcc, 1.0, v229, 1.0
	v_fma_f32 v131, -v230, v231, 1.0
	v_fmac_f32_e32 v231, v131, v231
	v_mul_f32_e32 v233, v232, v231
	v_fma_f32 v131, -v230, v233, v232
	v_fmac_f32_e32 v233, v131, v231
	v_fma_f32 v230, -v230, v233, v232
	v_div_fmas_f32 v230, v230, v231, v233
	v_div_fixup_f32 v135, v230, v229, 1.0
	v_mul_f32_e32 v228, 0xbfb8aa3b, v52
	v_exp_f32_e32 v228, v228
	s_nop 0
	v_add_f32_e32 v229, 1.0, v228
	v_div_scale_f32 v230, s[4:5], v229, v229, 1.0
	v_rcp_f32_e32 v231, v230
	v_div_scale_f32 v232, vcc, 1.0, v229, 1.0
	v_fma_f32 v131, -v230, v231, 1.0
	v_fmac_f32_e32 v231, v131, v231
	v_mul_f32_e32 v233, v232, v231
	v_fma_f32 v131, -v230, v233, v232
	v_fmac_f32_e32 v233, v131, v231
	v_fma_f32 v230, -v230, v233, v232
	v_div_fmas_f32 v230, v230, v231, v233
	v_div_fixup_f32 v133, v230, v229, 1.0
	v_cvt_pk_bf16_f32 v133, v135, v133
	global_store_dword v[226:227], v133, off
	v_mul_f32_e32 v228, 0xbfb8aa3b, v56
	v_exp_f32_e32 v228, v228
	s_nop 0
	v_add_f32_e32 v229, 1.0, v228
	v_div_scale_f32 v230, s[4:5], v229, v229, 1.0
	v_rcp_f32_e32 v231, v230
	v_div_scale_f32 v232, vcc, 1.0, v229, 1.0
	v_fma_f32 v131, -v230, v231, 1.0
	v_fmac_f32_e32 v231, v131, v231
	v_mul_f32_e32 v233, v232, v231
	v_fma_f32 v131, -v230, v233, v232
	v_fmac_f32_e32 v233, v131, v231
	v_fma_f32 v230, -v230, v233, v232
	v_div_fmas_f32 v230, v230, v231, v233
	v_div_fixup_f32 v135, v230, v229, 1.0
	v_mul_f32_e32 v228, 0xbfb8aa3b, v60
	v_exp_f32_e32 v228, v228
	s_nop 0
	v_add_f32_e32 v229, 1.0, v228
	v_div_scale_f32 v230, s[4:5], v229, v229, 1.0
	v_rcp_f32_e32 v231, v230
	v_div_scale_f32 v232, vcc, 1.0, v229, 1.0
	v_fma_f32 v131, -v230, v231, 1.0
	v_fmac_f32_e32 v231, v131, v231
	v_mul_f32_e32 v233, v232, v231
	v_fma_f32 v131, -v230, v233, v232
	v_fmac_f32_e32 v233, v131, v231
	v_fma_f32 v230, -v230, v233, v232
	v_div_fmas_f32 v230, v230, v231, v233
	v_div_fixup_f32 v133, v230, v229, 1.0
	v_cvt_pk_bf16_f32 v133, v135, v133
	global_store_dword v[226:227], v133, off offset:64
	s_mov_b64 s[4:5], 0x300
	v_lshl_add_u64 v[226:227], v[226:227], 0, s[4:5]
	v_mul_f32_e32 v228, 0xbfb8aa3b, v49
	v_exp_f32_e32 v228, v228
	s_nop 0
	v_add_f32_e32 v229, 1.0, v228
	v_div_scale_f32 v230, s[4:5], v229, v229, 1.0
	v_rcp_f32_e32 v231, v230
	v_div_scale_f32 v232, vcc, 1.0, v229, 1.0
	v_fma_f32 v131, -v230, v231, 1.0
	v_fmac_f32_e32 v231, v131, v231
	v_mul_f32_e32 v233, v232, v231
	v_fma_f32 v131, -v230, v233, v232
	v_fmac_f32_e32 v233, v131, v231
	v_fma_f32 v230, -v230, v233, v232
	v_div_fmas_f32 v230, v230, v231, v233
	v_div_fixup_f32 v135, v230, v229, 1.0
	v_mul_f32_e32 v228, 0xbfb8aa3b, v53
	v_exp_f32_e32 v228, v228
	s_nop 0
	v_add_f32_e32 v229, 1.0, v228
	v_div_scale_f32 v230, s[4:5], v229, v229, 1.0
	v_rcp_f32_e32 v231, v230
	v_div_scale_f32 v232, vcc, 1.0, v229, 1.0
	v_fma_f32 v131, -v230, v231, 1.0
	v_fmac_f32_e32 v231, v131, v231
	v_mul_f32_e32 v233, v232, v231
	v_fma_f32 v131, -v230, v233, v232
	v_fmac_f32_e32 v233, v131, v231
	v_fma_f32 v230, -v230, v233, v232
	v_div_fmas_f32 v230, v230, v231, v233
	v_div_fixup_f32 v133, v230, v229, 1.0
	v_cvt_pk_bf16_f32 v133, v135, v133
	global_store_dword v[226:227], v133, off
	v_mul_f32_e32 v228, 0xbfb8aa3b, v57
	v_exp_f32_e32 v228, v228
	s_nop 0
	v_add_f32_e32 v229, 1.0, v228
	v_div_scale_f32 v230, s[4:5], v229, v229, 1.0
	v_rcp_f32_e32 v231, v230
	v_div_scale_f32 v232, vcc, 1.0, v229, 1.0
	v_fma_f32 v131, -v230, v231, 1.0
	v_fmac_f32_e32 v231, v131, v231
	v_mul_f32_e32 v233, v232, v231
	v_fma_f32 v131, -v230, v233, v232
	v_fmac_f32_e32 v233, v131, v231
	v_fma_f32 v230, -v230, v233, v232
	v_div_fmas_f32 v230, v230, v231, v233
	v_div_fixup_f32 v135, v230, v229, 1.0
	v_mul_f32_e32 v228, 0xbfb8aa3b, v61
	v_exp_f32_e32 v228, v228
	s_nop 0
	v_add_f32_e32 v229, 1.0, v228
	v_div_scale_f32 v230, s[4:5], v229, v229, 1.0
	v_rcp_f32_e32 v231, v230
	v_div_scale_f32 v232, vcc, 1.0, v229, 1.0
	v_fma_f32 v131, -v230, v231, 1.0
	v_fmac_f32_e32 v231, v131, v231
	v_mul_f32_e32 v233, v232, v231
	v_fma_f32 v131, -v230, v233, v232
	v_fmac_f32_e32 v233, v131, v231
	v_fma_f32 v230, -v230, v233, v232
	v_div_fmas_f32 v230, v230, v231, v233
	v_div_fixup_f32 v133, v230, v229, 1.0
	v_cvt_pk_bf16_f32 v133, v135, v133
	global_store_dword v[226:227], v133, off offset:64
	s_mov_b64 s[4:5], 0x300
	v_lshl_add_u64 v[226:227], v[226:227], 0, s[4:5]
	v_mul_f32_e32 v228, 0xbfb8aa3b, v50
	v_exp_f32_e32 v228, v228
	s_nop 0
	v_add_f32_e32 v229, 1.0, v228
	v_div_scale_f32 v230, s[4:5], v229, v229, 1.0
	v_rcp_f32_e32 v231, v230
	v_div_scale_f32 v232, vcc, 1.0, v229, 1.0
	v_fma_f32 v131, -v230, v231, 1.0
	v_fmac_f32_e32 v231, v131, v231
	v_mul_f32_e32 v233, v232, v231
	v_fma_f32 v131, -v230, v233, v232
	v_fmac_f32_e32 v233, v131, v231
	v_fma_f32 v230, -v230, v233, v232
	v_div_fmas_f32 v230, v230, v231, v233
	v_div_fixup_f32 v135, v230, v229, 1.0
	v_mul_f32_e32 v228, 0xbfb8aa3b, v54
	v_exp_f32_e32 v228, v228
	s_nop 0
	v_add_f32_e32 v229, 1.0, v228
	v_div_scale_f32 v230, s[4:5], v229, v229, 1.0
	v_rcp_f32_e32 v231, v230
	v_div_scale_f32 v232, vcc, 1.0, v229, 1.0
	v_fma_f32 v131, -v230, v231, 1.0
	v_fmac_f32_e32 v231, v131, v231
	v_mul_f32_e32 v233, v232, v231
	v_fma_f32 v131, -v230, v233, v232
	v_fmac_f32_e32 v233, v131, v231
	v_fma_f32 v230, -v230, v233, v232
	v_div_fmas_f32 v230, v230, v231, v233
	v_div_fixup_f32 v133, v230, v229, 1.0
	v_cvt_pk_bf16_f32 v133, v135, v133
	global_store_dword v[226:227], v133, off
	v_mul_f32_e32 v228, 0xbfb8aa3b, v58
	v_exp_f32_e32 v228, v228
	s_nop 0
	v_add_f32_e32 v229, 1.0, v228
	v_div_scale_f32 v230, s[4:5], v229, v229, 1.0
	v_rcp_f32_e32 v231, v230
	v_div_scale_f32 v232, vcc, 1.0, v229, 1.0
	v_fma_f32 v131, -v230, v231, 1.0
	v_fmac_f32_e32 v231, v131, v231
	v_mul_f32_e32 v233, v232, v231
	v_fma_f32 v131, -v230, v233, v232
	v_fmac_f32_e32 v233, v131, v231
	v_fma_f32 v230, -v230, v233, v232
	v_div_fmas_f32 v230, v230, v231, v233
	v_div_fixup_f32 v135, v230, v229, 1.0
	v_mul_f32_e32 v228, 0xbfb8aa3b, v62
	v_exp_f32_e32 v228, v228
	s_nop 0
	v_add_f32_e32 v229, 1.0, v228
	v_div_scale_f32 v230, s[4:5], v229, v229, 1.0
	v_rcp_f32_e32 v231, v230
	v_div_scale_f32 v232, vcc, 1.0, v229, 1.0
	v_fma_f32 v131, -v230, v231, 1.0
	v_fmac_f32_e32 v231, v131, v231
	v_mul_f32_e32 v233, v232, v231
	v_fma_f32 v131, -v230, v233, v232
	v_fmac_f32_e32 v233, v131, v231
	v_fma_f32 v230, -v230, v233, v232
	v_div_fmas_f32 v230, v230, v231, v233
	v_div_fixup_f32 v133, v230, v229, 1.0
	v_cvt_pk_bf16_f32 v133, v135, v133
	global_store_dword v[226:227], v133, off offset:64
	s_mov_b64 s[4:5], 0x300
	v_lshl_add_u64 v[226:227], v[226:227], 0, s[4:5]
	v_mul_f32_e32 v228, 0xbfb8aa3b, v51
	v_exp_f32_e32 v228, v228
	s_nop 0
	v_add_f32_e32 v229, 1.0, v228
	v_div_scale_f32 v230, s[4:5], v229, v229, 1.0
	v_rcp_f32_e32 v231, v230
	v_div_scale_f32 v232, vcc, 1.0, v229, 1.0
	v_fma_f32 v131, -v230, v231, 1.0
	v_fmac_f32_e32 v231, v131, v231
	v_mul_f32_e32 v233, v232, v231
	v_fma_f32 v131, -v230, v233, v232
	v_fmac_f32_e32 v233, v131, v231
	v_fma_f32 v230, -v230, v233, v232
	v_div_fmas_f32 v230, v230, v231, v233
	v_div_fixup_f32 v135, v230, v229, 1.0
	v_mul_f32_e32 v228, 0xbfb8aa3b, v55
	v_exp_f32_e32 v228, v228
	s_nop 0
	v_add_f32_e32 v229, 1.0, v228
	v_div_scale_f32 v230, s[4:5], v229, v229, 1.0
	v_rcp_f32_e32 v231, v230
	v_div_scale_f32 v232, vcc, 1.0, v229, 1.0
	v_fma_f32 v131, -v230, v231, 1.0
	v_fmac_f32_e32 v231, v131, v231
	v_mul_f32_e32 v233, v232, v231
	v_fma_f32 v131, -v230, v233, v232
	v_fmac_f32_e32 v233, v131, v231
	v_fma_f32 v230, -v230, v233, v232
	v_div_fmas_f32 v230, v230, v231, v233
	v_div_fixup_f32 v133, v230, v229, 1.0
	v_cvt_pk_bf16_f32 v133, v135, v133
	global_store_dword v[226:227], v133, off
	v_mul_f32_e32 v228, 0xbfb8aa3b, v59
	v_exp_f32_e32 v228, v228
	s_nop 0
	v_add_f32_e32 v229, 1.0, v228
	v_div_scale_f32 v230, s[4:5], v229, v229, 1.0
	v_rcp_f32_e32 v231, v230
	v_div_scale_f32 v232, vcc, 1.0, v229, 1.0
	v_fma_f32 v131, -v230, v231, 1.0
	v_fmac_f32_e32 v231, v131, v231
	v_mul_f32_e32 v233, v232, v231
	v_fma_f32 v131, -v230, v233, v232
	v_fmac_f32_e32 v233, v131, v231
	v_fma_f32 v230, -v230, v233, v232
	v_div_fmas_f32 v230, v230, v231, v233
	v_div_fixup_f32 v135, v230, v229, 1.0
	v_mul_f32_e32 v228, 0xbfb8aa3b, v63
	v_exp_f32_e32 v228, v228
	s_nop 0
	v_add_f32_e32 v229, 1.0, v228
	v_div_scale_f32 v230, s[4:5], v229, v229, 1.0
	v_rcp_f32_e32 v231, v230
	v_div_scale_f32 v232, vcc, 1.0, v229, 1.0
	v_fma_f32 v131, -v230, v231, 1.0
	v_fmac_f32_e32 v231, v131, v231
	v_mul_f32_e32 v233, v232, v231
	v_fma_f32 v131, -v230, v233, v232
	v_fmac_f32_e32 v233, v131, v231
	v_fma_f32 v230, -v230, v233, v232
	v_div_fmas_f32 v230, v230, v231, v233
	v_div_fixup_f32 v133, v230, v229, 1.0
	v_cvt_pk_bf16_f32 v133, v135, v133
	global_store_dword v[226:227], v133, off offset:64
	s_mov_b64 s[4:5], 0x2700
	v_lshl_add_u64 v[226:227], v[226:227], 0, s[4:5]
	v_mul_f32_e32 v228, 0xbfb8aa3b, v64
	v_exp_f32_e32 v228, v228
	s_nop 0
	v_add_f32_e32 v229, 1.0, v228
	v_div_scale_f32 v230, s[4:5], v229, v229, 1.0
	v_rcp_f32_e32 v231, v230
	v_div_scale_f32 v232, vcc, 1.0, v229, 1.0
	v_fma_f32 v131, -v230, v231, 1.0
	v_fmac_f32_e32 v231, v131, v231
	v_mul_f32_e32 v233, v232, v231
	v_fma_f32 v131, -v230, v233, v232
	v_fmac_f32_e32 v233, v131, v231
	v_fma_f32 v230, -v230, v233, v232
	v_div_fmas_f32 v230, v230, v231, v233
	v_div_fixup_f32 v135, v230, v229, 1.0
	v_mul_f32_e32 v228, 0xbfb8aa3b, v68
	v_exp_f32_e32 v228, v228
	s_nop 0
	v_add_f32_e32 v229, 1.0, v228
	v_div_scale_f32 v230, s[4:5], v229, v229, 1.0
	v_rcp_f32_e32 v231, v230
	v_div_scale_f32 v232, vcc, 1.0, v229, 1.0
	v_fma_f32 v131, -v230, v231, 1.0
	v_fmac_f32_e32 v231, v131, v231
	v_mul_f32_e32 v233, v232, v231
	v_fma_f32 v131, -v230, v233, v232
	v_fmac_f32_e32 v233, v131, v231
	v_fma_f32 v230, -v230, v233, v232
	v_div_fmas_f32 v230, v230, v231, v233
	v_div_fixup_f32 v133, v230, v229, 1.0
	v_cvt_pk_bf16_f32 v133, v135, v133
	global_store_dword v[226:227], v133, off
	v_mul_f32_e32 v228, 0xbfb8aa3b, v72
	v_exp_f32_e32 v228, v228
	s_nop 0
	v_add_f32_e32 v229, 1.0, v228
	v_div_scale_f32 v230, s[4:5], v229, v229, 1.0
	v_rcp_f32_e32 v231, v230
	v_div_scale_f32 v232, vcc, 1.0, v229, 1.0
	v_fma_f32 v131, -v230, v231, 1.0
	v_fmac_f32_e32 v231, v131, v231
	v_mul_f32_e32 v233, v232, v231
	v_fma_f32 v131, -v230, v233, v232
	v_fmac_f32_e32 v233, v131, v231
	v_fma_f32 v230, -v230, v233, v232
	v_div_fmas_f32 v230, v230, v231, v233
	v_div_fixup_f32 v135, v230, v229, 1.0
	v_mul_f32_e32 v228, 0xbfb8aa3b, v76
	v_exp_f32_e32 v228, v228
	s_nop 0
	v_add_f32_e32 v229, 1.0, v228
	v_div_scale_f32 v230, s[4:5], v229, v229, 1.0
	v_rcp_f32_e32 v231, v230
	v_div_scale_f32 v232, vcc, 1.0, v229, 1.0
	v_fma_f32 v131, -v230, v231, 1.0
	v_fmac_f32_e32 v231, v131, v231
	v_mul_f32_e32 v233, v232, v231
	v_fma_f32 v131, -v230, v233, v232
	v_fmac_f32_e32 v233, v131, v231
	v_fma_f32 v230, -v230, v233, v232
	v_div_fmas_f32 v230, v230, v231, v233
	v_div_fixup_f32 v133, v230, v229, 1.0
	v_cvt_pk_bf16_f32 v133, v135, v133
	global_store_dword v[226:227], v133, off offset:64
	s_mov_b64 s[4:5], 0x300
	v_lshl_add_u64 v[226:227], v[226:227], 0, s[4:5]
	v_mul_f32_e32 v228, 0xbfb8aa3b, v65
	v_exp_f32_e32 v228, v228
	s_nop 0
	v_add_f32_e32 v229, 1.0, v228
	v_div_scale_f32 v230, s[4:5], v229, v229, 1.0
	v_rcp_f32_e32 v231, v230
	v_div_scale_f32 v232, vcc, 1.0, v229, 1.0
	v_fma_f32 v131, -v230, v231, 1.0
	v_fmac_f32_e32 v231, v131, v231
	v_mul_f32_e32 v233, v232, v231
	v_fma_f32 v131, -v230, v233, v232
	v_fmac_f32_e32 v233, v131, v231
	v_fma_f32 v230, -v230, v233, v232
	v_div_fmas_f32 v230, v230, v231, v233
	v_div_fixup_f32 v135, v230, v229, 1.0
	v_mul_f32_e32 v228, 0xbfb8aa3b, v69
	v_exp_f32_e32 v228, v228
	s_nop 0
	v_add_f32_e32 v229, 1.0, v228
	v_div_scale_f32 v230, s[4:5], v229, v229, 1.0
	v_rcp_f32_e32 v231, v230
	v_div_scale_f32 v232, vcc, 1.0, v229, 1.0
	v_fma_f32 v131, -v230, v231, 1.0
	v_fmac_f32_e32 v231, v131, v231
	v_mul_f32_e32 v233, v232, v231
	v_fma_f32 v131, -v230, v233, v232
	v_fmac_f32_e32 v233, v131, v231
	v_fma_f32 v230, -v230, v233, v232
	v_div_fmas_f32 v230, v230, v231, v233
	v_div_fixup_f32 v133, v230, v229, 1.0
	v_cvt_pk_bf16_f32 v133, v135, v133
	global_store_dword v[226:227], v133, off
	v_mul_f32_e32 v228, 0xbfb8aa3b, v73
	v_exp_f32_e32 v228, v228
	s_nop 0
	v_add_f32_e32 v229, 1.0, v228
	v_div_scale_f32 v230, s[4:5], v229, v229, 1.0
	v_rcp_f32_e32 v231, v230
	v_div_scale_f32 v232, vcc, 1.0, v229, 1.0
	v_fma_f32 v131, -v230, v231, 1.0
	v_fmac_f32_e32 v231, v131, v231
	v_mul_f32_e32 v233, v232, v231
	v_fma_f32 v131, -v230, v233, v232
	v_fmac_f32_e32 v233, v131, v231
	v_fma_f32 v230, -v230, v233, v232
	v_div_fmas_f32 v230, v230, v231, v233
	v_div_fixup_f32 v135, v230, v229, 1.0
	v_mul_f32_e32 v228, 0xbfb8aa3b, v77
	v_exp_f32_e32 v228, v228
	s_nop 0
	v_add_f32_e32 v229, 1.0, v228
	v_div_scale_f32 v230, s[4:5], v229, v229, 1.0
	v_rcp_f32_e32 v231, v230
	v_div_scale_f32 v232, vcc, 1.0, v229, 1.0
	v_fma_f32 v131, -v230, v231, 1.0
	v_fmac_f32_e32 v231, v131, v231
	v_mul_f32_e32 v233, v232, v231
	v_fma_f32 v131, -v230, v233, v232
	v_fmac_f32_e32 v233, v131, v231
	v_fma_f32 v230, -v230, v233, v232
	v_div_fmas_f32 v230, v230, v231, v233
	v_div_fixup_f32 v133, v230, v229, 1.0
	v_cvt_pk_bf16_f32 v133, v135, v133
	global_store_dword v[226:227], v133, off offset:64
	s_mov_b64 s[4:5], 0x300
	v_lshl_add_u64 v[226:227], v[226:227], 0, s[4:5]
	v_mul_f32_e32 v228, 0xbfb8aa3b, v66
	v_exp_f32_e32 v228, v228
	s_nop 0
	v_add_f32_e32 v229, 1.0, v228
	v_div_scale_f32 v230, s[4:5], v229, v229, 1.0
	v_rcp_f32_e32 v231, v230
	v_div_scale_f32 v232, vcc, 1.0, v229, 1.0
	v_fma_f32 v131, -v230, v231, 1.0
	v_fmac_f32_e32 v231, v131, v231
	v_mul_f32_e32 v233, v232, v231
	v_fma_f32 v131, -v230, v233, v232
	v_fmac_f32_e32 v233, v131, v231
	v_fma_f32 v230, -v230, v233, v232
	v_div_fmas_f32 v230, v230, v231, v233
	v_div_fixup_f32 v135, v230, v229, 1.0
	v_mul_f32_e32 v228, 0xbfb8aa3b, v70
	v_exp_f32_e32 v228, v228
	s_nop 0
	v_add_f32_e32 v229, 1.0, v228
	v_div_scale_f32 v230, s[4:5], v229, v229, 1.0
	v_rcp_f32_e32 v231, v230
	v_div_scale_f32 v232, vcc, 1.0, v229, 1.0
	v_fma_f32 v131, -v230, v231, 1.0
	v_fmac_f32_e32 v231, v131, v231
	v_mul_f32_e32 v233, v232, v231
	v_fma_f32 v131, -v230, v233, v232
	v_fmac_f32_e32 v233, v131, v231
	v_fma_f32 v230, -v230, v233, v232
	v_div_fmas_f32 v230, v230, v231, v233
	v_div_fixup_f32 v133, v230, v229, 1.0
	v_cvt_pk_bf16_f32 v133, v135, v133
	global_store_dword v[226:227], v133, off
	v_mul_f32_e32 v228, 0xbfb8aa3b, v74
	v_exp_f32_e32 v228, v228
	s_nop 0
	v_add_f32_e32 v229, 1.0, v228
	v_div_scale_f32 v230, s[4:5], v229, v229, 1.0
	v_rcp_f32_e32 v231, v230
	v_div_scale_f32 v232, vcc, 1.0, v229, 1.0
	v_fma_f32 v131, -v230, v231, 1.0
	v_fmac_f32_e32 v231, v131, v231
	v_mul_f32_e32 v233, v232, v231
	v_fma_f32 v131, -v230, v233, v232
	v_fmac_f32_e32 v233, v131, v231
	v_fma_f32 v230, -v230, v233, v232
	v_div_fmas_f32 v230, v230, v231, v233
	v_div_fixup_f32 v135, v230, v229, 1.0
	v_mul_f32_e32 v228, 0xbfb8aa3b, v78
	v_exp_f32_e32 v228, v228
	s_nop 0
	v_add_f32_e32 v229, 1.0, v228
	v_div_scale_f32 v230, s[4:5], v229, v229, 1.0
	v_rcp_f32_e32 v231, v230
	v_div_scale_f32 v232, vcc, 1.0, v229, 1.0
	v_fma_f32 v131, -v230, v231, 1.0
	v_fmac_f32_e32 v231, v131, v231
	v_mul_f32_e32 v233, v232, v231
	v_fma_f32 v131, -v230, v233, v232
	v_fmac_f32_e32 v233, v131, v231
	v_fma_f32 v230, -v230, v233, v232
	v_div_fmas_f32 v230, v230, v231, v233
	v_div_fixup_f32 v133, v230, v229, 1.0
	v_cvt_pk_bf16_f32 v133, v135, v133
	global_store_dword v[226:227], v133, off offset:64
	s_mov_b64 s[4:5], 0x300
	v_lshl_add_u64 v[226:227], v[226:227], 0, s[4:5]
	v_mul_f32_e32 v228, 0xbfb8aa3b, v67
	v_exp_f32_e32 v228, v228
	s_nop 0
	v_add_f32_e32 v229, 1.0, v228
	v_div_scale_f32 v230, s[4:5], v229, v229, 1.0
	v_rcp_f32_e32 v231, v230
	v_div_scale_f32 v232, vcc, 1.0, v229, 1.0
	v_fma_f32 v131, -v230, v231, 1.0
	v_fmac_f32_e32 v231, v131, v231
	v_mul_f32_e32 v233, v232, v231
	v_fma_f32 v131, -v230, v233, v232
	v_fmac_f32_e32 v233, v131, v231
	v_fma_f32 v230, -v230, v233, v232
	v_div_fmas_f32 v230, v230, v231, v233
	v_div_fixup_f32 v135, v230, v229, 1.0
	v_mul_f32_e32 v228, 0xbfb8aa3b, v71
	v_exp_f32_e32 v228, v228
	s_nop 0
	v_add_f32_e32 v229, 1.0, v228
	v_div_scale_f32 v230, s[4:5], v229, v229, 1.0
	v_rcp_f32_e32 v231, v230
	v_div_scale_f32 v232, vcc, 1.0, v229, 1.0
	v_fma_f32 v131, -v230, v231, 1.0
	v_fmac_f32_e32 v231, v131, v231
	v_mul_f32_e32 v233, v232, v231
	v_fma_f32 v131, -v230, v233, v232
	v_fmac_f32_e32 v233, v131, v231
	v_fma_f32 v230, -v230, v233, v232
	v_div_fmas_f32 v230, v230, v231, v233
	v_div_fixup_f32 v133, v230, v229, 1.0
	v_cvt_pk_bf16_f32 v133, v135, v133
	global_store_dword v[226:227], v133, off
	v_mul_f32_e32 v228, 0xbfb8aa3b, v75
	v_exp_f32_e32 v228, v228
	s_nop 0
	v_add_f32_e32 v229, 1.0, v228
	v_div_scale_f32 v230, s[4:5], v229, v229, 1.0
	v_rcp_f32_e32 v231, v230
	v_div_scale_f32 v232, vcc, 1.0, v229, 1.0
	v_fma_f32 v131, -v230, v231, 1.0
	v_fmac_f32_e32 v231, v131, v231
	v_mul_f32_e32 v233, v232, v231
	v_fma_f32 v131, -v230, v233, v232
	v_fmac_f32_e32 v233, v131, v231
	v_fma_f32 v230, -v230, v233, v232
	v_div_fmas_f32 v230, v230, v231, v233
	v_div_fixup_f32 v135, v230, v229, 1.0
	v_mul_f32_e32 v228, 0xbfb8aa3b, v79
	v_exp_f32_e32 v228, v228
	s_nop 0
	v_add_f32_e32 v229, 1.0, v228
	v_div_scale_f32 v230, s[4:5], v229, v229, 1.0
	v_rcp_f32_e32 v231, v230
	v_div_scale_f32 v232, vcc, 1.0, v229, 1.0
	v_fma_f32 v131, -v230, v231, 1.0
	v_fmac_f32_e32 v231, v131, v231
	v_mul_f32_e32 v233, v232, v231
	v_fma_f32 v131, -v230, v233, v232
	v_fmac_f32_e32 v233, v131, v231
	v_fma_f32 v230, -v230, v233, v232
	v_div_fmas_f32 v230, v230, v231, v233
	v_div_fixup_f32 v133, v230, v229, 1.0
	v_cvt_pk_bf16_f32 v133, v135, v133
	global_store_dword v[226:227], v133, off offset:64
	s_mov_b64 s[4:5], 0x2700
	v_lshl_add_u64 v[226:227], v[226:227], 0, s[4:5]
	v_mul_f32_e32 v228, 0xbfb8aa3b, v80
	v_exp_f32_e32 v228, v228
	s_nop 0
	v_add_f32_e32 v229, 1.0, v228
	v_div_scale_f32 v230, s[4:5], v229, v229, 1.0
	v_rcp_f32_e32 v231, v230
	v_div_scale_f32 v232, vcc, 1.0, v229, 1.0
	v_fma_f32 v131, -v230, v231, 1.0
	v_fmac_f32_e32 v231, v131, v231
	v_mul_f32_e32 v233, v232, v231
	v_fma_f32 v131, -v230, v233, v232
	v_fmac_f32_e32 v233, v131, v231
	v_fma_f32 v230, -v230, v233, v232
	v_div_fmas_f32 v230, v230, v231, v233
	v_div_fixup_f32 v135, v230, v229, 1.0
	v_mul_f32_e32 v228, 0xbfb8aa3b, v84
	v_exp_f32_e32 v228, v228
	s_nop 0
	v_add_f32_e32 v229, 1.0, v228
	v_div_scale_f32 v230, s[4:5], v229, v229, 1.0
	v_rcp_f32_e32 v231, v230
	v_div_scale_f32 v232, vcc, 1.0, v229, 1.0
	v_fma_f32 v131, -v230, v231, 1.0
	v_fmac_f32_e32 v231, v131, v231
	v_mul_f32_e32 v233, v232, v231
	v_fma_f32 v131, -v230, v233, v232
	v_fmac_f32_e32 v233, v131, v231
	v_fma_f32 v230, -v230, v233, v232
	v_div_fmas_f32 v230, v230, v231, v233
	v_div_fixup_f32 v133, v230, v229, 1.0
	v_cvt_pk_bf16_f32 v133, v135, v133
	global_store_dword v[226:227], v133, off
	v_mul_f32_e32 v228, 0xbfb8aa3b, v88
	v_exp_f32_e32 v228, v228
	s_nop 0
	v_add_f32_e32 v229, 1.0, v228
	v_div_scale_f32 v230, s[4:5], v229, v229, 1.0
	v_rcp_f32_e32 v231, v230
	v_div_scale_f32 v232, vcc, 1.0, v229, 1.0
	v_fma_f32 v131, -v230, v231, 1.0
	v_fmac_f32_e32 v231, v131, v231
	v_mul_f32_e32 v233, v232, v231
	v_fma_f32 v131, -v230, v233, v232
	v_fmac_f32_e32 v233, v131, v231
	v_fma_f32 v230, -v230, v233, v232
	v_div_fmas_f32 v230, v230, v231, v233
	v_div_fixup_f32 v135, v230, v229, 1.0
	v_mul_f32_e32 v228, 0xbfb8aa3b, v92
	v_exp_f32_e32 v228, v228
	s_nop 0
	v_add_f32_e32 v229, 1.0, v228
	v_div_scale_f32 v230, s[4:5], v229, v229, 1.0
	v_rcp_f32_e32 v231, v230
	v_div_scale_f32 v232, vcc, 1.0, v229, 1.0
	v_fma_f32 v131, -v230, v231, 1.0
	v_fmac_f32_e32 v231, v131, v231
	v_mul_f32_e32 v233, v232, v231
	v_fma_f32 v131, -v230, v233, v232
	v_fmac_f32_e32 v233, v131, v231
	v_fma_f32 v230, -v230, v233, v232
	v_div_fmas_f32 v230, v230, v231, v233
	v_div_fixup_f32 v133, v230, v229, 1.0
	v_cvt_pk_bf16_f32 v133, v135, v133
	global_store_dword v[226:227], v133, off offset:64
	s_mov_b64 s[4:5], 0x300
	v_lshl_add_u64 v[226:227], v[226:227], 0, s[4:5]
	v_mul_f32_e32 v228, 0xbfb8aa3b, v81
	v_exp_f32_e32 v228, v228
	s_nop 0
	v_add_f32_e32 v229, 1.0, v228
	v_div_scale_f32 v230, s[4:5], v229, v229, 1.0
	v_rcp_f32_e32 v231, v230
	v_div_scale_f32 v232, vcc, 1.0, v229, 1.0
	v_fma_f32 v131, -v230, v231, 1.0
	v_fmac_f32_e32 v231, v131, v231
	v_mul_f32_e32 v233, v232, v231
	v_fma_f32 v131, -v230, v233, v232
	v_fmac_f32_e32 v233, v131, v231
	v_fma_f32 v230, -v230, v233, v232
	v_div_fmas_f32 v230, v230, v231, v233
	v_div_fixup_f32 v135, v230, v229, 1.0
	v_mul_f32_e32 v228, 0xbfb8aa3b, v85
	v_exp_f32_e32 v228, v228
	s_nop 0
	v_add_f32_e32 v229, 1.0, v228
	v_div_scale_f32 v230, s[4:5], v229, v229, 1.0
	v_rcp_f32_e32 v231, v230
	v_div_scale_f32 v232, vcc, 1.0, v229, 1.0
	v_fma_f32 v131, -v230, v231, 1.0
	v_fmac_f32_e32 v231, v131, v231
	v_mul_f32_e32 v233, v232, v231
	v_fma_f32 v131, -v230, v233, v232
	v_fmac_f32_e32 v233, v131, v231
	v_fma_f32 v230, -v230, v233, v232
	v_div_fmas_f32 v230, v230, v231, v233
	v_div_fixup_f32 v133, v230, v229, 1.0
	v_cvt_pk_bf16_f32 v133, v135, v133
	global_store_dword v[226:227], v133, off
	v_mul_f32_e32 v228, 0xbfb8aa3b, v89
	v_exp_f32_e32 v228, v228
	s_nop 0
	v_add_f32_e32 v229, 1.0, v228
	v_div_scale_f32 v230, s[4:5], v229, v229, 1.0
	v_rcp_f32_e32 v231, v230
	v_div_scale_f32 v232, vcc, 1.0, v229, 1.0
	v_fma_f32 v131, -v230, v231, 1.0
	v_fmac_f32_e32 v231, v131, v231
	v_mul_f32_e32 v233, v232, v231
	v_fma_f32 v131, -v230, v233, v232
	v_fmac_f32_e32 v233, v131, v231
	v_fma_f32 v230, -v230, v233, v232
	v_div_fmas_f32 v230, v230, v231, v233
	v_div_fixup_f32 v135, v230, v229, 1.0
	v_mul_f32_e32 v228, 0xbfb8aa3b, v93
	v_exp_f32_e32 v228, v228
	s_nop 0
	v_add_f32_e32 v229, 1.0, v228
	v_div_scale_f32 v230, s[4:5], v229, v229, 1.0
	v_rcp_f32_e32 v231, v230
	v_div_scale_f32 v232, vcc, 1.0, v229, 1.0
	v_fma_f32 v131, -v230, v231, 1.0
	v_fmac_f32_e32 v231, v131, v231
	v_mul_f32_e32 v233, v232, v231
	v_fma_f32 v131, -v230, v233, v232
	v_fmac_f32_e32 v233, v131, v231
	v_fma_f32 v230, -v230, v233, v232
	v_div_fmas_f32 v230, v230, v231, v233
	v_div_fixup_f32 v133, v230, v229, 1.0
	v_cvt_pk_bf16_f32 v133, v135, v133
	global_store_dword v[226:227], v133, off offset:64
	s_mov_b64 s[4:5], 0x300
	v_lshl_add_u64 v[226:227], v[226:227], 0, s[4:5]
	v_mul_f32_e32 v228, 0xbfb8aa3b, v82
	v_exp_f32_e32 v228, v228
	s_nop 0
	v_add_f32_e32 v229, 1.0, v228
	v_div_scale_f32 v230, s[4:5], v229, v229, 1.0
	v_rcp_f32_e32 v231, v230
	v_div_scale_f32 v232, vcc, 1.0, v229, 1.0
	v_fma_f32 v131, -v230, v231, 1.0
	v_fmac_f32_e32 v231, v131, v231
	v_mul_f32_e32 v233, v232, v231
	v_fma_f32 v131, -v230, v233, v232
	v_fmac_f32_e32 v233, v131, v231
	v_fma_f32 v230, -v230, v233, v232
	v_div_fmas_f32 v230, v230, v231, v233
	v_div_fixup_f32 v135, v230, v229, 1.0
	v_mul_f32_e32 v228, 0xbfb8aa3b, v86
	v_exp_f32_e32 v228, v228
	s_nop 0
	v_add_f32_e32 v229, 1.0, v228
	v_div_scale_f32 v230, s[4:5], v229, v229, 1.0
	v_rcp_f32_e32 v231, v230
	v_div_scale_f32 v232, vcc, 1.0, v229, 1.0
	v_fma_f32 v131, -v230, v231, 1.0
	v_fmac_f32_e32 v231, v131, v231
	v_mul_f32_e32 v233, v232, v231
	v_fma_f32 v131, -v230, v233, v232
	v_fmac_f32_e32 v233, v131, v231
	v_fma_f32 v230, -v230, v233, v232
	v_div_fmas_f32 v230, v230, v231, v233
	v_div_fixup_f32 v133, v230, v229, 1.0
	v_cvt_pk_bf16_f32 v133, v135, v133
	global_store_dword v[226:227], v133, off
	v_mul_f32_e32 v228, 0xbfb8aa3b, v90
	v_exp_f32_e32 v228, v228
	s_nop 0
	v_add_f32_e32 v229, 1.0, v228
	v_div_scale_f32 v230, s[4:5], v229, v229, 1.0
	v_rcp_f32_e32 v231, v230
	v_div_scale_f32 v232, vcc, 1.0, v229, 1.0
	v_fma_f32 v131, -v230, v231, 1.0
	v_fmac_f32_e32 v231, v131, v231
	v_mul_f32_e32 v233, v232, v231
	v_fma_f32 v131, -v230, v233, v232
	v_fmac_f32_e32 v233, v131, v231
	v_fma_f32 v230, -v230, v233, v232
	v_div_fmas_f32 v230, v230, v231, v233
	v_div_fixup_f32 v135, v230, v229, 1.0
	v_mul_f32_e32 v228, 0xbfb8aa3b, v94
	v_exp_f32_e32 v228, v228
	s_nop 0
	v_add_f32_e32 v229, 1.0, v228
	v_div_scale_f32 v230, s[4:5], v229, v229, 1.0
	v_rcp_f32_e32 v231, v230
	v_div_scale_f32 v232, vcc, 1.0, v229, 1.0
	v_fma_f32 v131, -v230, v231, 1.0
	v_fmac_f32_e32 v231, v131, v231
	v_mul_f32_e32 v233, v232, v231
	v_fma_f32 v131, -v230, v233, v232
	v_fmac_f32_e32 v233, v131, v231
	v_fma_f32 v230, -v230, v233, v232
	v_div_fmas_f32 v230, v230, v231, v233
	v_div_fixup_f32 v133, v230, v229, 1.0
	v_cvt_pk_bf16_f32 v133, v135, v133
	global_store_dword v[226:227], v133, off offset:64
	s_mov_b64 s[4:5], 0x300
	v_lshl_add_u64 v[226:227], v[226:227], 0, s[4:5]
	v_mul_f32_e32 v228, 0xbfb8aa3b, v83
	v_exp_f32_e32 v228, v228
	s_nop 0
	v_add_f32_e32 v229, 1.0, v228
	v_div_scale_f32 v230, s[4:5], v229, v229, 1.0
	v_rcp_f32_e32 v231, v230
	v_div_scale_f32 v232, vcc, 1.0, v229, 1.0
	v_fma_f32 v131, -v230, v231, 1.0
	v_fmac_f32_e32 v231, v131, v231
	v_mul_f32_e32 v233, v232, v231
	v_fma_f32 v131, -v230, v233, v232
	v_fmac_f32_e32 v233, v131, v231
	v_fma_f32 v230, -v230, v233, v232
	v_div_fmas_f32 v230, v230, v231, v233
	v_div_fixup_f32 v135, v230, v229, 1.0
	v_mul_f32_e32 v228, 0xbfb8aa3b, v87
	v_exp_f32_e32 v228, v228
	s_nop 0
	v_add_f32_e32 v229, 1.0, v228
	v_div_scale_f32 v230, s[4:5], v229, v229, 1.0
	v_rcp_f32_e32 v231, v230
	v_div_scale_f32 v232, vcc, 1.0, v229, 1.0
	v_fma_f32 v131, -v230, v231, 1.0
	v_fmac_f32_e32 v231, v131, v231
	v_mul_f32_e32 v233, v232, v231
	v_fma_f32 v131, -v230, v233, v232
	v_fmac_f32_e32 v233, v131, v231
	v_fma_f32 v230, -v230, v233, v232
	v_div_fmas_f32 v230, v230, v231, v233
	v_div_fixup_f32 v133, v230, v229, 1.0
	v_cvt_pk_bf16_f32 v133, v135, v133
	global_store_dword v[226:227], v133, off
	v_mul_f32_e32 v228, 0xbfb8aa3b, v91
	v_exp_f32_e32 v228, v228
	s_nop 0
	v_add_f32_e32 v229, 1.0, v228
	v_div_scale_f32 v230, s[4:5], v229, v229, 1.0
	v_rcp_f32_e32 v231, v230
	v_div_scale_f32 v232, vcc, 1.0, v229, 1.0
	v_fma_f32 v131, -v230, v231, 1.0
	v_fmac_f32_e32 v231, v131, v231
	v_mul_f32_e32 v233, v232, v231
	v_fma_f32 v131, -v230, v233, v232
	v_fmac_f32_e32 v233, v131, v231
	v_fma_f32 v230, -v230, v233, v232
	v_div_fmas_f32 v230, v230, v231, v233
	v_div_fixup_f32 v135, v230, v229, 1.0
	v_mul_f32_e32 v228, 0xbfb8aa3b, v95
	v_exp_f32_e32 v228, v228
	s_nop 0
	v_add_f32_e32 v229, 1.0, v228
	v_div_scale_f32 v230, s[4:5], v229, v229, 1.0
	v_rcp_f32_e32 v231, v230
	v_div_scale_f32 v232, vcc, 1.0, v229, 1.0
	v_fma_f32 v131, -v230, v231, 1.0
	v_fmac_f32_e32 v231, v131, v231
	v_mul_f32_e32 v233, v232, v231
	v_fma_f32 v131, -v230, v233, v232
	v_fmac_f32_e32 v233, v131, v231
	v_fma_f32 v230, -v230, v233, v232
	v_div_fmas_f32 v230, v230, v231, v233
	v_div_fixup_f32 v133, v230, v229, 1.0
	v_cvt_pk_bf16_f32 v133, v135, v133
	global_store_dword v[226:227], v133, off offset:64
	s_mov_b64 s[4:5], 0x2700
	v_lshl_add_u64 v[226:227], v[226:227], 0, s[4:5]
	v_mul_f32_e32 v228, 0xbfb8aa3b, v96
	v_exp_f32_e32 v228, v228
	s_nop 0
	v_add_f32_e32 v229, 1.0, v228
	v_div_scale_f32 v230, s[4:5], v229, v229, 1.0
	v_rcp_f32_e32 v231, v230
	v_div_scale_f32 v232, vcc, 1.0, v229, 1.0
	v_fma_f32 v131, -v230, v231, 1.0
	v_fmac_f32_e32 v231, v131, v231
	v_mul_f32_e32 v233, v232, v231
	v_fma_f32 v131, -v230, v233, v232
	v_fmac_f32_e32 v233, v131, v231
	v_fma_f32 v230, -v230, v233, v232
	v_div_fmas_f32 v230, v230, v231, v233
	v_div_fixup_f32 v135, v230, v229, 1.0
	v_mul_f32_e32 v228, 0xbfb8aa3b, v100
	v_exp_f32_e32 v228, v228
	s_nop 0
	v_add_f32_e32 v229, 1.0, v228
	v_div_scale_f32 v230, s[4:5], v229, v229, 1.0
	v_rcp_f32_e32 v231, v230
	v_div_scale_f32 v232, vcc, 1.0, v229, 1.0
	v_fma_f32 v131, -v230, v231, 1.0
	v_fmac_f32_e32 v231, v131, v231
	v_mul_f32_e32 v233, v232, v231
	v_fma_f32 v131, -v230, v233, v232
	v_fmac_f32_e32 v233, v131, v231
	v_fma_f32 v230, -v230, v233, v232
	v_div_fmas_f32 v230, v230, v231, v233
	v_div_fixup_f32 v133, v230, v229, 1.0
	v_cvt_pk_bf16_f32 v133, v135, v133
	global_store_dword v[226:227], v133, off
	v_mul_f32_e32 v228, 0xbfb8aa3b, v104
	v_exp_f32_e32 v228, v228
	s_nop 0
	v_add_f32_e32 v229, 1.0, v228
	v_div_scale_f32 v230, s[4:5], v229, v229, 1.0
	v_rcp_f32_e32 v231, v230
	v_div_scale_f32 v232, vcc, 1.0, v229, 1.0
	v_fma_f32 v131, -v230, v231, 1.0
	v_fmac_f32_e32 v231, v131, v231
	v_mul_f32_e32 v233, v232, v231
	v_fma_f32 v131, -v230, v233, v232
	v_fmac_f32_e32 v233, v131, v231
	v_fma_f32 v230, -v230, v233, v232
	v_div_fmas_f32 v230, v230, v231, v233
	v_div_fixup_f32 v135, v230, v229, 1.0
	v_mul_f32_e32 v228, 0xbfb8aa3b, v108
	v_exp_f32_e32 v228, v228
	s_nop 0
	v_add_f32_e32 v229, 1.0, v228
	v_div_scale_f32 v230, s[4:5], v229, v229, 1.0
	v_rcp_f32_e32 v231, v230
	v_div_scale_f32 v232, vcc, 1.0, v229, 1.0
	v_fma_f32 v131, -v230, v231, 1.0
	v_fmac_f32_e32 v231, v131, v231
	v_mul_f32_e32 v233, v232, v231
	v_fma_f32 v131, -v230, v233, v232
	v_fmac_f32_e32 v233, v131, v231
	v_fma_f32 v230, -v230, v233, v232
	v_div_fmas_f32 v230, v230, v231, v233
	v_div_fixup_f32 v133, v230, v229, 1.0
	v_cvt_pk_bf16_f32 v133, v135, v133
	global_store_dword v[226:227], v133, off offset:64
	s_mov_b64 s[4:5], 0x300
	v_lshl_add_u64 v[226:227], v[226:227], 0, s[4:5]
	v_mul_f32_e32 v228, 0xbfb8aa3b, v97
	v_exp_f32_e32 v228, v228
	s_nop 0
	v_add_f32_e32 v229, 1.0, v228
	v_div_scale_f32 v230, s[4:5], v229, v229, 1.0
	v_rcp_f32_e32 v231, v230
	v_div_scale_f32 v232, vcc, 1.0, v229, 1.0
	v_fma_f32 v131, -v230, v231, 1.0
	v_fmac_f32_e32 v231, v131, v231
	v_mul_f32_e32 v233, v232, v231
	v_fma_f32 v131, -v230, v233, v232
	v_fmac_f32_e32 v233, v131, v231
	v_fma_f32 v230, -v230, v233, v232
	v_div_fmas_f32 v230, v230, v231, v233
	v_div_fixup_f32 v135, v230, v229, 1.0
	v_mul_f32_e32 v228, 0xbfb8aa3b, v101
	v_exp_f32_e32 v228, v228
	s_nop 0
	v_add_f32_e32 v229, 1.0, v228
	v_div_scale_f32 v230, s[4:5], v229, v229, 1.0
	v_rcp_f32_e32 v231, v230
	v_div_scale_f32 v232, vcc, 1.0, v229, 1.0
	v_fma_f32 v131, -v230, v231, 1.0
	v_fmac_f32_e32 v231, v131, v231
	v_mul_f32_e32 v233, v232, v231
	v_fma_f32 v131, -v230, v233, v232
	v_fmac_f32_e32 v233, v131, v231
	v_fma_f32 v230, -v230, v233, v232
	v_div_fmas_f32 v230, v230, v231, v233
	v_div_fixup_f32 v133, v230, v229, 1.0
	v_cvt_pk_bf16_f32 v133, v135, v133
	global_store_dword v[226:227], v133, off
	v_mul_f32_e32 v228, 0xbfb8aa3b, v105
	v_exp_f32_e32 v228, v228
	s_nop 0
	v_add_f32_e32 v229, 1.0, v228
	v_div_scale_f32 v230, s[4:5], v229, v229, 1.0
	v_rcp_f32_e32 v231, v230
	v_div_scale_f32 v232, vcc, 1.0, v229, 1.0
	v_fma_f32 v131, -v230, v231, 1.0
	v_fmac_f32_e32 v231, v131, v231
	v_mul_f32_e32 v233, v232, v231
	v_fma_f32 v131, -v230, v233, v232
	v_fmac_f32_e32 v233, v131, v231
	v_fma_f32 v230, -v230, v233, v232
	v_div_fmas_f32 v230, v230, v231, v233
	v_div_fixup_f32 v135, v230, v229, 1.0
	v_mul_f32_e32 v228, 0xbfb8aa3b, v109
	v_exp_f32_e32 v228, v228
	s_nop 0
	v_add_f32_e32 v229, 1.0, v228
	v_div_scale_f32 v230, s[4:5], v229, v229, 1.0
	v_rcp_f32_e32 v231, v230
	v_div_scale_f32 v232, vcc, 1.0, v229, 1.0
	v_fma_f32 v131, -v230, v231, 1.0
	v_fmac_f32_e32 v231, v131, v231
	v_mul_f32_e32 v233, v232, v231
	v_fma_f32 v131, -v230, v233, v232
	v_fmac_f32_e32 v233, v131, v231
	v_fma_f32 v230, -v230, v233, v232
	v_div_fmas_f32 v230, v230, v231, v233
	v_div_fixup_f32 v133, v230, v229, 1.0
	v_cvt_pk_bf16_f32 v133, v135, v133
	global_store_dword v[226:227], v133, off offset:64
	s_mov_b64 s[4:5], 0x300
	v_lshl_add_u64 v[226:227], v[226:227], 0, s[4:5]
	v_mul_f32_e32 v228, 0xbfb8aa3b, v98
	v_exp_f32_e32 v228, v228
	s_nop 0
	v_add_f32_e32 v229, 1.0, v228
	v_div_scale_f32 v230, s[4:5], v229, v229, 1.0
	v_rcp_f32_e32 v231, v230
	v_div_scale_f32 v232, vcc, 1.0, v229, 1.0
	v_fma_f32 v131, -v230, v231, 1.0
	v_fmac_f32_e32 v231, v131, v231
	v_mul_f32_e32 v233, v232, v231
	v_fma_f32 v131, -v230, v233, v232
	v_fmac_f32_e32 v233, v131, v231
	v_fma_f32 v230, -v230, v233, v232
	v_div_fmas_f32 v230, v230, v231, v233
	v_div_fixup_f32 v135, v230, v229, 1.0
	v_mul_f32_e32 v228, 0xbfb8aa3b, v102
	v_exp_f32_e32 v228, v228
	s_nop 0
	v_add_f32_e32 v229, 1.0, v228
	v_div_scale_f32 v230, s[4:5], v229, v229, 1.0
	v_rcp_f32_e32 v231, v230
	v_div_scale_f32 v232, vcc, 1.0, v229, 1.0
	v_fma_f32 v131, -v230, v231, 1.0
	v_fmac_f32_e32 v231, v131, v231
	v_mul_f32_e32 v233, v232, v231
	v_fma_f32 v131, -v230, v233, v232
	v_fmac_f32_e32 v233, v131, v231
	v_fma_f32 v230, -v230, v233, v232
	v_div_fmas_f32 v230, v230, v231, v233
	v_div_fixup_f32 v133, v230, v229, 1.0
	v_cvt_pk_bf16_f32 v133, v135, v133
	global_store_dword v[226:227], v133, off
	v_mul_f32_e32 v228, 0xbfb8aa3b, v106
	v_exp_f32_e32 v228, v228
	s_nop 0
	v_add_f32_e32 v229, 1.0, v228
	v_div_scale_f32 v230, s[4:5], v229, v229, 1.0
	v_rcp_f32_e32 v231, v230
	v_div_scale_f32 v232, vcc, 1.0, v229, 1.0
	v_fma_f32 v131, -v230, v231, 1.0
	v_fmac_f32_e32 v231, v131, v231
	v_mul_f32_e32 v233, v232, v231
	v_fma_f32 v131, -v230, v233, v232
	v_fmac_f32_e32 v233, v131, v231
	v_fma_f32 v230, -v230, v233, v232
	v_div_fmas_f32 v230, v230, v231, v233
	v_div_fixup_f32 v135, v230, v229, 1.0
	v_mul_f32_e32 v228, 0xbfb8aa3b, v110
	v_exp_f32_e32 v228, v228
	s_nop 0
	v_add_f32_e32 v229, 1.0, v228
	v_div_scale_f32 v230, s[4:5], v229, v229, 1.0
	v_rcp_f32_e32 v231, v230
	v_div_scale_f32 v232, vcc, 1.0, v229, 1.0
	v_fma_f32 v131, -v230, v231, 1.0
	v_fmac_f32_e32 v231, v131, v231
	v_mul_f32_e32 v233, v232, v231
	v_fma_f32 v131, -v230, v233, v232
	v_fmac_f32_e32 v233, v131, v231
	v_fma_f32 v230, -v230, v233, v232
	v_div_fmas_f32 v230, v230, v231, v233
	v_div_fixup_f32 v133, v230, v229, 1.0
	v_cvt_pk_bf16_f32 v133, v135, v133
	global_store_dword v[226:227], v133, off offset:64
	s_mov_b64 s[4:5], 0x300
	v_lshl_add_u64 v[226:227], v[226:227], 0, s[4:5]
	v_mul_f32_e32 v228, 0xbfb8aa3b, v99
	v_exp_f32_e32 v228, v228
	s_nop 0
	v_add_f32_e32 v229, 1.0, v228
	v_div_scale_f32 v230, s[4:5], v229, v229, 1.0
	v_rcp_f32_e32 v231, v230
	v_div_scale_f32 v232, vcc, 1.0, v229, 1.0
	v_fma_f32 v131, -v230, v231, 1.0
	v_fmac_f32_e32 v231, v131, v231
	v_mul_f32_e32 v233, v232, v231
	v_fma_f32 v131, -v230, v233, v232
	v_fmac_f32_e32 v233, v131, v231
	v_fma_f32 v230, -v230, v233, v232
	v_div_fmas_f32 v230, v230, v231, v233
	v_div_fixup_f32 v135, v230, v229, 1.0
	v_mul_f32_e32 v228, 0xbfb8aa3b, v103
	v_exp_f32_e32 v228, v228
	s_nop 0
	v_add_f32_e32 v229, 1.0, v228
	v_div_scale_f32 v230, s[4:5], v229, v229, 1.0
	v_rcp_f32_e32 v231, v230
	v_div_scale_f32 v232, vcc, 1.0, v229, 1.0
	v_fma_f32 v131, -v230, v231, 1.0
	v_fmac_f32_e32 v231, v131, v231
	v_mul_f32_e32 v233, v232, v231
	v_fma_f32 v131, -v230, v233, v232
	v_fmac_f32_e32 v233, v131, v231
	v_fma_f32 v230, -v230, v233, v232
	v_div_fmas_f32 v230, v230, v231, v233
	v_div_fixup_f32 v133, v230, v229, 1.0
	v_cvt_pk_bf16_f32 v133, v135, v133
	global_store_dword v[226:227], v133, off
	v_mul_f32_e32 v228, 0xbfb8aa3b, v107
	v_exp_f32_e32 v228, v228
	s_nop 0
	v_add_f32_e32 v229, 1.0, v228
	v_div_scale_f32 v230, s[4:5], v229, v229, 1.0
	v_rcp_f32_e32 v231, v230
	v_div_scale_f32 v232, vcc, 1.0, v229, 1.0
	v_fma_f32 v131, -v230, v231, 1.0
	v_fmac_f32_e32 v231, v131, v231
	v_mul_f32_e32 v233, v232, v231
	v_fma_f32 v131, -v230, v233, v232
	v_fmac_f32_e32 v233, v131, v231
	v_fma_f32 v230, -v230, v233, v232
	v_div_fmas_f32 v230, v230, v231, v233
	v_div_fixup_f32 v135, v230, v229, 1.0
	v_mul_f32_e32 v228, 0xbfb8aa3b, v111
	v_exp_f32_e32 v228, v228
	s_nop 0
	v_add_f32_e32 v229, 1.0, v228
	v_div_scale_f32 v230, s[4:5], v229, v229, 1.0
	v_rcp_f32_e32 v231, v230
	v_div_scale_f32 v232, vcc, 1.0, v229, 1.0
	v_fma_f32 v131, -v230, v231, 1.0
	v_fmac_f32_e32 v231, v131, v231
	v_mul_f32_e32 v233, v232, v231
	v_fma_f32 v131, -v230, v233, v232
	v_fmac_f32_e32 v233, v131, v231
	v_fma_f32 v230, -v230, v233, v232
	v_div_fmas_f32 v230, v230, v231, v233
	v_div_fixup_f32 v133, v230, v229, 1.0
	v_cvt_pk_bf16_f32 v133, v135, v133
	global_store_dword v[226:227], v133, off offset:64
	s_mov_b64 s[4:5], 0x2700
	v_lshl_add_u64 v[226:227], v[226:227], 0, s[4:5]
	v_mul_f32_e32 v228, 0xbfb8aa3b, v112
	v_exp_f32_e32 v228, v228
	s_nop 0
	v_add_f32_e32 v229, 1.0, v228
	v_div_scale_f32 v230, s[4:5], v229, v229, 1.0
	v_rcp_f32_e32 v231, v230
	v_div_scale_f32 v232, vcc, 1.0, v229, 1.0
	v_fma_f32 v131, -v230, v231, 1.0
	v_fmac_f32_e32 v231, v131, v231
	v_mul_f32_e32 v233, v232, v231
	v_fma_f32 v131, -v230, v233, v232
	v_fmac_f32_e32 v233, v131, v231
	v_fma_f32 v230, -v230, v233, v232
	v_div_fmas_f32 v230, v230, v231, v233
	v_div_fixup_f32 v135, v230, v229, 1.0
	v_mul_f32_e32 v228, 0xbfb8aa3b, v116
	v_exp_f32_e32 v228, v228
	s_nop 0
	v_add_f32_e32 v229, 1.0, v228
	v_div_scale_f32 v230, s[4:5], v229, v229, 1.0
	v_rcp_f32_e32 v231, v230
	v_div_scale_f32 v232, vcc, 1.0, v229, 1.0
	v_fma_f32 v131, -v230, v231, 1.0
	v_fmac_f32_e32 v231, v131, v231
	v_mul_f32_e32 v233, v232, v231
	v_fma_f32 v131, -v230, v233, v232
	v_fmac_f32_e32 v233, v131, v231
	v_fma_f32 v230, -v230, v233, v232
	v_div_fmas_f32 v230, v230, v231, v233
	v_div_fixup_f32 v133, v230, v229, 1.0
	v_cvt_pk_bf16_f32 v133, v135, v133
	global_store_dword v[226:227], v133, off
	v_mul_f32_e32 v228, 0xbfb8aa3b, v120
	v_exp_f32_e32 v228, v228
	s_nop 0
	v_add_f32_e32 v229, 1.0, v228
	v_div_scale_f32 v230, s[4:5], v229, v229, 1.0
	v_rcp_f32_e32 v231, v230
	v_div_scale_f32 v232, vcc, 1.0, v229, 1.0
	v_fma_f32 v131, -v230, v231, 1.0
	v_fmac_f32_e32 v231, v131, v231
	v_mul_f32_e32 v233, v232, v231
	v_fma_f32 v131, -v230, v233, v232
	v_fmac_f32_e32 v233, v131, v231
	v_fma_f32 v230, -v230, v233, v232
	v_div_fmas_f32 v230, v230, v231, v233
	v_div_fixup_f32 v135, v230, v229, 1.0
	v_mul_f32_e32 v228, 0xbfb8aa3b, v124
	v_exp_f32_e32 v228, v228
	s_nop 0
	v_add_f32_e32 v229, 1.0, v228
	v_div_scale_f32 v230, s[4:5], v229, v229, 1.0
	v_rcp_f32_e32 v231, v230
	v_div_scale_f32 v232, vcc, 1.0, v229, 1.0
	v_fma_f32 v131, -v230, v231, 1.0
	v_fmac_f32_e32 v231, v131, v231
	v_mul_f32_e32 v233, v232, v231
	v_fma_f32 v131, -v230, v233, v232
	v_fmac_f32_e32 v233, v131, v231
	v_fma_f32 v230, -v230, v233, v232
	v_div_fmas_f32 v230, v230, v231, v233
	v_div_fixup_f32 v133, v230, v229, 1.0
	v_cvt_pk_bf16_f32 v133, v135, v133
	global_store_dword v[226:227], v133, off offset:64
	s_mov_b64 s[4:5], 0x300
	v_lshl_add_u64 v[226:227], v[226:227], 0, s[4:5]
	v_mul_f32_e32 v228, 0xbfb8aa3b, v113
	v_exp_f32_e32 v228, v228
	s_nop 0
	v_add_f32_e32 v229, 1.0, v228
	v_div_scale_f32 v230, s[4:5], v229, v229, 1.0
	v_rcp_f32_e32 v231, v230
	v_div_scale_f32 v232, vcc, 1.0, v229, 1.0
	v_fma_f32 v131, -v230, v231, 1.0
	v_fmac_f32_e32 v231, v131, v231
	v_mul_f32_e32 v233, v232, v231
	v_fma_f32 v131, -v230, v233, v232
	v_fmac_f32_e32 v233, v131, v231
	v_fma_f32 v230, -v230, v233, v232
	v_div_fmas_f32 v230, v230, v231, v233
	v_div_fixup_f32 v135, v230, v229, 1.0
	v_mul_f32_e32 v228, 0xbfb8aa3b, v117
	v_exp_f32_e32 v228, v228
	s_nop 0
	v_add_f32_e32 v229, 1.0, v228
	v_div_scale_f32 v230, s[4:5], v229, v229, 1.0
	v_rcp_f32_e32 v231, v230
	v_div_scale_f32 v232, vcc, 1.0, v229, 1.0
	v_fma_f32 v131, -v230, v231, 1.0
	v_fmac_f32_e32 v231, v131, v231
	v_mul_f32_e32 v233, v232, v231
	v_fma_f32 v131, -v230, v233, v232
	v_fmac_f32_e32 v233, v131, v231
	v_fma_f32 v230, -v230, v233, v232
	v_div_fmas_f32 v230, v230, v231, v233
	v_div_fixup_f32 v133, v230, v229, 1.0
	v_cvt_pk_bf16_f32 v133, v135, v133
	global_store_dword v[226:227], v133, off
	v_mul_f32_e32 v228, 0xbfb8aa3b, v121
	v_exp_f32_e32 v228, v228
	s_nop 0
	v_add_f32_e32 v229, 1.0, v228
	v_div_scale_f32 v230, s[4:5], v229, v229, 1.0
	v_rcp_f32_e32 v231, v230
	v_div_scale_f32 v232, vcc, 1.0, v229, 1.0
	v_fma_f32 v131, -v230, v231, 1.0
	v_fmac_f32_e32 v231, v131, v231
	v_mul_f32_e32 v233, v232, v231
	v_fma_f32 v131, -v230, v233, v232
	v_fmac_f32_e32 v233, v131, v231
	v_fma_f32 v230, -v230, v233, v232
	v_div_fmas_f32 v230, v230, v231, v233
	v_div_fixup_f32 v135, v230, v229, 1.0
	v_mul_f32_e32 v228, 0xbfb8aa3b, v125
	v_exp_f32_e32 v228, v228
	s_nop 0
	v_add_f32_e32 v229, 1.0, v228
	v_div_scale_f32 v230, s[4:5], v229, v229, 1.0
	v_rcp_f32_e32 v231, v230
	v_div_scale_f32 v232, vcc, 1.0, v229, 1.0
	v_fma_f32 v131, -v230, v231, 1.0
	v_fmac_f32_e32 v231, v131, v231
	v_mul_f32_e32 v233, v232, v231
	v_fma_f32 v131, -v230, v233, v232
	v_fmac_f32_e32 v233, v131, v231
	v_fma_f32 v230, -v230, v233, v232
	v_div_fmas_f32 v230, v230, v231, v233
	v_div_fixup_f32 v133, v230, v229, 1.0
	v_cvt_pk_bf16_f32 v133, v135, v133
	global_store_dword v[226:227], v133, off offset:64
	s_mov_b64 s[4:5], 0x300
	v_lshl_add_u64 v[226:227], v[226:227], 0, s[4:5]
	v_mul_f32_e32 v228, 0xbfb8aa3b, v114
	v_exp_f32_e32 v228, v228
	s_nop 0
	v_add_f32_e32 v229, 1.0, v228
	v_div_scale_f32 v230, s[4:5], v229, v229, 1.0
	v_rcp_f32_e32 v231, v230
	v_div_scale_f32 v232, vcc, 1.0, v229, 1.0
	v_fma_f32 v131, -v230, v231, 1.0
	v_fmac_f32_e32 v231, v131, v231
	v_mul_f32_e32 v233, v232, v231
	v_fma_f32 v131, -v230, v233, v232
	v_fmac_f32_e32 v233, v131, v231
	v_fma_f32 v230, -v230, v233, v232
	v_div_fmas_f32 v230, v230, v231, v233
	v_div_fixup_f32 v135, v230, v229, 1.0
	v_mul_f32_e32 v228, 0xbfb8aa3b, v118
	v_exp_f32_e32 v228, v228
	s_nop 0
	v_add_f32_e32 v229, 1.0, v228
	v_div_scale_f32 v230, s[4:5], v229, v229, 1.0
	v_rcp_f32_e32 v231, v230
	v_div_scale_f32 v232, vcc, 1.0, v229, 1.0
	v_fma_f32 v131, -v230, v231, 1.0
	v_fmac_f32_e32 v231, v131, v231
	v_mul_f32_e32 v233, v232, v231
	v_fma_f32 v131, -v230, v233, v232
	v_fmac_f32_e32 v233, v131, v231
	v_fma_f32 v230, -v230, v233, v232
	v_div_fmas_f32 v230, v230, v231, v233
	v_div_fixup_f32 v133, v230, v229, 1.0
	v_cvt_pk_bf16_f32 v133, v135, v133
	global_store_dword v[226:227], v133, off
	v_mul_f32_e32 v228, 0xbfb8aa3b, v122
	v_exp_f32_e32 v228, v228
	s_nop 0
	v_add_f32_e32 v229, 1.0, v228
	v_div_scale_f32 v230, s[4:5], v229, v229, 1.0
	v_rcp_f32_e32 v231, v230
	v_div_scale_f32 v232, vcc, 1.0, v229, 1.0
	v_fma_f32 v131, -v230, v231, 1.0
	v_fmac_f32_e32 v231, v131, v231
	v_mul_f32_e32 v233, v232, v231
	v_fma_f32 v131, -v230, v233, v232
	v_fmac_f32_e32 v233, v131, v231
	v_fma_f32 v230, -v230, v233, v232
	v_div_fmas_f32 v230, v230, v231, v233
	v_div_fixup_f32 v135, v230, v229, 1.0
	v_mul_f32_e32 v228, 0xbfb8aa3b, v126
	v_exp_f32_e32 v228, v228
	s_nop 0
	v_add_f32_e32 v229, 1.0, v228
	v_div_scale_f32 v230, s[4:5], v229, v229, 1.0
	v_rcp_f32_e32 v231, v230
	v_div_scale_f32 v232, vcc, 1.0, v229, 1.0
	v_fma_f32 v131, -v230, v231, 1.0
	v_fmac_f32_e32 v231, v131, v231
	v_mul_f32_e32 v233, v232, v231
	v_fma_f32 v131, -v230, v233, v232
	v_fmac_f32_e32 v233, v131, v231
	v_fma_f32 v230, -v230, v233, v232
	v_div_fmas_f32 v230, v230, v231, v233
	v_div_fixup_f32 v133, v230, v229, 1.0
	v_cvt_pk_bf16_f32 v133, v135, v133
	global_store_dword v[226:227], v133, off offset:64
	s_mov_b64 s[4:5], 0x300
	v_lshl_add_u64 v[226:227], v[226:227], 0, s[4:5]
	v_mul_f32_e32 v228, 0xbfb8aa3b, v115
	v_exp_f32_e32 v228, v228
	s_nop 0
	v_add_f32_e32 v229, 1.0, v228
	v_div_scale_f32 v230, s[4:5], v229, v229, 1.0
	v_rcp_f32_e32 v231, v230
	v_div_scale_f32 v232, vcc, 1.0, v229, 1.0
	v_fma_f32 v131, -v230, v231, 1.0
	v_fmac_f32_e32 v231, v131, v231
	v_mul_f32_e32 v233, v232, v231
	v_fma_f32 v131, -v230, v233, v232
	v_fmac_f32_e32 v233, v131, v231
	v_fma_f32 v230, -v230, v233, v232
	v_div_fmas_f32 v230, v230, v231, v233
	v_div_fixup_f32 v135, v230, v229, 1.0
	v_mul_f32_e32 v228, 0xbfb8aa3b, v119
	v_exp_f32_e32 v228, v228
	s_nop 0
	v_add_f32_e32 v229, 1.0, v228
	v_div_scale_f32 v230, s[4:5], v229, v229, 1.0
	v_rcp_f32_e32 v231, v230
	v_div_scale_f32 v232, vcc, 1.0, v229, 1.0
	v_fma_f32 v131, -v230, v231, 1.0
	v_fmac_f32_e32 v231, v131, v231
	v_mul_f32_e32 v233, v232, v231
	v_fma_f32 v131, -v230, v233, v232
	v_fmac_f32_e32 v233, v131, v231
	v_fma_f32 v230, -v230, v233, v232
	v_div_fmas_f32 v230, v230, v231, v233
	v_div_fixup_f32 v133, v230, v229, 1.0
	v_cvt_pk_bf16_f32 v133, v135, v133
	global_store_dword v[226:227], v133, off
	v_mul_f32_e32 v228, 0xbfb8aa3b, v123
	v_exp_f32_e32 v228, v228
	s_nop 0
	v_add_f32_e32 v229, 1.0, v228
	v_div_scale_f32 v230, s[4:5], v229, v229, 1.0
	v_rcp_f32_e32 v231, v230
	v_div_scale_f32 v232, vcc, 1.0, v229, 1.0
	v_fma_f32 v131, -v230, v231, 1.0
	v_fmac_f32_e32 v231, v131, v231
	v_mul_f32_e32 v233, v232, v231
	v_fma_f32 v131, -v230, v233, v232
	v_fmac_f32_e32 v233, v131, v231
	v_fma_f32 v230, -v230, v233, v232
	v_div_fmas_f32 v230, v230, v231, v233
	v_div_fixup_f32 v135, v230, v229, 1.0
	v_mul_f32_e32 v228, 0xbfb8aa3b, v127
	v_exp_f32_e32 v228, v228
	s_nop 0
	v_add_f32_e32 v229, 1.0, v228
	v_div_scale_f32 v230, s[4:5], v229, v229, 1.0
	v_rcp_f32_e32 v231, v230
	v_div_scale_f32 v232, vcc, 1.0, v229, 1.0
	v_fma_f32 v131, -v230, v231, 1.0
	v_fmac_f32_e32 v231, v131, v231
	v_mul_f32_e32 v233, v232, v231
	v_fma_f32 v131, -v230, v233, v232
	v_fmac_f32_e32 v233, v131, v231
	v_fma_f32 v230, -v230, v233, v232
	v_div_fmas_f32 v230, v230, v231, v233
	v_div_fixup_f32 v133, v230, v229, 1.0
	v_cvt_pk_bf16_f32 v133, v135, v133
	global_store_dword v[226:227], v133, off offset:64
.Lip_nolin:
	s_cmp_ge_u32 s54, 1296
	s_cbranch_scc1 .Lip_done
	s_lshr_b32 s55, s54, 4
	s_mul_hi_u32 s55, s55, 0x55555556
	s_mul_i32 s53, s55, 48
	s_sub_u32 s53, s54, s53
	v_readlane_b32 s4, v235, 34
	v_readlane_b32 s5, v235, 35
	s_mov_b32 s56, s55
	s_mul_i32 s46, s53, 0x360000
	s_lshl_b32 s57, s55, 9
	s_add_u32 s46, s46, s57
	s_add_u32 s46, s46, 0xfae6000
	s_add_u32 s46, s46, s4
	s_addc_u32 s47, s5, 0
	s_mul_i32 s50, s53, 0x30000
	s_lshl_b32 s57, s55, 8
	s_add_u32 s50, s50, s57
	s_add_u32 s50, s50, 0x19ce5a00
	s_add_u32 s50, s50, s4
	s_addc_u32 s51, s5, 0
	s_branch .Lip_tile
.Lip_done:
	s_waitcnt vmcnt(0)
	s_branch .LBB0_1197
.LBB0_1197:
	s_mov_b64 s[34:35], 0

.Lfi_entry:
	v_and_b32_e32 v225, 63, v170
	v_lshrrev_b32_e32 v226, 6, v170
	v_lshrrev_b32_e32 v227, 1, v226
	v_and_b32_e32 v228, 1, v226
	v_and_b32_e32 v229, 15, v225
	v_lshrrev_b32_e32 v230, 4, v225
	v_lshlrev_b32_e32 v231, 10, v226
	v_lshrrev_b32_e32 v232, 3, v170
	v_readfirstlane_b32 s52, v231
	v_and_b32_e32 v233, 7, v170
	v_bfe_u32 v224, v232, 1, 3
	v_xor_b32_e32 v233, v233, v224
	v_lshlrev_b32_e32 v233, 4, v233
	s_movk_i32 s4, 0x880
	v_mad_u32_u24 v224, v232, s4, v233
	v_lshrrev_b32_e32 v232, 3, v170
	v_and_b32_e32 v233, 15, v232
	v_lshlrev_b32_e32 v233, 1, v233
	v_lshrrev_b32_e32 v168, 4, v232
	v_add_u32_e32 v233, v233, v168
	v_and_b32_e32 v168, 7, v170
	v_bfe_u32 v169, v232, 1, 3
	v_xor_b32_e32 v168, v168, v169
	v_lshlrev_b32_e32 v168, 4, v168
	v_mad_u32_u24 v168, v233, s4, v168
	v_bfe_u32 v233, v229, 1, 3
	v_xor_b32_e32 v231, v230, v233
	v_or_b32_e32 v232, 4, v230
	v_xor_b32_e32 v232, v232, v233
	v_lshlrev_b32_e32 v231, 4, v231
	v_lshlrev_b32_e32 v232, 4, v232
	v_lshl_add_u32 v233, v227, 7, v229
	v_lshlrev_b32_e32 v233, 7, v233
	v_add_u32_e32 v220, v233, v231
	v_add_u32_e32 v221, v233, v232
	v_lshl_add_u32 v233, v228, 6, v229
	v_lshlrev_b32_e32 v233, 7, v233
	v_add_u32_e32 v233, 0x8000, v233
	v_add_u32_e32 v222, v233, v231
	v_add_u32_e32 v223, v233, v232
	v_lshlrev_b32_e32 v231, 7, v227
	v_lshl_add_u32 v231, v230, 2, v231
	s_movk_i32 s4, 0x1680
	v_lshlrev_b32_e32 v232, 4, v228
	v_add_u32_e32 v232, v232, v229
	v_lshlrev_b32_e32 v232, 2, v232
	v_mad_u32_u24 v225, v231, s4, v232
	v_readlane_b32 s54, v237, 0
	s_cmp_ge_u32 s54, 2112
	s_cbranch_scc1 .Lfi_done
	s_lshr_b32 s55, s54, 4
	s_mul_hi_u32 s55, s55, 0x55555556
	s_mul_i32 s53, s55, 48
	s_sub_u32 s53, s54, s53
	v_readlane_b32 s4, v235, 34
	v_readlane_b32 s5, v235, 35
	s_mul_i32 s44, s53, 0x88000
	s_add_u32 s44, s44, 0xe166000
	s_add_u32 s44, s44, s4
	s_addc_u32 s45, s5, 0
	s_mul_i32 s46, s55, 0x44000
	s_add_u32 s46, s46, s36
	s_addc_u32 s47, s37, 0
	s_lshr_b32 s55, s54, 4
	s_mul_hi_u32 s55, s55, 0x55555556
	s_mul_i32 s53, s55, 48
	s_sub_u32 s53, s54, s53
	v_readlane_b32 s4, v235, 34
	v_readlane_b32 s5, v235, 35
	s_mul_i32 s50, s53, 0x168000
	s_lshl_b32 s55, s55, 7
	s_add_u32 s50, s50, s55
	s_add_u32 s50, s50, 0xfae6000
	s_add_u32 s50, s50, s4
	s_addc_u32 s51, s5, 0
	s_add_u32 m0, s52, 0x0
	s_add_u32 s4, s44, 0x0
	s_addc_u32 s5, s45, 0
	global_load_lds_dwordx4 v224, s[4:5]
	s_add_u32 m0, s52, 0x1000
	s_add_u32 s4, s44, 0x11000
	s_addc_u32 s5, s45, 0
	global_load_lds_dwordx4 v224, s[4:5]
	s_add_u32 m0, s52, 0x2000
	s_add_u32 s4, s44, 0x22000
	s_addc_u32 s5, s45, 0
	global_load_lds_dwordx4 v224, s[4:5]
	s_add_u32 m0, s52, 0x3000
	s_add_u32 s4, s44, 0x33000
	s_addc_u32 s5, s45, 0
	global_load_lds_dwordx4 v224, s[4:5]
	s_add_u32 m0, s52, 0x4000
	s_add_u32 s4, s44, 0x44000
	s_addc_u32 s5, s45, 0
	global_load_lds_dwordx4 v224, s[4:5]
	s_add_u32 m0, s52, 0x5000
	s_add_u32 s4, s44, 0x55000
	s_addc_u32 s5, s45, 0
	global_load_lds_dwordx4 v224, s[4:5]
	s_add_u32 m0, s52, 0x6000
	s_add_u32 s4, s44, 0x66000
	s_addc_u32 s5, s45, 0
	global_load_lds_dwordx4 v224, s[4:5]
	s_add_u32 m0, s52, 0x7000
	s_add_u32 s4, s44, 0x77000
	s_addc_u32 s5, s45, 0
	global_load_lds_dwordx4 v224, s[4:5]
	s_add_u32 m0, s52, 0x8000
	s_add_u32 s4, s46, 0x0
	s_addc_u32 s5, s47, 0
	global_load_lds_dwordx4 v168, s[4:5]
	s_add_u32 m0, s52, 0x9000
	s_add_u32 s4, s46, 0x11000
	s_addc_u32 s5, s47, 0
	global_load_lds_dwordx4 v168, s[4:5]
	s_add_u32 m0, s52, 0xa000
	s_add_u32 s4, s46, 0x22000
	s_addc_u32 s5, s47, 0
	global_load_lds_dwordx4 v168, s[4:5]
	s_add_u32 m0, s52, 0xb000
	s_add_u32 s4, s46, 0x33000
	s_addc_u32 s5, s47, 0
	global_load_lds_dwordx4 v168, s[4:5]
	s_add_u32 s44, s44, 0x80
	s_addc_u32 s45, s45, 0
	s_add_u32 s46, s46, 0x80
	s_addc_u32 s47, s47, 0

.Lfi_k:
	s_waitcnt vmcnt(0)
	s_barrier
	ds_read_b128 v[204:207], v222
	ds_read_b128 v[208:211], v222 offset:2048
	ds_read_b128 v[212:215], v222 offset:4096
	ds_read_b128 v[216:219], v222 offset:6144
	ds_read_b128 a[0:3], v223
	ds_read_b128 a[4:7], v223 offset:2048
	ds_read_b128 a[8:11], v223 offset:4096
	ds_read_b128 a[12:15], v223 offset:6144
	ds_read_b128 v[136:139], v220
	ds_read_b128 v[140:143], v220 offset:2048
	ds_read_b128 v[144:147], v220 offset:4096
	ds_read_b128 v[148:151], v220 offset:6144
	ds_read_b128 v[152:155], v220 offset:8192
	ds_read_b128 v[156:159], v220 offset:10240
	ds_read_b128 v[160:163], v220 offset:12288
	ds_read_b128 v[164:167], v220 offset:14336
	s_waitcnt lgkmcnt(7)
	v_mfma_f32_16x16x32_bf16 v[0:3], v[136:139], v[204:207], v[0:3]
	v_mfma_f32_16x16x32_bf16 v[4:7], v[136:139], v[208:211], v[4:7]
	v_mfma_f32_16x16x32_bf16 v[8:11], v[136:139], v[212:215], v[8:11]
	v_mfma_f32_16x16x32_bf16 v[12:15], v[136:139], v[216:219], v[12:15]
	ds_read_b128 v[136:139], v221
	s_waitcnt lgkmcnt(7)
	v_mfma_f32_16x16x32_bf16 v[16:19], v[140:143], v[204:207], v[16:19]
	v_mfma_f32_16x16x32_bf16 v[20:23], v[140:143], v[208:211], v[20:23]
	v_mfma_f32_16x16x32_bf16 v[24:27], v[140:143], v[212:215], v[24:27]
	v_mfma_f32_16x16x32_bf16 v[28:31], v[140:143], v[216:219], v[28:31]
	ds_read_b128 v[140:143], v221 offset:2048
	s_waitcnt lgkmcnt(7)
	v_mfma_f32_16x16x32_bf16 v[32:35], v[144:147], v[204:207], v[32:35]
	v_mfma_f32_16x16x32_bf16 v[36:39], v[144:147], v[208:211], v[36:39]
	v_mfma_f32_16x16x32_bf16 v[40:43], v[144:147], v[212:215], v[40:43]
	v_mfma_f32_16x16x32_bf16 v[44:47], v[144:147], v[216:219], v[44:47]
	ds_read_b128 v[144:147], v221 offset:4096
	s_waitcnt lgkmcnt(7)
	v_mfma_f32_16x16x32_bf16 v[48:51], v[148:151], v[204:207], v[48:51]
	v_mfma_f32_16x16x32_bf16 v[52:55], v[148:151], v[208:211], v[52:55]
	v_mfma_f32_16x16x32_bf16 v[56:59], v[148:151], v[212:215], v[56:59]
	v_mfma_f32_16x16x32_bf16 v[60:63], v[148:151], v[216:219], v[60:63]
	ds_read_b128 v[148:151], v221 offset:6144
	s_waitcnt lgkmcnt(7)
	v_mfma_f32_16x16x32_bf16 v[64:67], v[152:155], v[204:207], v[64:67]
	v_mfma_f32_16x16x32_bf16 v[68:71], v[152:155], v[208:211], v[68:71]
	v_mfma_f32_16x16x32_bf16 v[72:75], v[152:155], v[212:215], v[72:75]
	v_mfma_f32_16x16x32_bf16 v[76:79], v[152:155], v[216:219], v[76:79]
	ds_read_b128 v[152:155], v221 offset:8192
	s_waitcnt lgkmcnt(7)
	v_mfma_f32_16x16x32_bf16 v[80:83], v[156:159], v[204:207], v[80:83]
	v_mfma_f32_16x16x32_bf16 v[84:87], v[156:159], v[208:211], v[84:87]
	v_mfma_f32_16x16x32_bf16 v[88:91], v[156:159], v[212:215], v[88:91]
	v_mfma_f32_16x16x32_bf16 v[92:95], v[156:159], v[216:219], v[92:95]
	ds_read_b128 v[156:159], v221 offset:10240
	s_waitcnt lgkmcnt(7)
	v_mfma_f32_16x16x32_bf16 v[96:99], v[160:163], v[204:207], v[96:99]
	v_mfma_f32_16x16x32_bf16 v[100:103], v[160:163], v[208:211], v[100:103]
	v_mfma_f32_16x16x32_bf16 v[104:107], v[160:163], v[212:215], v[104:107]
	v_mfma_f32_16x16x32_bf16 v[108:111], v[160:163], v[216:219], v[108:111]
	ds_read_b128 v[160:163], v221 offset:12288
	s_waitcnt lgkmcnt(7)
	v_mfma_f32_16x16x32_bf16 v[112:115], v[164:167], v[204:207], v[112:115]
	v_mfma_f32_16x16x32_bf16 v[116:119], v[164:167], v[208:211], v[116:119]
	v_mfma_f32_16x16x32_bf16 v[120:123], v[164:167], v[212:215], v[120:123]
	v_mfma_f32_16x16x32_bf16 v[124:127], v[164:167], v[216:219], v[124:127]
	ds_read_b128 v[164:167], v221 offset:14336
	s_waitcnt lgkmcnt(0)
	s_barrier
	s_cmp_eq_u32 s53, 15
	s_cbranch_scc1 .Lfi_last
	s_add_u32 m0, s52, 0x0
	s_add_u32 s4, s44, 0x0
	s_addc_u32 s5, s45, 0
	global_load_lds_dwordx4 v224, s[4:5]
	s_add_u32 m0, s52, 0x1000
	s_add_u32 s4, s44, 0x11000
	s_addc_u32 s5, s45, 0
	global_load_lds_dwordx4 v224, s[4:5]
	s_add_u32 m0, s52, 0x2000
	s_add_u32 s4, s44, 0x22000
	s_addc_u32 s5, s45, 0
	global_load_lds_dwordx4 v224, s[4:5]
	s_add_u32 m0, s52, 0x3000
	s_add_u32 s4, s44, 0x33000
	s_addc_u32 s5, s45, 0
	global_load_lds_dwordx4 v224, s[4:5]
	s_add_u32 m0, s52, 0x4000
	s_add_u32 s4, s44, 0x44000
	s_addc_u32 s5, s45, 0
	global_load_lds_dwordx4 v224, s[4:5]
	s_add_u32 m0, s52, 0x5000
	s_add_u32 s4, s44, 0x55000
	s_addc_u32 s5, s45, 0
	global_load_lds_dwordx4 v224, s[4:5]
	s_add_u32 m0, s52, 0x6000
	s_add_u32 s4, s44, 0x66000
	s_addc_u32 s5, s45, 0
	global_load_lds_dwordx4 v224, s[4:5]
	s_add_u32 m0, s52, 0x7000
	s_add_u32 s4, s44, 0x77000
	s_addc_u32 s5, s45, 0
	global_load_lds_dwordx4 v224, s[4:5]
	s_add_u32 m0, s52, 0x8000
	s_add_u32 s4, s46, 0x0
	s_addc_u32 s5, s47, 0
	global_load_lds_dwordx4 v168, s[4:5]
	s_add_u32 m0, s52, 0x9000
	s_add_u32 s4, s46, 0x11000
	s_addc_u32 s5, s47, 0
	global_load_lds_dwordx4 v168, s[4:5]
	s_add_u32 m0, s52, 0xa000
	s_add_u32 s4, s46, 0x22000
	s_addc_u32 s5, s47, 0
	global_load_lds_dwordx4 v168, s[4:5]
	s_add_u32 m0, s52, 0xb000
	s_add_u32 s4, s46, 0x33000
	s_addc_u32 s5, s47, 0
	global_load_lds_dwordx4 v168, s[4:5]
	s_add_u32 s44, s44, 0x80
	s_addc_u32 s45, s45, 0
	s_add_u32 s46, s46, 0x80
	s_addc_u32 s47, s47, 0
	v_mfma_f32_16x16x32_bf16 v[0:3], v[136:139], a[0:3], v[0:3]
	v_mfma_f32_16x16x32_bf16 v[4:7], v[136:139], a[4:7], v[4:7]
	v_mfma_f32_16x16x32_bf16 v[8:11], v[136:139], a[8:11], v[8:11]
	v_mfma_f32_16x16x32_bf16 v[12:15], v[136:139], a[12:15], v[12:15]
	v_mfma_f32_16x16x32_bf16 v[16:19], v[140:143], a[0:3], v[16:19]
	v_mfma_f32_16x16x32_bf16 v[20:23], v[140:143], a[4:7], v[20:23]
	v_mfma_f32_16x16x32_bf16 v[24:27], v[140:143], a[8:11], v[24:27]
	v_mfma_f32_16x16x32_bf16 v[28:31], v[140:143], a[12:15], v[28:31]
	v_mfma_f32_16x16x32_bf16 v[32:35], v[144:147], a[0:3], v[32:35]
	v_mfma_f32_16x16x32_bf16 v[36:39], v[144:147], a[4:7], v[36:39]
	v_mfma_f32_16x16x32_bf16 v[40:43], v[144:147], a[8:11], v[40:43]
	v_mfma_f32_16x16x32_bf16 v[44:47], v[144:147], a[12:15], v[44:47]
	v_mfma_f32_16x16x32_bf16 v[48:51], v[148:151], a[0:3], v[48:51]
	v_mfma_f32_16x16x32_bf16 v[52:55], v[148:151], a[4:7], v[52:55]
	v_mfma_f32_16x16x32_bf16 v[56:59], v[148:151], a[8:11], v[56:59]
	v_mfma_f32_16x16x32_bf16 v[60:63], v[148:151], a[12:15], v[60:63]
	v_mfma_f32_16x16x32_bf16 v[64:67], v[152:155], a[0:3], v[64:67]
	v_mfma_f32_16x16x32_bf16 v[68:71], v[152:155], a[4:7], v[68:71]
	v_mfma_f32_16x16x32_bf16 v[72:75], v[152:155], a[8:11], v[72:75]
	v_mfma_f32_16x16x32_bf16 v[76:79], v[152:155], a[12:15], v[76:79]
	v_mfma_f32_16x16x32_bf16 v[80:83], v[156:159], a[0:3], v[80:83]
	v_mfma_f32_16x16x32_bf16 v[84:87], v[156:159], a[4:7], v[84:87]
	v_mfma_f32_16x16x32_bf16 v[88:91], v[156:159], a[8:11], v[88:91]
	v_mfma_f32_16x16x32_bf16 v[92:95], v[156:159], a[12:15], v[92:95]
	v_mfma_f32_16x16x32_bf16 v[96:99], v[160:163], a[0:3], v[96:99]
	v_mfma_f32_16x16x32_bf16 v[100:103], v[160:163], a[4:7], v[100:103]
	v_mfma_f32_16x16x32_bf16 v[104:107], v[160:163], a[8:11], v[104:107]
	v_mfma_f32_16x16x32_bf16 v[108:111], v[160:163], a[12:15], v[108:111]
	v_mfma_f32_16x16x32_bf16 v[112:115], v[164:167], a[0:3], v[112:115]
	v_mfma_f32_16x16x32_bf16 v[116:119], v[164:167], a[4:7], v[116:119]
	v_mfma_f32_16x16x32_bf16 v[120:123], v[164:167], a[8:11], v[120:123]
	v_mfma_f32_16x16x32_bf16 v[124:127], v[164:167], a[12:15], v[124:127]
	s_add_u32 s53, s53, 1
	s_branch .Lfi_k
.Lfi_last:
	v_readlane_b32 s55, v235, 33
	s_add_u32 s54, s54, s55
	s_cmp_ge_u32 s54, 2112
	s_cbranch_scc1 .Lfi_nopf
	s_lshr_b32 s55, s54, 4
	s_mul_hi_u32 s55, s55, 0x55555556
	s_mul_i32 s53, s55, 48
	s_sub_u32 s53, s54, s53
	v_readlane_b32 s4, v235, 34
	v_readlane_b32 s5, v235, 35
	s_mul_i32 s44, s53, 0x88000
	s_add_u32 s44, s44, 0xe166000
	s_add_u32 s44, s44, s4
	s_addc_u32 s45, s5, 0
	s_mul_i32 s46, s55, 0x44000
	s_add_u32 s46, s46, s36
	s_addc_u32 s47, s37, 0
	s_add_u32 m0, s52, 0x0
	s_add_u32 s4, s44, 0x0
	s_addc_u32 s5, s45, 0
	global_load_lds_dwordx4 v224, s[4:5]
	s_add_u32 m0, s52, 0x1000
	s_add_u32 s4, s44, 0x11000
	s_addc_u32 s5, s45, 0
	global_load_lds_dwordx4 v224, s[4:5]
	s_add_u32 m0, s52, 0x2000
	s_add_u32 s4, s44, 0x22000
	s_addc_u32 s5, s45, 0
	global_load_lds_dwordx4 v224, s[4:5]
	s_add_u32 m0, s52, 0x3000
	s_add_u32 s4, s44, 0x33000
	s_addc_u32 s5, s45, 0
	global_load_lds_dwordx4 v224, s[4:5]
	s_add_u32 m0, s52, 0x4000
	s_add_u32 s4, s44, 0x44000
	s_addc_u32 s5, s45, 0
	global_load_lds_dwordx4 v224, s[4:5]
	s_add_u32 m0, s52, 0x5000
	s_add_u32 s4, s44, 0x55000
	s_addc_u32 s5, s45, 0
	global_load_lds_dwordx4 v224, s[4:5]
	s_add_u32 m0, s52, 0x6000
	s_add_u32 s4, s44, 0x66000
	s_addc_u32 s5, s45, 0
	global_load_lds_dwordx4 v224, s[4:5]
	s_add_u32 m0, s52, 0x7000
	s_add_u32 s4, s44, 0x77000
	s_addc_u32 s5, s45, 0
	global_load_lds_dwordx4 v224, s[4:5]
	s_add_u32 m0, s52, 0x8000
	s_add_u32 s4, s46, 0x0
	s_addc_u32 s5, s47, 0
	global_load_lds_dwordx4 v168, s[4:5]
	s_add_u32 m0, s52, 0x9000
	s_add_u32 s4, s46, 0x11000
	s_addc_u32 s5, s47, 0
	global_load_lds_dwordx4 v168, s[4:5]
	s_add_u32 m0, s52, 0xa000
	s_add_u32 s4, s46, 0x22000
	s_addc_u32 s5, s47, 0
	global_load_lds_dwordx4 v168, s[4:5]
	s_add_u32 m0, s52, 0xb000
	s_add_u32 s4, s46, 0x33000
	s_addc_u32 s5, s47, 0
	global_load_lds_dwordx4 v168, s[4:5]
	s_add_u32 s44, s44, 0x80
	s_addc_u32 s45, s45, 0
	s_add_u32 s46, s46, 0x80
	s_addc_u32 s47, s47, 0
.Lfi_nopf:
	v_mfma_f32_16x16x32_bf16 v[0:3], v[136:139], a[0:3], v[0:3]
	v_mfma_f32_16x16x32_bf16 v[4:7], v[136:139], a[4:7], v[4:7]
	v_mfma_f32_16x16x32_bf16 v[8:11], v[136:139], a[8:11], v[8:11]
	v_mfma_f32_16x16x32_bf16 v[12:15], v[136:139], a[12:15], v[12:15]
	v_mfma_f32_16x16x32_bf16 v[16:19], v[140:143], a[0:3], v[16:19]
	v_mfma_f32_16x16x32_bf16 v[20:23], v[140:143], a[4:7], v[20:23]
	v_mfma_f32_16x16x32_bf16 v[24:27], v[140:143], a[8:11], v[24:27]
	v_mfma_f32_16x16x32_bf16 v[28:31], v[140:143], a[12:15], v[28:31]
	v_mfma_f32_16x16x32_bf16 v[32:35], v[144:147], a[0:3], v[32:35]
	v_mfma_f32_16x16x32_bf16 v[36:39], v[144:147], a[4:7], v[36:39]
	v_mfma_f32_16x16x32_bf16 v[40:43], v[144:147], a[8:11], v[40:43]
	v_mfma_f32_16x16x32_bf16 v[44:47], v[144:147], a[12:15], v[44:47]
	v_mfma_f32_16x16x32_bf16 v[48:51], v[148:151], a[0:3], v[48:51]
	v_mfma_f32_16x16x32_bf16 v[52:55], v[148:151], a[4:7], v[52:55]
	v_mfma_f32_16x16x32_bf16 v[56:59], v[148:151], a[8:11], v[56:59]
	v_mfma_f32_16x16x32_bf16 v[60:63], v[148:151], a[12:15], v[60:63]
	v_mfma_f32_16x16x32_bf16 v[64:67], v[152:155], a[0:3], v[64:67]
	v_mfma_f32_16x16x32_bf16 v[68:71], v[152:155], a[4:7], v[68:71]
	v_mfma_f32_16x16x32_bf16 v[72:75], v[152:155], a[8:11], v[72:75]
	v_mfma_f32_16x16x32_bf16 v[76:79], v[152:155], a[12:15], v[76:79]
	v_mfma_f32_16x16x32_bf16 v[80:83], v[156:159], a[0:3], v[80:83]
	v_mfma_f32_16x16x32_bf16 v[84:87], v[156:159], a[4:7], v[84:87]
	v_mfma_f32_16x16x32_bf16 v[88:91], v[156:159], a[8:11], v[88:91]
	v_mfma_f32_16x16x32_bf16 v[92:95], v[156:159], a[12:15], v[92:95]
	v_mfma_f32_16x16x32_bf16 v[96:99], v[160:163], a[0:3], v[96:99]
	v_mfma_f32_16x16x32_bf16 v[100:103], v[160:163], a[4:7], v[100:103]
	v_mfma_f32_16x16x32_bf16 v[104:107], v[160:163], a[8:11], v[104:107]
	v_mfma_f32_16x16x32_bf16 v[108:111], v[160:163], a[12:15], v[108:111]
	v_mfma_f32_16x16x32_bf16 v[112:115], v[164:167], a[0:3], v[112:115]
	v_mfma_f32_16x16x32_bf16 v[116:119], v[164:167], a[4:7], v[116:119]
	v_mfma_f32_16x16x32_bf16 v[120:123], v[164:167], a[8:11], v[120:123]
	v_mfma_f32_16x16x32_bf16 v[124:127], v[164:167], a[12:15], v[124:127]
	s_nop 7
	s_nop 7
	v_mov_b32_e32 v226, s50
	v_mov_b32_e32 v227, s51
	v_add_co_u32_e32 v226, vcc, v226, v225
	s_nop 1
	v_addc_co_u32_e32 v227, vcc, 0, v227, vcc
	s_mov_b64 s[56:57], 0x1680
	s_mov_b64 s[40:41], 0x12480
	v_mul_f32_e32 v228, 0xbfb8aa3b, v0
	v_exp_f32_e32 v228, v228
	s_nop 0
	v_add_f32_e32 v229, 1.0, v228
	v_div_scale_f32 v230, s[4:5], v229, v229, v0
	v_rcp_f32_e32 v231, v230
	v_div_scale_f32 v232, vcc, v0, v229, v0
	s_nop 0
	v_fma_f32 v131, -v230, v231, 1.0
	v_fmac_f32_e32 v231, v131, v231
	v_mul_f32_e32 v233, v232, v231
	v_fma_f32 v131, -v230, v233, v232
	v_fmac_f32_e32 v233, v131, v231
	v_fma_f32 v230, -v230, v233, v232
	v_div_fmas_f32 v230, v230, v231, v233
	v_div_fixup_f32 v135, v230, v229, v0
	v_mul_f32_e32 v135, v8, v135
	v_mul_f32_e32 v228, 0xbfb8aa3b, v4
	v_exp_f32_e32 v228, v228
	s_nop 0
	v_add_f32_e32 v229, 1.0, v228
	v_div_scale_f32 v230, s[4:5], v229, v229, v4
	v_rcp_f32_e32 v231, v230
	v_div_scale_f32 v232, vcc, v4, v229, v4
	s_nop 0
	v_fma_f32 v131, -v230, v231, 1.0
	v_fmac_f32_e32 v231, v131, v231
	v_mul_f32_e32 v233, v232, v231
	v_fma_f32 v131, -v230, v233, v232
	v_fmac_f32_e32 v233, v131, v231
	v_fma_f32 v230, -v230, v233, v232
	v_div_fmas_f32 v230, v230, v231, v233
	v_div_fixup_f32 v133, v230, v229, v4
	v_mul_f32_e32 v133, v12, v133
	v_cvt_pk_bf16_f32 v133, v135, v133
	global_store_dword v[226:227], v133, off
	v_lshl_add_u64 v[226:227], v[226:227], 0, s[56:57]
	v_mul_f32_e32 v228, 0xbfb8aa3b, v1
	v_exp_f32_e32 v228, v228
	s_nop 0
	v_add_f32_e32 v229, 1.0, v228
	v_div_scale_f32 v230, s[4:5], v229, v229, v1
	v_rcp_f32_e32 v231, v230
	v_div_scale_f32 v232, vcc, v1, v229, v1
	s_nop 0
	v_fma_f32 v131, -v230, v231, 1.0
	v_fmac_f32_e32 v231, v131, v231
	v_mul_f32_e32 v233, v232, v231
	v_fma_f32 v131, -v230, v233, v232
	v_fmac_f32_e32 v233, v131, v231
	v_fma_f32 v230, -v230, v233, v232
	v_div_fmas_f32 v230, v230, v231, v233
	v_div_fixup_f32 v135, v230, v229, v1
	v_mul_f32_e32 v135, v9, v135
	v_mul_f32_e32 v228, 0xbfb8aa3b, v5
	v_exp_f32_e32 v228, v228
	s_nop 0
	v_add_f32_e32 v229, 1.0, v228
	v_div_scale_f32 v230, s[4:5], v229, v229, v5
	v_rcp_f32_e32 v231, v230
	v_div_scale_f32 v232, vcc, v5, v229, v5
	s_nop 0
	v_fma_f32 v131, -v230, v231, 1.0
	v_fmac_f32_e32 v231, v131, v231
	v_mul_f32_e32 v233, v232, v231
	v_fma_f32 v131, -v230, v233, v232
	v_fmac_f32_e32 v233, v131, v231
	v_fma_f32 v230, -v230, v233, v232
	v_div_fmas_f32 v230, v230, v231, v233
	v_div_fixup_f32 v133, v230, v229, v5
	v_mul_f32_e32 v133, v13, v133
	v_cvt_pk_bf16_f32 v133, v135, v133
	global_store_dword v[226:227], v133, off
	v_lshl_add_u64 v[226:227], v[226:227], 0, s[56:57]
	v_mul_f32_e32 v228, 0xbfb8aa3b, v2
	v_exp_f32_e32 v228, v228
	s_nop 0
	v_add_f32_e32 v229, 1.0, v228
	v_div_scale_f32 v230, s[4:5], v229, v229, v2
	v_rcp_f32_e32 v231, v230
	v_div_scale_f32 v232, vcc, v2, v229, v2
	s_nop 0
	v_fma_f32 v131, -v230, v231, 1.0
	v_fmac_f32_e32 v231, v131, v231
	v_mul_f32_e32 v233, v232, v231
	v_fma_f32 v131, -v230, v233, v232
	v_fmac_f32_e32 v233, v131, v231
	v_fma_f32 v230, -v230, v233, v232
	v_div_fmas_f32 v230, v230, v231, v233
	v_div_fixup_f32 v135, v230, v229, v2
	v_mul_f32_e32 v135, v10, v135
	v_mul_f32_e32 v228, 0xbfb8aa3b, v6
	v_exp_f32_e32 v228, v228
	s_nop 0
	v_add_f32_e32 v229, 1.0, v228
	v_div_scale_f32 v230, s[4:5], v229, v229, v6
	v_rcp_f32_e32 v231, v230
	v_div_scale_f32 v232, vcc, v6, v229, v6
	s_nop 0
	v_fma_f32 v131, -v230, v231, 1.0
	v_fmac_f32_e32 v231, v131, v231
	v_mul_f32_e32 v233, v232, v231
	v_fma_f32 v131, -v230, v233, v232
	v_fmac_f32_e32 v233, v131, v231
	v_fma_f32 v230, -v230, v233, v232
	v_div_fmas_f32 v230, v230, v231, v233
	v_div_fixup_f32 v133, v230, v229, v6
	v_mul_f32_e32 v133, v14, v133
	v_cvt_pk_bf16_f32 v133, v135, v133
	global_store_dword v[226:227], v133, off
	v_lshl_add_u64 v[226:227], v[226:227], 0, s[56:57]
	v_mul_f32_e32 v228, 0xbfb8aa3b, v3
	v_exp_f32_e32 v228, v228
	s_nop 0
	v_add_f32_e32 v229, 1.0, v228
	v_div_scale_f32 v230, s[4:5], v229, v229, v3
	v_rcp_f32_e32 v231, v230
	v_div_scale_f32 v232, vcc, v3, v229, v3
	s_nop 0
	v_fma_f32 v131, -v230, v231, 1.0
	v_fmac_f32_e32 v231, v131, v231
	v_mul_f32_e32 v233, v232, v231
	v_fma_f32 v131, -v230, v233, v232
	v_fmac_f32_e32 v233, v131, v231
	v_fma_f32 v230, -v230, v233, v232
	v_div_fmas_f32 v230, v230, v231, v233
	v_div_fixup_f32 v135, v230, v229, v3
	v_mul_f32_e32 v135, v11, v135
	v_mul_f32_e32 v228, 0xbfb8aa3b, v7
	v_exp_f32_e32 v228, v228
	s_nop 0
	v_add_f32_e32 v229, 1.0, v228
	v_div_scale_f32 v230, s[4:5], v229, v229, v7
	v_rcp_f32_e32 v231, v230
	v_div_scale_f32 v232, vcc, v7, v229, v7
	s_nop 0
	v_fma_f32 v131, -v230, v231, 1.0
	v_fmac_f32_e32 v231, v131, v231
	v_mul_f32_e32 v233, v232, v231
	v_fma_f32 v131, -v230, v233, v232
	v_fmac_f32_e32 v233, v131, v231
	v_fma_f32 v230, -v230, v233, v232
	v_div_fmas_f32 v230, v230, v231, v233
	v_div_fixup_f32 v133, v230, v229, v7
	v_mul_f32_e32 v133, v15, v133
	v_cvt_pk_bf16_f32 v133, v135, v133
	global_store_dword v[226:227], v133, off
	v_lshl_add_u64 v[226:227], v[226:227], 0, s[40:41]
	v_mul_f32_e32 v228, 0xbfb8aa3b, v16
	v_exp_f32_e32 v228, v228
	s_nop 0
	v_add_f32_e32 v229, 1.0, v228
	v_div_scale_f32 v230, s[4:5], v229, v229, v16
	v_rcp_f32_e32 v231, v230
	v_div_scale_f32 v232, vcc, v16, v229, v16
	s_nop 0
	v_fma_f32 v131, -v230, v231, 1.0
	v_fmac_f32_e32 v231, v131, v231
	v_mul_f32_e32 v233, v232, v231
	v_fma_f32 v131, -v230, v233, v232
	v_fmac_f32_e32 v233, v131, v231
	v_fma_f32 v230, -v230, v233, v232
	v_div_fmas_f32 v230, v230, v231, v233
	v_div_fixup_f32 v135, v230, v229, v16
	v_mul_f32_e32 v135, v24, v135
	v_mul_f32_e32 v228, 0xbfb8aa3b, v20
	v_exp_f32_e32 v228, v228
	s_nop 0
	v_add_f32_e32 v229, 1.0, v228
	v_div_scale_f32 v230, s[4:5], v229, v229, v20
	v_rcp_f32_e32 v231, v230
	v_div_scale_f32 v232, vcc, v20, v229, v20
	s_nop 0
	v_fma_f32 v131, -v230, v231, 1.0
	v_fmac_f32_e32 v231, v131, v231
	v_mul_f32_e32 v233, v232, v231
	v_fma_f32 v131, -v230, v233, v232
	v_fmac_f32_e32 v233, v131, v231
	v_fma_f32 v230, -v230, v233, v232
	v_div_fmas_f32 v230, v230, v231, v233
	v_div_fixup_f32 v133, v230, v229, v20
	v_mul_f32_e32 v133, v28, v133
	v_cvt_pk_bf16_f32 v133, v135, v133
	global_store_dword v[226:227], v133, off
	v_lshl_add_u64 v[226:227], v[226:227], 0, s[56:57]
	v_mul_f32_e32 v228, 0xbfb8aa3b, v17
	v_exp_f32_e32 v228, v228
	s_nop 0
	v_add_f32_e32 v229, 1.0, v228
	v_div_scale_f32 v230, s[4:5], v229, v229, v17
	v_rcp_f32_e32 v231, v230
	v_div_scale_f32 v232, vcc, v17, v229, v17
	s_nop 0
	v_fma_f32 v131, -v230, v231, 1.0
	v_fmac_f32_e32 v231, v131, v231
	v_mul_f32_e32 v233, v232, v231
	v_fma_f32 v131, -v230, v233, v232
	v_fmac_f32_e32 v233, v131, v231
	v_fma_f32 v230, -v230, v233, v232
	v_div_fmas_f32 v230, v230, v231, v233
	v_div_fixup_f32 v135, v230, v229, v17
	v_mul_f32_e32 v135, v25, v135
	v_mul_f32_e32 v228, 0xbfb8aa3b, v21
	v_exp_f32_e32 v228, v228
	s_nop 0
	v_add_f32_e32 v229, 1.0, v228
	v_div_scale_f32 v230, s[4:5], v229, v229, v21
	v_rcp_f32_e32 v231, v230
	v_div_scale_f32 v232, vcc, v21, v229, v21
	s_nop 0
	v_fma_f32 v131, -v230, v231, 1.0
	v_fmac_f32_e32 v231, v131, v231
	v_mul_f32_e32 v233, v232, v231
	v_fma_f32 v131, -v230, v233, v232
	v_fmac_f32_e32 v233, v131, v231
	v_fma_f32 v230, -v230, v233, v232
	v_div_fmas_f32 v230, v230, v231, v233
	v_div_fixup_f32 v133, v230, v229, v21
	v_mul_f32_e32 v133, v29, v133
	v_cvt_pk_bf16_f32 v133, v135, v133
	global_store_dword v[226:227], v133, off
	v_lshl_add_u64 v[226:227], v[226:227], 0, s[56:57]
	v_mul_f32_e32 v228, 0xbfb8aa3b, v18
	v_exp_f32_e32 v228, v228
	s_nop 0
	v_add_f32_e32 v229, 1.0, v228
	v_div_scale_f32 v230, s[4:5], v229, v229, v18
	v_rcp_f32_e32 v231, v230
	v_div_scale_f32 v232, vcc, v18, v229, v18
	s_nop 0
	v_fma_f32 v131, -v230, v231, 1.0
	v_fmac_f32_e32 v231, v131, v231
	v_mul_f32_e32 v233, v232, v231
	v_fma_f32 v131, -v230, v233, v232
	v_fmac_f32_e32 v233, v131, v231
	v_fma_f32 v230, -v230, v233, v232
	v_div_fmas_f32 v230, v230, v231, v233
	v_div_fixup_f32 v135, v230, v229, v18
	v_mul_f32_e32 v135, v26, v135
	v_mul_f32_e32 v228, 0xbfb8aa3b, v22
	v_exp_f32_e32 v228, v228
	s_nop 0
	v_add_f32_e32 v229, 1.0, v228
	v_div_scale_f32 v230, s[4:5], v229, v229, v22
	v_rcp_f32_e32 v231, v230
	v_div_scale_f32 v232, vcc, v22, v229, v22
	s_nop 0
	v_fma_f32 v131, -v230, v231, 1.0
	v_fmac_f32_e32 v231, v131, v231
	v_mul_f32_e32 v233, v232, v231
	v_fma_f32 v131, -v230, v233, v232
	v_fmac_f32_e32 v233, v131, v231
	v_fma_f32 v230, -v230, v233, v232
	v_div_fmas_f32 v230, v230, v231, v233
	v_div_fixup_f32 v133, v230, v229, v22
	v_mul_f32_e32 v133, v30, v133
	v_cvt_pk_bf16_f32 v133, v135, v133
	global_store_dword v[226:227], v133, off
	v_lshl_add_u64 v[226:227], v[226:227], 0, s[56:57]
	v_mul_f32_e32 v228, 0xbfb8aa3b, v19
	v_exp_f32_e32 v228, v228
	s_nop 0
	v_add_f32_e32 v229, 1.0, v228
	v_div_scale_f32 v230, s[4:5], v229, v229, v19
	v_rcp_f32_e32 v231, v230
	v_div_scale_f32 v232, vcc, v19, v229, v19
	s_nop 0
	v_fma_f32 v131, -v230, v231, 1.0
	v_fmac_f32_e32 v231, v131, v231
	v_mul_f32_e32 v233, v232, v231
	v_fma_f32 v131, -v230, v233, v232
	v_fmac_f32_e32 v233, v131, v231
	v_fma_f32 v230, -v230, v233, v232
	v_div_fmas_f32 v230, v230, v231, v233
	v_div_fixup_f32 v135, v230, v229, v19
	v_mul_f32_e32 v135, v27, v135
	v_mul_f32_e32 v228, 0xbfb8aa3b, v23
	v_exp_f32_e32 v228, v228
	s_nop 0
	v_add_f32_e32 v229, 1.0, v228
	v_div_scale_f32 v230, s[4:5], v229, v229, v23
	v_rcp_f32_e32 v231, v230
	v_div_scale_f32 v232, vcc, v23, v229, v23
	s_nop 0
	v_fma_f32 v131, -v230, v231, 1.0
	v_fmac_f32_e32 v231, v131, v231
	v_mul_f32_e32 v233, v232, v231
	v_fma_f32 v131, -v230, v233, v232
	v_fmac_f32_e32 v233, v131, v231
	v_fma_f32 v230, -v230, v233, v232
	v_div_fmas_f32 v230, v230, v231, v233
	v_div_fixup_f32 v133, v230, v229, v23
	v_mul_f32_e32 v133, v31, v133
	v_cvt_pk_bf16_f32 v133, v135, v133
	global_store_dword v[226:227], v133, off
	v_lshl_add_u64 v[226:227], v[226:227], 0, s[40:41]
	v_mul_f32_e32 v228, 0xbfb8aa3b, v32
	v_exp_f32_e32 v228, v228
	s_nop 0
	v_add_f32_e32 v229, 1.0, v228
	v_div_scale_f32 v230, s[4:5], v229, v229, v32
	v_rcp_f32_e32 v231, v230
	v_div_scale_f32 v232, vcc, v32, v229, v32
	s_nop 0
	v_fma_f32 v131, -v230, v231, 1.0
	v_fmac_f32_e32 v231, v131, v231
	v_mul_f32_e32 v233, v232, v231
	v_fma_f32 v131, -v230, v233, v232
	v_fmac_f32_e32 v233, v131, v231
	v_fma_f32 v230, -v230, v233, v232
	v_div_fmas_f32 v230, v230, v231, v233
	v_div_fixup_f32 v135, v230, v229, v32
	v_mul_f32_e32 v135, v40, v135
	v_mul_f32_e32 v228, 0xbfb8aa3b, v36
	v_exp_f32_e32 v228, v228
	s_nop 0
	v_add_f32_e32 v229, 1.0, v228
	v_div_scale_f32 v230, s[4:5], v229, v229, v36
	v_rcp_f32_e32 v231, v230
	v_div_scale_f32 v232, vcc, v36, v229, v36
	s_nop 0
	v_fma_f32 v131, -v230, v231, 1.0
	v_fmac_f32_e32 v231, v131, v231
	v_mul_f32_e32 v233, v232, v231
	v_fma_f32 v131, -v230, v233, v232
	v_fmac_f32_e32 v233, v131, v231
	v_fma_f32 v230, -v230, v233, v232
	v_div_fmas_f32 v230, v230, v231, v233
	v_div_fixup_f32 v133, v230, v229, v36
	v_mul_f32_e32 v133, v44, v133
	v_cvt_pk_bf16_f32 v133, v135, v133
	global_store_dword v[226:227], v133, off
	v_lshl_add_u64 v[226:227], v[226:227], 0, s[56:57]
	v_mul_f32_e32 v228, 0xbfb8aa3b, v33
	v_exp_f32_e32 v228, v228
	s_nop 0
	v_add_f32_e32 v229, 1.0, v228
	v_div_scale_f32 v230, s[4:5], v229, v229, v33
	v_rcp_f32_e32 v231, v230
	v_div_scale_f32 v232, vcc, v33, v229, v33
	s_nop 0
	v_fma_f32 v131, -v230, v231, 1.0
	v_fmac_f32_e32 v231, v131, v231
	v_mul_f32_e32 v233, v232, v231
	v_fma_f32 v131, -v230, v233, v232
	v_fmac_f32_e32 v233, v131, v231
	v_fma_f32 v230, -v230, v233, v232
	v_div_fmas_f32 v230, v230, v231, v233
	v_div_fixup_f32 v135, v230, v229, v33
	v_mul_f32_e32 v135, v41, v135
	v_mul_f32_e32 v228, 0xbfb8aa3b, v37
	v_exp_f32_e32 v228, v228
	s_nop 0
	v_add_f32_e32 v229, 1.0, v228
	v_div_scale_f32 v230, s[4:5], v229, v229, v37
	v_rcp_f32_e32 v231, v230
	v_div_scale_f32 v232, vcc, v37, v229, v37
	s_nop 0
	v_fma_f32 v131, -v230, v231, 1.0
	v_fmac_f32_e32 v231, v131, v231
	v_mul_f32_e32 v233, v232, v231
	v_fma_f32 v131, -v230, v233, v232
	v_fmac_f32_e32 v233, v131, v231
	v_fma_f32 v230, -v230, v233, v232
	v_div_fmas_f32 v230, v230, v231, v233
	v_div_fixup_f32 v133, v230, v229, v37
	v_mul_f32_e32 v133, v45, v133
	v_cvt_pk_bf16_f32 v133, v135, v133
	global_store_dword v[226:227], v133, off
	v_lshl_add_u64 v[226:227], v[226:227], 0, s[56:57]
	v_mul_f32_e32 v228, 0xbfb8aa3b, v34
	v_exp_f32_e32 v228, v228
	s_nop 0
	v_add_f32_e32 v229, 1.0, v228
	v_div_scale_f32 v230, s[4:5], v229, v229, v34
	v_rcp_f32_e32 v231, v230
	v_div_scale_f32 v232, vcc, v34, v229, v34
	s_nop 0
	v_fma_f32 v131, -v230, v231, 1.0
	v_fmac_f32_e32 v231, v131, v231
	v_mul_f32_e32 v233, v232, v231
	v_fma_f32 v131, -v230, v233, v232
	v_fmac_f32_e32 v233, v131, v231
	v_fma_f32 v230, -v230, v233, v232
	v_div_fmas_f32 v230, v230, v231, v233
	v_div_fixup_f32 v135, v230, v229, v34
	v_mul_f32_e32 v135, v42, v135
	v_mul_f32_e32 v228, 0xbfb8aa3b, v38
	v_exp_f32_e32 v228, v228
	s_nop 0
	v_add_f32_e32 v229, 1.0, v228
	v_div_scale_f32 v230, s[4:5], v229, v229, v38
	v_rcp_f32_e32 v231, v230
	v_div_scale_f32 v232, vcc, v38, v229, v38
	s_nop 0
	v_fma_f32 v131, -v230, v231, 1.0
	v_fmac_f32_e32 v231, v131, v231
	v_mul_f32_e32 v233, v232, v231
	v_fma_f32 v131, -v230, v233, v232
	v_fmac_f32_e32 v233, v131, v231
	v_fma_f32 v230, -v230, v233, v232
	v_div_fmas_f32 v230, v230, v231, v233
	v_div_fixup_f32 v133, v230, v229, v38
	v_mul_f32_e32 v133, v46, v133
	v_cvt_pk_bf16_f32 v133, v135, v133
	global_store_dword v[226:227], v133, off
	v_lshl_add_u64 v[226:227], v[226:227], 0, s[56:57]
	v_mul_f32_e32 v228, 0xbfb8aa3b, v35
	v_exp_f32_e32 v228, v228
	s_nop 0
	v_add_f32_e32 v229, 1.0, v228
	v_div_scale_f32 v230, s[4:5], v229, v229, v35
	v_rcp_f32_e32 v231, v230
	v_div_scale_f32 v232, vcc, v35, v229, v35
	s_nop 0
	v_fma_f32 v131, -v230, v231, 1.0
	v_fmac_f32_e32 v231, v131, v231
	v_mul_f32_e32 v233, v232, v231
	v_fma_f32 v131, -v230, v233, v232
	v_fmac_f32_e32 v233, v131, v231
	v_fma_f32 v230, -v230, v233, v232
	v_div_fmas_f32 v230, v230, v231, v233
	v_div_fixup_f32 v135, v230, v229, v35
	v_mul_f32_e32 v135, v43, v135
	v_mul_f32_e32 v228, 0xbfb8aa3b, v39
	v_exp_f32_e32 v228, v228
	s_nop 0
	v_add_f32_e32 v229, 1.0, v228
	v_div_scale_f32 v230, s[4:5], v229, v229, v39
	v_rcp_f32_e32 v231, v230
	v_div_scale_f32 v232, vcc, v39, v229, v39
	s_nop 0
	v_fma_f32 v131, -v230, v231, 1.0
	v_fmac_f32_e32 v231, v131, v231
	v_mul_f32_e32 v233, v232, v231
	v_fma_f32 v131, -v230, v233, v232
	v_fmac_f32_e32 v233, v131, v231
	v_fma_f32 v230, -v230, v233, v232
	v_div_fmas_f32 v230, v230, v231, v233
	v_div_fixup_f32 v133, v230, v229, v39
	v_mul_f32_e32 v133, v47, v133
	v_cvt_pk_bf16_f32 v133, v135, v133
	global_store_dword v[226:227], v133, off
	v_lshl_add_u64 v[226:227], v[226:227], 0, s[40:41]
	v_mul_f32_e32 v228, 0xbfb8aa3b, v48
	v_exp_f32_e32 v228, v228
	s_nop 0
	v_add_f32_e32 v229, 1.0, v228
	v_div_scale_f32 v230, s[4:5], v229, v229, v48
	v_rcp_f32_e32 v231, v230
	v_div_scale_f32 v232, vcc, v48, v229, v48
	s_nop 0
	v_fma_f32 v131, -v230, v231, 1.0
	v_fmac_f32_e32 v231, v131, v231
	v_mul_f32_e32 v233, v232, v231
	v_fma_f32 v131, -v230, v233, v232
	v_fmac_f32_e32 v233, v131, v231
	v_fma_f32 v230, -v230, v233, v232
	v_div_fmas_f32 v230, v230, v231, v233
	v_div_fixup_f32 v135, v230, v229, v48
	v_mul_f32_e32 v135, v56, v135
	v_mul_f32_e32 v228, 0xbfb8aa3b, v52
	v_exp_f32_e32 v228, v228
	s_nop 0
	v_add_f32_e32 v229, 1.0, v228
	v_div_scale_f32 v230, s[4:5], v229, v229, v52
	v_rcp_f32_e32 v231, v230
	v_div_scale_f32 v232, vcc, v52, v229, v52
	s_nop 0
	v_fma_f32 v131, -v230, v231, 1.0
	v_fmac_f32_e32 v231, v131, v231
	v_mul_f32_e32 v233, v232, v231
	v_fma_f32 v131, -v230, v233, v232
	v_fmac_f32_e32 v233, v131, v231
	v_fma_f32 v230, -v230, v233, v232
	v_div_fmas_f32 v230, v230, v231, v233
	v_div_fixup_f32 v133, v230, v229, v52
	v_mul_f32_e32 v133, v60, v133
	v_cvt_pk_bf16_f32 v133, v135, v133
	global_store_dword v[226:227], v133, off
	v_lshl_add_u64 v[226:227], v[226:227], 0, s[56:57]
	v_mul_f32_e32 v228, 0xbfb8aa3b, v49
	v_exp_f32_e32 v228, v228
	s_nop 0
	v_add_f32_e32 v229, 1.0, v228
	v_div_scale_f32 v230, s[4:5], v229, v229, v49
	v_rcp_f32_e32 v231, v230
	v_div_scale_f32 v232, vcc, v49, v229, v49
	s_nop 0
	v_fma_f32 v131, -v230, v231, 1.0
	v_fmac_f32_e32 v231, v131, v231
	v_mul_f32_e32 v233, v232, v231
	v_fma_f32 v131, -v230, v233, v232
	v_fmac_f32_e32 v233, v131, v231
	v_fma_f32 v230, -v230, v233, v232
	v_div_fmas_f32 v230, v230, v231, v233
	v_div_fixup_f32 v135, v230, v229, v49
	v_mul_f32_e32 v135, v57, v135
	v_mul_f32_e32 v228, 0xbfb8aa3b, v53
	v_exp_f32_e32 v228, v228
	s_nop 0
	v_add_f32_e32 v229, 1.0, v228
	v_div_scale_f32 v230, s[4:5], v229, v229, v53
	v_rcp_f32_e32 v231, v230
	v_div_scale_f32 v232, vcc, v53, v229, v53
	s_nop 0
	v_fma_f32 v131, -v230, v231, 1.0
	v_fmac_f32_e32 v231, v131, v231
	v_mul_f32_e32 v233, v232, v231
	v_fma_f32 v131, -v230, v233, v232
	v_fmac_f32_e32 v233, v131, v231
	v_fma_f32 v230, -v230, v233, v232
	v_div_fmas_f32 v230, v230, v231, v233
	v_div_fixup_f32 v133, v230, v229, v53
	v_mul_f32_e32 v133, v61, v133
	v_cvt_pk_bf16_f32 v133, v135, v133
	global_store_dword v[226:227], v133, off
	v_lshl_add_u64 v[226:227], v[226:227], 0, s[56:57]
	v_mul_f32_e32 v228, 0xbfb8aa3b, v50
	v_exp_f32_e32 v228, v228
	s_nop 0
	v_add_f32_e32 v229, 1.0, v228
	v_div_scale_f32 v230, s[4:5], v229, v229, v50
	v_rcp_f32_e32 v231, v230
	v_div_scale_f32 v232, vcc, v50, v229, v50
	s_nop 0
	v_fma_f32 v131, -v230, v231, 1.0
	v_fmac_f32_e32 v231, v131, v231
	v_mul_f32_e32 v233, v232, v231
	v_fma_f32 v131, -v230, v233, v232
	v_fmac_f32_e32 v233, v131, v231
	v_fma_f32 v230, -v230, v233, v232
	v_div_fmas_f32 v230, v230, v231, v233
	v_div_fixup_f32 v135, v230, v229, v50
	v_mul_f32_e32 v135, v58, v135
	v_mul_f32_e32 v228, 0xbfb8aa3b, v54
	v_exp_f32_e32 v228, v228
	s_nop 0
	v_add_f32_e32 v229, 1.0, v228
	v_div_scale_f32 v230, s[4:5], v229, v229, v54
	v_rcp_f32_e32 v231, v230
	v_div_scale_f32 v232, vcc, v54, v229, v54
	s_nop 0
	v_fma_f32 v131, -v230, v231, 1.0
	v_fmac_f32_e32 v231, v131, v231
	v_mul_f32_e32 v233, v232, v231
	v_fma_f32 v131, -v230, v233, v232
	v_fmac_f32_e32 v233, v131, v231
	v_fma_f32 v230, -v230, v233, v232
	v_div_fmas_f32 v230, v230, v231, v233
	v_div_fixup_f32 v133, v230, v229, v54
	v_mul_f32_e32 v133, v62, v133
	v_cvt_pk_bf16_f32 v133, v135, v133
	global_store_dword v[226:227], v133, off
	v_lshl_add_u64 v[226:227], v[226:227], 0, s[56:57]
	v_mul_f32_e32 v228, 0xbfb8aa3b, v51
	v_exp_f32_e32 v228, v228
	s_nop 0
	v_add_f32_e32 v229, 1.0, v228
	v_div_scale_f32 v230, s[4:5], v229, v229, v51
	v_rcp_f32_e32 v231, v230
	v_div_scale_f32 v232, vcc, v51, v229, v51
	s_nop 0
	v_fma_f32 v131, -v230, v231, 1.0
	v_fmac_f32_e32 v231, v131, v231
	v_mul_f32_e32 v233, v232, v231
	v_fma_f32 v131, -v230, v233, v232
	v_fmac_f32_e32 v233, v131, v231
	v_fma_f32 v230, -v230, v233, v232
	v_div_fmas_f32 v230, v230, v231, v233
	v_div_fixup_f32 v135, v230, v229, v51
	v_mul_f32_e32 v135, v59, v135
	v_mul_f32_e32 v228, 0xbfb8aa3b, v55
	v_exp_f32_e32 v228, v228
	s_nop 0
	v_add_f32_e32 v229, 1.0, v228
	v_div_scale_f32 v230, s[4:5], v229, v229, v55
	v_rcp_f32_e32 v231, v230
	v_div_scale_f32 v232, vcc, v55, v229, v55
	s_nop 0
	v_fma_f32 v131, -v230, v231, 1.0
	v_fmac_f32_e32 v231, v131, v231
	v_mul_f32_e32 v233, v232, v231
	v_fma_f32 v131, -v230, v233, v232
	v_fmac_f32_e32 v233, v131, v231
	v_fma_f32 v230, -v230, v233, v232
	v_div_fmas_f32 v230, v230, v231, v233
	v_div_fixup_f32 v133, v230, v229, v55
	v_mul_f32_e32 v133, v63, v133
	v_cvt_pk_bf16_f32 v133, v135, v133
	global_store_dword v[226:227], v133, off
	v_lshl_add_u64 v[226:227], v[226:227], 0, s[40:41]
	v_mul_f32_e32 v228, 0xbfb8aa3b, v64
	v_exp_f32_e32 v228, v228
	s_nop 0
	v_add_f32_e32 v229, 1.0, v228
	v_div_scale_f32 v230, s[4:5], v229, v229, v64
	v_rcp_f32_e32 v231, v230
	v_div_scale_f32 v232, vcc, v64, v229, v64
	s_nop 0
	v_fma_f32 v131, -v230, v231, 1.0
	v_fmac_f32_e32 v231, v131, v231
	v_mul_f32_e32 v233, v232, v231
	v_fma_f32 v131, -v230, v233, v232
	v_fmac_f32_e32 v233, v131, v231
	v_fma_f32 v230, -v230, v233, v232
	v_div_fmas_f32 v230, v230, v231, v233
	v_div_fixup_f32 v135, v230, v229, v64
	v_mul_f32_e32 v135, v72, v135
	v_mul_f32_e32 v228, 0xbfb8aa3b, v68
	v_exp_f32_e32 v228, v228
	s_nop 0
	v_add_f32_e32 v229, 1.0, v228
	v_div_scale_f32 v230, s[4:5], v229, v229, v68
	v_rcp_f32_e32 v231, v230
	v_div_scale_f32 v232, vcc, v68, v229, v68
	s_nop 0
	v_fma_f32 v131, -v230, v231, 1.0
	v_fmac_f32_e32 v231, v131, v231
	v_mul_f32_e32 v233, v232, v231
	v_fma_f32 v131, -v230, v233, v232
	v_fmac_f32_e32 v233, v131, v231
	v_fma_f32 v230, -v230, v233, v232
	v_div_fmas_f32 v230, v230, v231, v233
	v_div_fixup_f32 v133, v230, v229, v68
	v_mul_f32_e32 v133, v76, v133
	v_cvt_pk_bf16_f32 v133, v135, v133
	global_store_dword v[226:227], v133, off
	v_lshl_add_u64 v[226:227], v[226:227], 0, s[56:57]
	v_mul_f32_e32 v228, 0xbfb8aa3b, v65
	v_exp_f32_e32 v228, v228
	s_nop 0
	v_add_f32_e32 v229, 1.0, v228
	v_div_scale_f32 v230, s[4:5], v229, v229, v65
	v_rcp_f32_e32 v231, v230
	v_div_scale_f32 v232, vcc, v65, v229, v65
	s_nop 0
	v_fma_f32 v131, -v230, v231, 1.0
	v_fmac_f32_e32 v231, v131, v231
	v_mul_f32_e32 v233, v232, v231
	v_fma_f32 v131, -v230, v233, v232
	v_fmac_f32_e32 v233, v131, v231
	v_fma_f32 v230, -v230, v233, v232
	v_div_fmas_f32 v230, v230, v231, v233
	v_div_fixup_f32 v135, v230, v229, v65
	v_mul_f32_e32 v135, v73, v135
	v_mul_f32_e32 v228, 0xbfb8aa3b, v69
	v_exp_f32_e32 v228, v228
	s_nop 0
	v_add_f32_e32 v229, 1.0, v228
	v_div_scale_f32 v230, s[4:5], v229, v229, v69
	v_rcp_f32_e32 v231, v230
	v_div_scale_f32 v232, vcc, v69, v229, v69
	s_nop 0
	v_fma_f32 v131, -v230, v231, 1.0
	v_fmac_f32_e32 v231, v131, v231
	v_mul_f32_e32 v233, v232, v231
	v_fma_f32 v131, -v230, v233, v232
	v_fmac_f32_e32 v233, v131, v231
	v_fma_f32 v230, -v230, v233, v232
	v_div_fmas_f32 v230, v230, v231, v233
	v_div_fixup_f32 v133, v230, v229, v69
	v_mul_f32_e32 v133, v77, v133
	v_cvt_pk_bf16_f32 v133, v135, v133
	global_store_dword v[226:227], v133, off
	v_lshl_add_u64 v[226:227], v[226:227], 0, s[56:57]
	v_mul_f32_e32 v228, 0xbfb8aa3b, v66
	v_exp_f32_e32 v228, v228
	s_nop 0
	v_add_f32_e32 v229, 1.0, v228
	v_div_scale_f32 v230, s[4:5], v229, v229, v66
	v_rcp_f32_e32 v231, v230
	v_div_scale_f32 v232, vcc, v66, v229, v66
	s_nop 0
	v_fma_f32 v131, -v230, v231, 1.0
	v_fmac_f32_e32 v231, v131, v231
	v_mul_f32_e32 v233, v232, v231
	v_fma_f32 v131, -v230, v233, v232
	v_fmac_f32_e32 v233, v131, v231
	v_fma_f32 v230, -v230, v233, v232
	v_div_fmas_f32 v230, v230, v231, v233
	v_div_fixup_f32 v135, v230, v229, v66
	v_mul_f32_e32 v135, v74, v135
	v_mul_f32_e32 v228, 0xbfb8aa3b, v70
	v_exp_f32_e32 v228, v228
	s_nop 0
	v_add_f32_e32 v229, 1.0, v228
	v_div_scale_f32 v230, s[4:5], v229, v229, v70
	v_rcp_f32_e32 v231, v230
	v_div_scale_f32 v232, vcc, v70, v229, v70
	s_nop 0
	v_fma_f32 v131, -v230, v231, 1.0
	v_fmac_f32_e32 v231, v131, v231
	v_mul_f32_e32 v233, v232, v231
	v_fma_f32 v131, -v230, v233, v232
	v_fmac_f32_e32 v233, v131, v231
	v_fma_f32 v230, -v230, v233, v232
	v_div_fmas_f32 v230, v230, v231, v233
	v_div_fixup_f32 v133, v230, v229, v70
	v_mul_f32_e32 v133, v78, v133
	v_cvt_pk_bf16_f32 v133, v135, v133
	global_store_dword v[226:227], v133, off
	v_lshl_add_u64 v[226:227], v[226:227], 0, s[56:57]
	v_mul_f32_e32 v228, 0xbfb8aa3b, v67
	v_exp_f32_e32 v228, v228
	s_nop 0
	v_add_f32_e32 v229, 1.0, v228
	v_div_scale_f32 v230, s[4:5], v229, v229, v67
	v_rcp_f32_e32 v231, v230
	v_div_scale_f32 v232, vcc, v67, v229, v67
	s_nop 0
	v_fma_f32 v131, -v230, v231, 1.0
	v_fmac_f32_e32 v231, v131, v231
	v_mul_f32_e32 v233, v232, v231
	v_fma_f32 v131, -v230, v233, v232
	v_fmac_f32_e32 v233, v131, v231
	v_fma_f32 v230, -v230, v233, v232
	v_div_fmas_f32 v230, v230, v231, v233
	v_div_fixup_f32 v135, v230, v229, v67
	v_mul_f32_e32 v135, v75, v135
	v_mul_f32_e32 v228, 0xbfb8aa3b, v71
	v_exp_f32_e32 v228, v228
	s_nop 0
	v_add_f32_e32 v229, 1.0, v228
	v_div_scale_f32 v230, s[4:5], v229, v229, v71
	v_rcp_f32_e32 v231, v230
	v_div_scale_f32 v232, vcc, v71, v229, v71
	s_nop 0
	v_fma_f32 v131, -v230, v231, 1.0
	v_fmac_f32_e32 v231, v131, v231
	v_mul_f32_e32 v233, v232, v231
	v_fma_f32 v131, -v230, v233, v232
	v_fmac_f32_e32 v233, v131, v231
	v_fma_f32 v230, -v230, v233, v232
	v_div_fmas_f32 v230, v230, v231, v233
	v_div_fixup_f32 v133, v230, v229, v71
	v_mul_f32_e32 v133, v79, v133
	v_cvt_pk_bf16_f32 v133, v135, v133
	global_store_dword v[226:227], v133, off
	v_lshl_add_u64 v[226:227], v[226:227], 0, s[40:41]
	v_mul_f32_e32 v228, 0xbfb8aa3b, v80
	v_exp_f32_e32 v228, v228
	s_nop 0
	v_add_f32_e32 v229, 1.0, v228
	v_div_scale_f32 v230, s[4:5], v229, v229, v80
	v_rcp_f32_e32 v231, v230
	v_div_scale_f32 v232, vcc, v80, v229, v80
	s_nop 0
	v_fma_f32 v131, -v230, v231, 1.0
	v_fmac_f32_e32 v231, v131, v231
	v_mul_f32_e32 v233, v232, v231
	v_fma_f32 v131, -v230, v233, v232
	v_fmac_f32_e32 v233, v131, v231
	v_fma_f32 v230, -v230, v233, v232
	v_div_fmas_f32 v230, v230, v231, v233
	v_div_fixup_f32 v135, v230, v229, v80
	v_mul_f32_e32 v135, v88, v135
	v_mul_f32_e32 v228, 0xbfb8aa3b, v84
	v_exp_f32_e32 v228, v228
	s_nop 0
	v_add_f32_e32 v229, 1.0, v228
	v_div_scale_f32 v230, s[4:5], v229, v229, v84
	v_rcp_f32_e32 v231, v230
	v_div_scale_f32 v232, vcc, v84, v229, v84
	s_nop 0
	v_fma_f32 v131, -v230, v231, 1.0
	v_fmac_f32_e32 v231, v131, v231
	v_mul_f32_e32 v233, v232, v231
	v_fma_f32 v131, -v230, v233, v232
	v_fmac_f32_e32 v233, v131, v231
	v_fma_f32 v230, -v230, v233, v232
	v_div_fmas_f32 v230, v230, v231, v233
	v_div_fixup_f32 v133, v230, v229, v84
	v_mul_f32_e32 v133, v92, v133
	v_cvt_pk_bf16_f32 v133, v135, v133
	global_store_dword v[226:227], v133, off
	v_lshl_add_u64 v[226:227], v[226:227], 0, s[56:57]
	v_mul_f32_e32 v228, 0xbfb8aa3b, v81
	v_exp_f32_e32 v228, v228
	s_nop 0
	v_add_f32_e32 v229, 1.0, v228
	v_div_scale_f32 v230, s[4:5], v229, v229, v81
	v_rcp_f32_e32 v231, v230
	v_div_scale_f32 v232, vcc, v81, v229, v81
	s_nop 0
	v_fma_f32 v131, -v230, v231, 1.0
	v_fmac_f32_e32 v231, v131, v231
	v_mul_f32_e32 v233, v232, v231
	v_fma_f32 v131, -v230, v233, v232
	v_fmac_f32_e32 v233, v131, v231
	v_fma_f32 v230, -v230, v233, v232
	v_div_fmas_f32 v230, v230, v231, v233
	v_div_fixup_f32 v135, v230, v229, v81
	v_mul_f32_e32 v135, v89, v135
	v_mul_f32_e32 v228, 0xbfb8aa3b, v85
	v_exp_f32_e32 v228, v228
	s_nop 0
	v_add_f32_e32 v229, 1.0, v228
	v_div_scale_f32 v230, s[4:5], v229, v229, v85
	v_rcp_f32_e32 v231, v230
	v_div_scale_f32 v232, vcc, v85, v229, v85
	s_nop 0
	v_fma_f32 v131, -v230, v231, 1.0
	v_fmac_f32_e32 v231, v131, v231
	v_mul_f32_e32 v233, v232, v231
	v_fma_f32 v131, -v230, v233, v232
	v_fmac_f32_e32 v233, v131, v231
	v_fma_f32 v230, -v230, v233, v232
	v_div_fmas_f32 v230, v230, v231, v233
	v_div_fixup_f32 v133, v230, v229, v85
	v_mul_f32_e32 v133, v93, v133
	v_cvt_pk_bf16_f32 v133, v135, v133
	global_store_dword v[226:227], v133, off
	v_lshl_add_u64 v[226:227], v[226:227], 0, s[56:57]
	v_mul_f32_e32 v228, 0xbfb8aa3b, v82
	v_exp_f32_e32 v228, v228
	s_nop 0
	v_add_f32_e32 v229, 1.0, v228
	v_div_scale_f32 v230, s[4:5], v229, v229, v82
	v_rcp_f32_e32 v231, v230
	v_div_scale_f32 v232, vcc, v82, v229, v82
	s_nop 0
	v_fma_f32 v131, -v230, v231, 1.0
	v_fmac_f32_e32 v231, v131, v231
	v_mul_f32_e32 v233, v232, v231
	v_fma_f32 v131, -v230, v233, v232
	v_fmac_f32_e32 v233, v131, v231
	v_fma_f32 v230, -v230, v233, v232
	v_div_fmas_f32 v230, v230, v231, v233
	v_div_fixup_f32 v135, v230, v229, v82
	v_mul_f32_e32 v135, v90, v135
	v_mul_f32_e32 v228, 0xbfb8aa3b, v86
	v_exp_f32_e32 v228, v228
	s_nop 0
	v_add_f32_e32 v229, 1.0, v228
	v_div_scale_f32 v230, s[4:5], v229, v229, v86
	v_rcp_f32_e32 v231, v230
	v_div_scale_f32 v232, vcc, v86, v229, v86
	s_nop 0
	v_fma_f32 v131, -v230, v231, 1.0
	v_fmac_f32_e32 v231, v131, v231
	v_mul_f32_e32 v233, v232, v231
	v_fma_f32 v131, -v230, v233, v232
	v_fmac_f32_e32 v233, v131, v231
	v_fma_f32 v230, -v230, v233, v232
	v_div_fmas_f32 v230, v230, v231, v233
	v_div_fixup_f32 v133, v230, v229, v86
	v_mul_f32_e32 v133, v94, v133
	v_cvt_pk_bf16_f32 v133, v135, v133
	global_store_dword v[226:227], v133, off
	v_lshl_add_u64 v[226:227], v[226:227], 0, s[56:57]
	v_mul_f32_e32 v228, 0xbfb8aa3b, v83
	v_exp_f32_e32 v228, v228
	s_nop 0
	v_add_f32_e32 v229, 1.0, v228
	v_div_scale_f32 v230, s[4:5], v229, v229, v83
	v_rcp_f32_e32 v231, v230
	v_div_scale_f32 v232, vcc, v83, v229, v83
	s_nop 0
	v_fma_f32 v131, -v230, v231, 1.0
	v_fmac_f32_e32 v231, v131, v231
	v_mul_f32_e32 v233, v232, v231
	v_fma_f32 v131, -v230, v233, v232
	v_fmac_f32_e32 v233, v131, v231
	v_fma_f32 v230, -v230, v233, v232
	v_div_fmas_f32 v230, v230, v231, v233
	v_div_fixup_f32 v135, v230, v229, v83
	v_mul_f32_e32 v135, v91, v135
	v_mul_f32_e32 v228, 0xbfb8aa3b, v87
	v_exp_f32_e32 v228, v228
	s_nop 0
	v_add_f32_e32 v229, 1.0, v228
	v_div_scale_f32 v230, s[4:5], v229, v229, v87
	v_rcp_f32_e32 v231, v230
	v_div_scale_f32 v232, vcc, v87, v229, v87
	s_nop 0
	v_fma_f32 v131, -v230, v231, 1.0
	v_fmac_f32_e32 v231, v131, v231
	v_mul_f32_e32 v233, v232, v231
	v_fma_f32 v131, -v230, v233, v232
	v_fmac_f32_e32 v233, v131, v231
	v_fma_f32 v230, -v230, v233, v232
	v_div_fmas_f32 v230, v230, v231, v233
	v_div_fixup_f32 v133, v230, v229, v87
	v_mul_f32_e32 v133, v95, v133
	v_cvt_pk_bf16_f32 v133, v135, v133
	global_store_dword v[226:227], v133, off
	v_lshl_add_u64 v[226:227], v[226:227], 0, s[40:41]
	v_mul_f32_e32 v228, 0xbfb8aa3b, v96
	v_exp_f32_e32 v228, v228
	s_nop 0
	v_add_f32_e32 v229, 1.0, v228
	v_div_scale_f32 v230, s[4:5], v229, v229, v96
	v_rcp_f32_e32 v231, v230
	v_div_scale_f32 v232, vcc, v96, v229, v96
	s_nop 0
	v_fma_f32 v131, -v230, v231, 1.0
	v_fmac_f32_e32 v231, v131, v231
	v_mul_f32_e32 v233, v232, v231
	v_fma_f32 v131, -v230, v233, v232
	v_fmac_f32_e32 v233, v131, v231
	v_fma_f32 v230, -v230, v233, v232
	v_div_fmas_f32 v230, v230, v231, v233
	v_div_fixup_f32 v135, v230, v229, v96
	v_mul_f32_e32 v135, v104, v135
	v_mul_f32_e32 v228, 0xbfb8aa3b, v100
	v_exp_f32_e32 v228, v228
	s_nop 0
	v_add_f32_e32 v229, 1.0, v228
	v_div_scale_f32 v230, s[4:5], v229, v229, v100
	v_rcp_f32_e32 v231, v230
	v_div_scale_f32 v232, vcc, v100, v229, v100
	s_nop 0
	v_fma_f32 v131, -v230, v231, 1.0
	v_fmac_f32_e32 v231, v131, v231
	v_mul_f32_e32 v233, v232, v231
	v_fma_f32 v131, -v230, v233, v232
	v_fmac_f32_e32 v233, v131, v231
	v_fma_f32 v230, -v230, v233, v232
	v_div_fmas_f32 v230, v230, v231, v233
	v_div_fixup_f32 v133, v230, v229, v100
	v_mul_f32_e32 v133, v108, v133
	v_cvt_pk_bf16_f32 v133, v135, v133
	global_store_dword v[226:227], v133, off
	v_lshl_add_u64 v[226:227], v[226:227], 0, s[56:57]
	v_mul_f32_e32 v228, 0xbfb8aa3b, v97
	v_exp_f32_e32 v228, v228
	s_nop 0
	v_add_f32_e32 v229, 1.0, v228
	v_div_scale_f32 v230, s[4:5], v229, v229, v97
	v_rcp_f32_e32 v231, v230
	v_div_scale_f32 v232, vcc, v97, v229, v97
	s_nop 0
	v_fma_f32 v131, -v230, v231, 1.0
	v_fmac_f32_e32 v231, v131, v231
	v_mul_f32_e32 v233, v232, v231
	v_fma_f32 v131, -v230, v233, v232
	v_fmac_f32_e32 v233, v131, v231
	v_fma_f32 v230, -v230, v233, v232
	v_div_fmas_f32 v230, v230, v231, v233
	v_div_fixup_f32 v135, v230, v229, v97
	v_mul_f32_e32 v135, v105, v135
	v_mul_f32_e32 v228, 0xbfb8aa3b, v101
	v_exp_f32_e32 v228, v228
	s_nop 0
	v_add_f32_e32 v229, 1.0, v228
	v_div_scale_f32 v230, s[4:5], v229, v229, v101
	v_rcp_f32_e32 v231, v230
	v_div_scale_f32 v232, vcc, v101, v229, v101
	s_nop 0
	v_fma_f32 v131, -v230, v231, 1.0
	v_fmac_f32_e32 v231, v131, v231
	v_mul_f32_e32 v233, v232, v231
	v_fma_f32 v131, -v230, v233, v232
	v_fmac_f32_e32 v233, v131, v231
	v_fma_f32 v230, -v230, v233, v232
	v_div_fmas_f32 v230, v230, v231, v233
	v_div_fixup_f32 v133, v230, v229, v101
	v_mul_f32_e32 v133, v109, v133
	v_cvt_pk_bf16_f32 v133, v135, v133
	global_store_dword v[226:227], v133, off
	v_lshl_add_u64 v[226:227], v[226:227], 0, s[56:57]
	v_mul_f32_e32 v228, 0xbfb8aa3b, v98
	v_exp_f32_e32 v228, v228
	s_nop 0
	v_add_f32_e32 v229, 1.0, v228
	v_div_scale_f32 v230, s[4:5], v229, v229, v98
	v_rcp_f32_e32 v231, v230
	v_div_scale_f32 v232, vcc, v98, v229, v98
	s_nop 0
	v_fma_f32 v131, -v230, v231, 1.0
	v_fmac_f32_e32 v231, v131, v231
	v_mul_f32_e32 v233, v232, v231
	v_fma_f32 v131, -v230, v233, v232
	v_fmac_f32_e32 v233, v131, v231
	v_fma_f32 v230, -v230, v233, v232
	v_div_fmas_f32 v230, v230, v231, v233
	v_div_fixup_f32 v135, v230, v229, v98
	v_mul_f32_e32 v135, v106, v135
	v_mul_f32_e32 v228, 0xbfb8aa3b, v102
	v_exp_f32_e32 v228, v228
	s_nop 0
	v_add_f32_e32 v229, 1.0, v228
	v_div_scale_f32 v230, s[4:5], v229, v229, v102
	v_rcp_f32_e32 v231, v230
	v_div_scale_f32 v232, vcc, v102, v229, v102
	s_nop 0
	v_fma_f32 v131, -v230, v231, 1.0
	v_fmac_f32_e32 v231, v131, v231
	v_mul_f32_e32 v233, v232, v231
	v_fma_f32 v131, -v230, v233, v232
	v_fmac_f32_e32 v233, v131, v231
	v_fma_f32 v230, -v230, v233, v232
	v_div_fmas_f32 v230, v230, v231, v233
	v_div_fixup_f32 v133, v230, v229, v102
	v_mul_f32_e32 v133, v110, v133
	v_cvt_pk_bf16_f32 v133, v135, v133
	global_store_dword v[226:227], v133, off
	v_lshl_add_u64 v[226:227], v[226:227], 0, s[56:57]
	v_mul_f32_e32 v228, 0xbfb8aa3b, v99
	v_exp_f32_e32 v228, v228
	s_nop 0
	v_add_f32_e32 v229, 1.0, v228
	v_div_scale_f32 v230, s[4:5], v229, v229, v99
	v_rcp_f32_e32 v231, v230
	v_div_scale_f32 v232, vcc, v99, v229, v99
	s_nop 0
	v_fma_f32 v131, -v230, v231, 1.0
	v_fmac_f32_e32 v231, v131, v231
	v_mul_f32_e32 v233, v232, v231
	v_fma_f32 v131, -v230, v233, v232
	v_fmac_f32_e32 v233, v131, v231
	v_fma_f32 v230, -v230, v233, v232
	v_div_fmas_f32 v230, v230, v231, v233
	v_div_fixup_f32 v135, v230, v229, v99
	v_mul_f32_e32 v135, v107, v135
	v_mul_f32_e32 v228, 0xbfb8aa3b, v103
	v_exp_f32_e32 v228, v228
	s_nop 0
	v_add_f32_e32 v229, 1.0, v228
	v_div_scale_f32 v230, s[4:5], v229, v229, v103
	v_rcp_f32_e32 v231, v230
	v_div_scale_f32 v232, vcc, v103, v229, v103
	s_nop 0
	v_fma_f32 v131, -v230, v231, 1.0
	v_fmac_f32_e32 v231, v131, v231
	v_mul_f32_e32 v233, v232, v231
	v_fma_f32 v131, -v230, v233, v232
	v_fmac_f32_e32 v233, v131, v231
	v_fma_f32 v230, -v230, v233, v232
	v_div_fmas_f32 v230, v230, v231, v233
	v_div_fixup_f32 v133, v230, v229, v103
	v_mul_f32_e32 v133, v111, v133
	v_cvt_pk_bf16_f32 v133, v135, v133
	global_store_dword v[226:227], v133, off
	v_lshl_add_u64 v[226:227], v[226:227], 0, s[40:41]
	v_mul_f32_e32 v228, 0xbfb8aa3b, v112
	v_exp_f32_e32 v228, v228
	s_nop 0
	v_add_f32_e32 v229, 1.0, v228
	v_div_scale_f32 v230, s[4:5], v229, v229, v112
	v_rcp_f32_e32 v231, v230
	v_div_scale_f32 v232, vcc, v112, v229, v112
	s_nop 0
	v_fma_f32 v131, -v230, v231, 1.0
	v_fmac_f32_e32 v231, v131, v231
	v_mul_f32_e32 v233, v232, v231
	v_fma_f32 v131, -v230, v233, v232
	v_fmac_f32_e32 v233, v131, v231
	v_fma_f32 v230, -v230, v233, v232
	v_div_fmas_f32 v230, v230, v231, v233
	v_div_fixup_f32 v135, v230, v229, v112
	v_mul_f32_e32 v135, v120, v135
	v_mul_f32_e32 v228, 0xbfb8aa3b, v116
	v_exp_f32_e32 v228, v228
	s_nop 0
	v_add_f32_e32 v229, 1.0, v228
	v_div_scale_f32 v230, s[4:5], v229, v229, v116
	v_rcp_f32_e32 v231, v230
	v_div_scale_f32 v232, vcc, v116, v229, v116
	s_nop 0
	v_fma_f32 v131, -v230, v231, 1.0
	v_fmac_f32_e32 v231, v131, v231
	v_mul_f32_e32 v233, v232, v231
	v_fma_f32 v131, -v230, v233, v232
	v_fmac_f32_e32 v233, v131, v231
	v_fma_f32 v230, -v230, v233, v232
	v_div_fmas_f32 v230, v230, v231, v233
	v_div_fixup_f32 v133, v230, v229, v116
	v_mul_f32_e32 v133, v124, v133
	v_cvt_pk_bf16_f32 v133, v135, v133
	global_store_dword v[226:227], v133, off
	v_lshl_add_u64 v[226:227], v[226:227], 0, s[56:57]
	v_mul_f32_e32 v228, 0xbfb8aa3b, v113
	v_exp_f32_e32 v228, v228
	s_nop 0
	v_add_f32_e32 v229, 1.0, v228
	v_div_scale_f32 v230, s[4:5], v229, v229, v113
	v_rcp_f32_e32 v231, v230
	v_div_scale_f32 v232, vcc, v113, v229, v113
	s_nop 0
	v_fma_f32 v131, -v230, v231, 1.0
	v_fmac_f32_e32 v231, v131, v231
	v_mul_f32_e32 v233, v232, v231
	v_fma_f32 v131, -v230, v233, v232
	v_fmac_f32_e32 v233, v131, v231
	v_fma_f32 v230, -v230, v233, v232
	v_div_fmas_f32 v230, v230, v231, v233
	v_div_fixup_f32 v135, v230, v229, v113
	v_mul_f32_e32 v135, v121, v135
	v_mul_f32_e32 v228, 0xbfb8aa3b, v117
	v_exp_f32_e32 v228, v228
	s_nop 0
	v_add_f32_e32 v229, 1.0, v228
	v_div_scale_f32 v230, s[4:5], v229, v229, v117
	v_rcp_f32_e32 v231, v230
	v_div_scale_f32 v232, vcc, v117, v229, v117
	s_nop 0
	v_fma_f32 v131, -v230, v231, 1.0
	v_fmac_f32_e32 v231, v131, v231
	v_mul_f32_e32 v233, v232, v231
	v_fma_f32 v131, -v230, v233, v232
	v_fmac_f32_e32 v233, v131, v231
	v_fma_f32 v230, -v230, v233, v232
	v_div_fmas_f32 v230, v230, v231, v233
	v_div_fixup_f32 v133, v230, v229, v117
	v_mul_f32_e32 v133, v125, v133
	v_cvt_pk_bf16_f32 v133, v135, v133
	global_store_dword v[226:227], v133, off
	v_lshl_add_u64 v[226:227], v[226:227], 0, s[56:57]
	v_mul_f32_e32 v228, 0xbfb8aa3b, v114
	v_exp_f32_e32 v228, v228
	s_nop 0
	v_add_f32_e32 v229, 1.0, v228
	v_div_scale_f32 v230, s[4:5], v229, v229, v114
	v_rcp_f32_e32 v231, v230
	v_div_scale_f32 v232, vcc, v114, v229, v114
	s_nop 0
	v_fma_f32 v131, -v230, v231, 1.0
	v_fmac_f32_e32 v231, v131, v231
	v_mul_f32_e32 v233, v232, v231
	v_fma_f32 v131, -v230, v233, v232
	v_fmac_f32_e32 v233, v131, v231
	v_fma_f32 v230, -v230, v233, v232
	v_div_fmas_f32 v230, v230, v231, v233
	v_div_fixup_f32 v135, v230, v229, v114
	v_mul_f32_e32 v135, v122, v135
	v_mul_f32_e32 v228, 0xbfb8aa3b, v118
	v_exp_f32_e32 v228, v228
	s_nop 0
	v_add_f32_e32 v229, 1.0, v228
	v_div_scale_f32 v230, s[4:5], v229, v229, v118
	v_rcp_f32_e32 v231, v230
	v_div_scale_f32 v232, vcc, v118, v229, v118
	s_nop 0
	v_fma_f32 v131, -v230, v231, 1.0
	v_fmac_f32_e32 v231, v131, v231
	v_mul_f32_e32 v233, v232, v231
	v_fma_f32 v131, -v230, v233, v232
	v_fmac_f32_e32 v233, v131, v231
	v_fma_f32 v230, -v230, v233, v232
	v_div_fmas_f32 v230, v230, v231, v233
	v_div_fixup_f32 v133, v230, v229, v118
	v_mul_f32_e32 v133, v126, v133
	v_cvt_pk_bf16_f32 v133, v135, v133
	global_store_dword v[226:227], v133, off
	v_lshl_add_u64 v[226:227], v[226:227], 0, s[56:57]
	v_mul_f32_e32 v228, 0xbfb8aa3b, v115
	v_exp_f32_e32 v228, v228
	s_nop 0
	v_add_f32_e32 v229, 1.0, v228
	v_div_scale_f32 v230, s[4:5], v229, v229, v115
	v_rcp_f32_e32 v231, v230
	v_div_scale_f32 v232, vcc, v115, v229, v115
	s_nop 0
	v_fma_f32 v131, -v230, v231, 1.0
	v_fmac_f32_e32 v231, v131, v231
	v_mul_f32_e32 v233, v232, v231
	v_fma_f32 v131, -v230, v233, v232
	v_fmac_f32_e32 v233, v131, v231
	v_fma_f32 v230, -v230, v233, v232
	v_div_fmas_f32 v230, v230, v231, v233
	v_div_fixup_f32 v135, v230, v229, v115
	v_mul_f32_e32 v135, v123, v135
	v_mul_f32_e32 v228, 0xbfb8aa3b, v119
	v_exp_f32_e32 v228, v228
	s_nop 0
	v_add_f32_e32 v229, 1.0, v228
	v_div_scale_f32 v230, s[4:5], v229, v229, v119
	v_rcp_f32_e32 v231, v230
	v_div_scale_f32 v232, vcc, v119, v229, v119
	s_nop 0
	v_fma_f32 v131, -v230, v231, 1.0
	v_fmac_f32_e32 v231, v131, v231
	v_mul_f32_e32 v233, v232, v231
	v_fma_f32 v131, -v230, v233, v232
	v_fmac_f32_e32 v233, v131, v231
	v_fma_f32 v230, -v230, v233, v232
	v_div_fmas_f32 v230, v230, v231, v233
	v_div_fixup_f32 v133, v230, v229, v119
	v_mul_f32_e32 v133, v127, v133
	v_cvt_pk_bf16_f32 v133, v135, v133
	global_store_dword v[226:227], v133, off
	s_cmp_ge_u32 s54, 2112
	s_cbranch_scc1 .Lfi_done
	s_lshr_b32 s55, s54, 4
	s_mul_hi_u32 s55, s55, 0x55555556
	s_mul_i32 s53, s55, 48
	s_sub_u32 s53, s54, s53
	v_readlane_b32 s4, v235, 34
	v_readlane_b32 s5, v235, 35
	s_mul_i32 s50, s53, 0x168000
	s_lshl_b32 s55, s55, 7
	s_add_u32 s50, s50, s55
	s_add_u32 s50, s50, 0xfae6000
	s_add_u32 s50, s50, s4
	s_addc_u32 s51, s5, 0
	s_branch .Lfi_tile
